# batched residual+gate epilogues (10 sites, loads batched per m-tile instead of load-wait-store per element) + pipelined UP K-loop MT2
# speedup vs baseline: 1.1342x; 1.1342x over previous
; DI int otid() { int t = threadIdx.x; asm volatile("" : "+v"(t)); return t; }
; DI bf16_t cv1(float x) { return (bf16_t)(pk2(x, 0.f) & 0xffffu); }
; DI float bf2f(bf16_t v) { return (float)__builtin_bit_cast(_Float16, v); }
; DI int crow(int i, int h) { return (i & 3) + 8 * (i >> 2) + 4 * h; }
;     DI void operator()(int unit, const f32x16 (&acc)[MT][NT]) const {
;         const int lane = otid() & 63, r = lane & 31, h = lane >> 5;
; #pragma unroll
;         for (int mi = 0; mi < MT; ++mi)
; #pragma unroll
;             for (int nj = 0; nj < NT; ++nj)
; #pragma unroll
;                 for (int i = 0; i < 16; ++i) {
;                     bf16_t* rowp = priv + (mi * 32 + crow(i, h) + (mi == 2 ? d2 : 0)) * PRIVW; const int c = unit * UW + nj * 32 + r;
;                     float v = bf2f(rowp[gcol + c]) * acc[mi][nj][i];
;                     if (SECOND) v += bf2f(rowp[PC_M + c]);
;                     rowp[PC_M + c] = cv1(v);
.LBB0_388:
	s_and_saveexec_b64 s[28:29], s[4:5]
	s_cbranch_execz .LBB0_377
	s_waitcnt vmcnt(0)
	v_and_b32_e32 v2, 31, v176
	v_lshrrev_b32_e32 v3, 3, v176
	v_and_b32_e32 v3, 4, v3
	v_mul_u32_u24_e32 v3, 0x2c00, v3
	v_lshl_add_u32 v4, v2, 1, v3
	v_lshl_add_u32 v4, v232, 7, v4
	v_add_u32_e32 v5, 0x1400, v4
	global_load_ushort v117, v5, s[6:7] offset:-3072
	global_load_ushort v118, v5, s[6:7] offset:-3008
	v_add_u32_e32 v6, 0x4000, v4
	global_load_ushort v119, v6, s[6:7] offset:-3072
	global_load_ushort v120, v6, s[6:7] offset:-3008
	v_add_u32_e32 v7, 0x6c00, v4
	global_load_ushort v121, v7, s[6:7] offset:-3072
	global_load_ushort v122, v7, s[6:7] offset:-3008
	v_add_u32_e32 v8, 0x9800, v4
	global_load_ushort v123, v8, s[6:7] offset:-3072
	global_load_ushort v124, v8, s[6:7] offset:-3008
	v_add_u32_e32 v9, 0x17400, v4
	global_load_ushort v125, v9, s[6:7] offset:-3072
	global_load_ushort v126, v9, s[6:7] offset:-3008
	v_add_u32_e32 v10, 0x1a000, v4
	global_load_ushort v127, v10, s[6:7] offset:-3072
	global_load_ushort v128, v10, s[6:7] offset:-3008
	v_add_u32_e32 v11, 0x1cc00, v4
	global_load_ushort v129, v11, s[6:7] offset:-3072
	global_load_ushort v130, v11, s[6:7] offset:-3008
	v_add_u32_e32 v12, 0x1f800, v4
	global_load_ushort v131, v12, s[6:7] offset:-3072
	global_load_ushort v132, v12, s[6:7] offset:-3008
	v_add_u32_e32 v13, 0x2d400, v4
	global_load_ushort v133, v13, s[6:7] offset:-3072
	global_load_ushort v134, v13, s[6:7] offset:-3008
	v_add_u32_e32 v14, 0x30000, v4
	global_load_ushort v135, v14, s[6:7] offset:-3072
	global_load_ushort v136, v14, s[6:7] offset:-3008
	v_add_u32_e32 v15, 0x32c00, v4
	global_load_ushort v137, v15, s[6:7] offset:-3072
	global_load_ushort v138, v15, s[6:7] offset:-3008
	v_add_u32_e32 v112, 0x35800, v4
	global_load_ushort v139, v112, s[6:7] offset:-3072
	global_load_ushort v140, v112, s[6:7] offset:-3008
	v_add_u32_e32 v113, 0x43400, v4
	global_load_ushort v141, v113, s[6:7] offset:-3072
	global_load_ushort v142, v113, s[6:7] offset:-3008
	v_add_u32_e32 v114, 0x46000, v4
	global_load_ushort v143, v114, s[6:7] offset:-3072
	global_load_ushort v144, v114, s[6:7] offset:-3008
	v_add_u32_e32 v115, 0x48c00, v4
	global_load_ushort v145, v115, s[6:7] offset:-3072
	global_load_ushort v146, v115, s[6:7] offset:-3008
	v_add_u32_e32 v116, 0x4b800, v4
	global_load_ushort v147, v116, s[6:7] offset:-3072
	global_load_ushort v148, v116, s[6:7] offset:-3008
	s_waitcnt vmcnt(0)
	v_fma_mixlo_f16 v117, v96, v117, 0 op_sel_hi:[0,1,0]
	global_store_short v5, v117, s[6:7] offset:3072
	v_fma_mixlo_f16 v118, v80, v118, 0 op_sel_hi:[0,1,0]
	global_store_short v5, v118, s[6:7] offset:3136
	v_fma_mixlo_f16 v119, v97, v119, 0 op_sel_hi:[0,1,0]
	global_store_short v6, v119, s[6:7] offset:3072
	v_fma_mixlo_f16 v120, v81, v120, 0 op_sel_hi:[0,1,0]
	global_store_short v6, v120, s[6:7] offset:3136
	v_fma_mixlo_f16 v121, v98, v121, 0 op_sel_hi:[0,1,0]
	global_store_short v7, v121, s[6:7] offset:3072
	v_fma_mixlo_f16 v122, v82, v122, 0 op_sel_hi:[0,1,0]
	global_store_short v7, v122, s[6:7] offset:3136
	v_fma_mixlo_f16 v123, v99, v123, 0 op_sel_hi:[0,1,0]
	global_store_short v8, v123, s[6:7] offset:3072
	v_fma_mixlo_f16 v124, v83, v124, 0 op_sel_hi:[0,1,0]
	global_store_short v8, v124, s[6:7] offset:3136
	v_fma_mixlo_f16 v125, v100, v125, 0 op_sel_hi:[0,1,0]
	global_store_short v9, v125, s[6:7] offset:3072
	v_fma_mixlo_f16 v126, v84, v126, 0 op_sel_hi:[0,1,0]
	global_store_short v9, v126, s[6:7] offset:3136
	v_fma_mixlo_f16 v127, v101, v127, 0 op_sel_hi:[0,1,0]
	global_store_short v10, v127, s[6:7] offset:3072
	v_fma_mixlo_f16 v128, v85, v128, 0 op_sel_hi:[0,1,0]
	global_store_short v10, v128, s[6:7] offset:3136
	v_fma_mixlo_f16 v129, v102, v129, 0 op_sel_hi:[0,1,0]
	global_store_short v11, v129, s[6:7] offset:3072
	v_fma_mixlo_f16 v130, v86, v130, 0 op_sel_hi:[0,1,0]
	global_store_short v11, v130, s[6:7] offset:3136
	v_fma_mixlo_f16 v131, v103, v131, 0 op_sel_hi:[0,1,0]
	global_store_short v12, v131, s[6:7] offset:3072
	v_fma_mixlo_f16 v132, v87, v132, 0 op_sel_hi:[0,1,0]
	global_store_short v12, v132, s[6:7] offset:3136
	v_fma_mixlo_f16 v133, v104, v133, 0 op_sel_hi:[0,1,0]
	global_store_short v13, v133, s[6:7] offset:3072
	v_fma_mixlo_f16 v134, v88, v134, 0 op_sel_hi:[0,1,0]
	global_store_short v13, v134, s[6:7] offset:3136
	v_fma_mixlo_f16 v135, v105, v135, 0 op_sel_hi:[0,1,0]
	global_store_short v14, v135, s[6:7] offset:3072
	v_fma_mixlo_f16 v136, v89, v136, 0 op_sel_hi:[0,1,0]
	global_store_short v14, v136, s[6:7] offset:3136
	v_fma_mixlo_f16 v137, v106, v137, 0 op_sel_hi:[0,1,0]
	global_store_short v15, v137, s[6:7] offset:3072
	v_fma_mixlo_f16 v138, v90, v138, 0 op_sel_hi:[0,1,0]
	global_store_short v15, v138, s[6:7] offset:3136
	v_fma_mixlo_f16 v139, v107, v139, 0 op_sel_hi:[0,1,0]
	global_store_short v112, v139, s[6:7] offset:3072
	v_fma_mixlo_f16 v140, v91, v140, 0 op_sel_hi:[0,1,0]
	global_store_short v112, v140, s[6:7] offset:3136
	v_fma_mixlo_f16 v141, v108, v141, 0 op_sel_hi:[0,1,0]
	global_store_short v113, v141, s[6:7] offset:3072
	v_fma_mixlo_f16 v142, v92, v142, 0 op_sel_hi:[0,1,0]
	global_store_short v113, v142, s[6:7] offset:3136
	v_fma_mixlo_f16 v143, v109, v143, 0 op_sel_hi:[0,1,0]
	global_store_short v114, v143, s[6:7] offset:3072
	v_fma_mixlo_f16 v144, v93, v144, 0 op_sel_hi:[0,1,0]
	global_store_short v114, v144, s[6:7] offset:3136
	v_fma_mixlo_f16 v145, v110, v145, 0 op_sel_hi:[0,1,0]
	global_store_short v115, v145, s[6:7] offset:3072
	v_fma_mixlo_f16 v146, v94, v146, 0 op_sel_hi:[0,1,0]
	global_store_short v115, v146, s[6:7] offset:3136
	v_fma_mixlo_f16 v147, v111, v147, 0 op_sel_hi:[0,1,0]
; DI bf16_t cv1(float x) { return (bf16_t)(pk2(x, 0.f) & 0xffffu); }
; DI float bf2f(bf16_t v) { return (float)__builtin_bit_cast(_Float16, v); }
; DI int crow(int i, int h) { return (i & 3) + 8 * (i >> 2) + 4 * h; }
;     DI void operator()(int unit, const f32x16 (&acc)[MT][NT]) const {
;     ...
; #pragma unroll
;         for (int mi = 0; mi < MT; ++mi)
; #pragma unroll
;             for (int nj = 0; nj < NT; ++nj)
; #pragma unroll
;                 for (int i = 0; i < 16; ++i) {
;                     bf16_t* rowp = priv + (mi * 32 + crow(i, h) + (mi == 2 ? d2 : 0)) * PRIVW; const int c = unit * UW + nj * 32 + r;
;                     float v = bf2f(rowp[gcol + c]) * acc[mi][nj][i];
;                     if (SECOND) v += bf2f(rowp[PC_M + c]);
;                     rowp[PC_M + c] = cv1(v);
	global_store_short v116, v147, s[6:7] offset:3072
	v_fma_mixlo_f16 v148, v95, v148, 0 op_sel_hi:[0,1,0]
	global_store_short v116, v148, s[6:7] offset:3136
	v_add_u32_e32 v5, 0x59400, v4
	global_load_ushort v117, v5, s[6:7] offset:-3072
	global_load_ushort v118, v5, s[6:7] offset:-3008
	v_add_u32_e32 v6, 0x5c000, v4
	global_load_ushort v119, v6, s[6:7] offset:-3072
	global_load_ushort v120, v6, s[6:7] offset:-3008
	v_add_u32_e32 v7, 0x5ec00, v4
	global_load_ushort v121, v7, s[6:7] offset:-3072
	global_load_ushort v122, v7, s[6:7] offset:-3008
	v_add_u32_e32 v8, 0x61800, v4
	global_load_ushort v123, v8, s[6:7] offset:-3072
	global_load_ushort v124, v8, s[6:7] offset:-3008
	v_add_u32_e32 v9, 0x6f400, v4
	global_load_ushort v125, v9, s[6:7] offset:-3072
	global_load_ushort v126, v9, s[6:7] offset:-3008
	v_add_u32_e32 v10, 0x72000, v4
	global_load_ushort v127, v10, s[6:7] offset:-3072
	global_load_ushort v128, v10, s[6:7] offset:-3008
	v_add_u32_e32 v11, 0x74c00, v4
	global_load_ushort v129, v11, s[6:7] offset:-3072
	global_load_ushort v130, v11, s[6:7] offset:-3008
	v_add_u32_e32 v12, 0x77800, v4
	global_load_ushort v131, v12, s[6:7] offset:-3072
	global_load_ushort v132, v12, s[6:7] offset:-3008
	v_add_u32_e32 v13, 0x85400, v4
	global_load_ushort v133, v13, s[6:7] offset:-3072
	global_load_ushort v134, v13, s[6:7] offset:-3008
	v_add_u32_e32 v14, 0x88000, v4
	global_load_ushort v135, v14, s[6:7] offset:-3072
	global_load_ushort v136, v14, s[6:7] offset:-3008
	v_add_u32_e32 v15, 0x8ac00, v4
	global_load_ushort v137, v15, s[6:7] offset:-3072
	global_load_ushort v138, v15, s[6:7] offset:-3008
	v_add_u32_e32 v112, 0x8d800, v4
	global_load_ushort v139, v112, s[6:7] offset:-3072
	global_load_ushort v140, v112, s[6:7] offset:-3008
	v_add_u32_e32 v113, 0x9b400, v4
	global_load_ushort v141, v113, s[6:7] offset:-3072
	global_load_ushort v142, v113, s[6:7] offset:-3008
	v_add_u32_e32 v114, 0x9e000, v4
	global_load_ushort v143, v114, s[6:7] offset:-3072
	global_load_ushort v144, v114, s[6:7] offset:-3008
	v_add_u32_e32 v115, 0xa0c00, v4
	global_load_ushort v145, v115, s[6:7] offset:-3072
	global_load_ushort v146, v115, s[6:7] offset:-3008
	v_add_u32_e32 v116, 0xa3800, v4
	global_load_ushort v147, v116, s[6:7] offset:-3072
	global_load_ushort v148, v116, s[6:7] offset:-3008
	s_waitcnt vmcnt(0)
	v_fma_mixlo_f16 v117, v64, v117, 0 op_sel_hi:[0,1,0]
	global_store_short v5, v117, s[6:7] offset:3072
	v_fma_mixlo_f16 v118, v48, v118, 0 op_sel_hi:[0,1,0]
	global_store_short v5, v118, s[6:7] offset:3136
	v_fma_mixlo_f16 v119, v65, v119, 0 op_sel_hi:[0,1,0]
	global_store_short v6, v119, s[6:7] offset:3072
	v_fma_mixlo_f16 v120, v49, v120, 0 op_sel_hi:[0,1,0]
	global_store_short v6, v120, s[6:7] offset:3136
	v_fma_mixlo_f16 v121, v66, v121, 0 op_sel_hi:[0,1,0]
	global_store_short v7, v121, s[6:7] offset:3072
	v_fma_mixlo_f16 v122, v50, v122, 0 op_sel_hi:[0,1,0]
	global_store_short v7, v122, s[6:7] offset:3136
	v_fma_mixlo_f16 v123, v67, v123, 0 op_sel_hi:[0,1,0]
	global_store_short v8, v123, s[6:7] offset:3072
	v_fma_mixlo_f16 v124, v51, v124, 0 op_sel_hi:[0,1,0]
	global_store_short v8, v124, s[6:7] offset:3136
	v_fma_mixlo_f16 v125, v68, v125, 0 op_sel_hi:[0,1,0]
	global_store_short v9, v125, s[6:7] offset:3072
	v_fma_mixlo_f16 v126, v52, v126, 0 op_sel_hi:[0,1,0]
	global_store_short v9, v126, s[6:7] offset:3136
	v_fma_mixlo_f16 v127, v69, v127, 0 op_sel_hi:[0,1,0]
	global_store_short v10, v127, s[6:7] offset:3072
	v_fma_mixlo_f16 v128, v53, v128, 0 op_sel_hi:[0,1,0]
	global_store_short v10, v128, s[6:7] offset:3136
	v_fma_mixlo_f16 v129, v70, v129, 0 op_sel_hi:[0,1,0]
	global_store_short v11, v129, s[6:7] offset:3072
	v_fma_mixlo_f16 v130, v54, v130, 0 op_sel_hi:[0,1,0]
	global_store_short v11, v130, s[6:7] offset:3136
	v_fma_mixlo_f16 v131, v71, v131, 0 op_sel_hi:[0,1,0]
	global_store_short v12, v131, s[6:7] offset:3072
	v_fma_mixlo_f16 v132, v55, v132, 0 op_sel_hi:[0,1,0]
	global_store_short v12, v132, s[6:7] offset:3136
	v_fma_mixlo_f16 v133, v72, v133, 0 op_sel_hi:[0,1,0]
	global_store_short v13, v133, s[6:7] offset:3072
	v_fma_mixlo_f16 v134, v56, v134, 0 op_sel_hi:[0,1,0]
	global_store_short v13, v134, s[6:7] offset:3136
	v_fma_mixlo_f16 v135, v73, v135, 0 op_sel_hi:[0,1,0]
	global_store_short v14, v135, s[6:7] offset:3072
	v_fma_mixlo_f16 v136, v57, v136, 0 op_sel_hi:[0,1,0]
	global_store_short v14, v136, s[6:7] offset:3136
	v_fma_mixlo_f16 v137, v74, v137, 0 op_sel_hi:[0,1,0]
	global_store_short v15, v137, s[6:7] offset:3072
	v_fma_mixlo_f16 v138, v58, v138, 0 op_sel_hi:[0,1,0]
	global_store_short v15, v138, s[6:7] offset:3136
	v_fma_mixlo_f16 v139, v75, v139, 0 op_sel_hi:[0,1,0]
	global_store_short v112, v139, s[6:7] offset:3072
	v_fma_mixlo_f16 v140, v59, v140, 0 op_sel_hi:[0,1,0]
	global_store_short v112, v140, s[6:7] offset:3136
	v_fma_mixlo_f16 v141, v76, v141, 0 op_sel_hi:[0,1,0]
	global_store_short v113, v141, s[6:7] offset:3072
	v_fma_mixlo_f16 v142, v60, v142, 0 op_sel_hi:[0,1,0]
	global_store_short v113, v142, s[6:7] offset:3136
	v_fma_mixlo_f16 v143, v77, v143, 0 op_sel_hi:[0,1,0]
	global_store_short v114, v143, s[6:7] offset:3072
	v_fma_mixlo_f16 v144, v61, v144, 0 op_sel_hi:[0,1,0]
	global_store_short v114, v144, s[6:7] offset:3136
	v_fma_mixlo_f16 v145, v78, v145, 0 op_sel_hi:[0,1,0]
	global_store_short v115, v145, s[6:7] offset:3072
	v_fma_mixlo_f16 v146, v62, v146, 0 op_sel_hi:[0,1,0]
	global_store_short v115, v146, s[6:7] offset:3136
	v_fma_mixlo_f16 v147, v79, v147, 0 op_sel_hi:[0,1,0]
	global_store_short v116, v147, s[6:7] offset:3072
	v_fma_mixlo_f16 v148, v63, v148, 0 op_sel_hi:[0,1,0]
	global_store_short v116, v148, s[6:7] offset:3136
; DI bf16_t cv1(float x) { return (bf16_t)(pk2(x, 0.f) & 0xffffu); }
; DI float bf2f(bf16_t v) { return (float)__builtin_bit_cast(_Float16, v); }
; DI int crow(int i, int h) { return (i & 3) + 8 * (i >> 2) + 4 * h; }
;     DI void operator()(int unit, const f32x16 (&acc)[MT][NT]) const {
;     ...
; #pragma unroll
;         for (int mi = 0; mi < MT; ++mi)
; #pragma unroll
;             for (int nj = 0; nj < NT; ++nj)
; #pragma unroll
;                 for (int i = 0; i < 16; ++i) {
;                     bf16_t* rowp = priv + (mi * 32 + crow(i, h) + (mi == 2 ? d2 : 0)) * PRIVW; const int c = unit * UW + nj * 32 + r;
;                     float v = bf2f(rowp[gcol + c]) * acc[mi][nj][i];
;                     if (SECOND) v += bf2f(rowp[PC_M + c]);
;                     rowp[PC_M + c] = cv1(v);
	s_sub_i32 s100, 0x4000, s62
	s_mul_i32 s101, s100, 0x2c00
	v_add_u32_e32 v3, s101, v4
	v_add_u32_e32 v5, 0x1400, v3
	global_load_ushort v117, v5, s[6:7] offset:-3072
	global_load_ushort v118, v5, s[6:7] offset:-3008
	v_add_u32_e32 v6, 0x4000, v3
	global_load_ushort v119, v6, s[6:7] offset:-3072
	global_load_ushort v120, v6, s[6:7] offset:-3008
	v_add_u32_e32 v7, 0x6c00, v3
	global_load_ushort v121, v7, s[6:7] offset:-3072
	global_load_ushort v122, v7, s[6:7] offset:-3008
	v_add_u32_e32 v8, 0x9800, v3
	global_load_ushort v123, v8, s[6:7] offset:-3072
	global_load_ushort v124, v8, s[6:7] offset:-3008
	v_add_u32_e32 v9, 0x17400, v3
	global_load_ushort v125, v9, s[6:7] offset:-3072
	global_load_ushort v126, v9, s[6:7] offset:-3008
	v_add_u32_e32 v10, 0x1a000, v3
	global_load_ushort v127, v10, s[6:7] offset:-3072
	global_load_ushort v128, v10, s[6:7] offset:-3008
	v_add_u32_e32 v11, 0x1cc00, v3
	global_load_ushort v129, v11, s[6:7] offset:-3072
	global_load_ushort v130, v11, s[6:7] offset:-3008
	v_add_u32_e32 v12, 0x1f800, v3
	global_load_ushort v131, v12, s[6:7] offset:-3072
	global_load_ushort v132, v12, s[6:7] offset:-3008
	v_add_u32_e32 v13, 0x2d400, v3
	global_load_ushort v133, v13, s[6:7] offset:-3072
	global_load_ushort v134, v13, s[6:7] offset:-3008
	v_add_u32_e32 v14, 0x30000, v3
	global_load_ushort v135, v14, s[6:7] offset:-3072
	global_load_ushort v136, v14, s[6:7] offset:-3008
	v_add_u32_e32 v15, 0x32c00, v3
	global_load_ushort v137, v15, s[6:7] offset:-3072
	global_load_ushort v138, v15, s[6:7] offset:-3008
	v_add_u32_e32 v112, 0x35800, v3
	global_load_ushort v139, v112, s[6:7] offset:-3072
	global_load_ushort v140, v112, s[6:7] offset:-3008
	v_add_u32_e32 v113, 0x43400, v3
	global_load_ushort v141, v113, s[6:7] offset:-3072
	global_load_ushort v142, v113, s[6:7] offset:-3008
	v_add_u32_e32 v114, 0x46000, v3
	global_load_ushort v143, v114, s[6:7] offset:-3072
	global_load_ushort v144, v114, s[6:7] offset:-3008
	v_add_u32_e32 v115, 0x48c00, v3
	global_load_ushort v145, v115, s[6:7] offset:-3072
	global_load_ushort v146, v115, s[6:7] offset:-3008
	v_add_u32_e32 v116, 0x4b800, v3
	global_load_ushort v147, v116, s[6:7] offset:-3072
	global_load_ushort v148, v116, s[6:7] offset:-3008
	s_waitcnt vmcnt(0)
	v_fma_mixlo_f16 v117, v32, v117, 0 op_sel_hi:[0,1,0]
	global_store_short v5, v117, s[6:7] offset:3072
	v_fma_mixlo_f16 v118, v16, v118, 0 op_sel_hi:[0,1,0]
	global_store_short v5, v118, s[6:7] offset:3136
	v_fma_mixlo_f16 v119, v33, v119, 0 op_sel_hi:[0,1,0]
	global_store_short v6, v119, s[6:7] offset:3072
	v_fma_mixlo_f16 v120, v17, v120, 0 op_sel_hi:[0,1,0]
	global_store_short v6, v120, s[6:7] offset:3136
	v_fma_mixlo_f16 v121, v34, v121, 0 op_sel_hi:[0,1,0]
	global_store_short v7, v121, s[6:7] offset:3072
	v_fma_mixlo_f16 v122, v18, v122, 0 op_sel_hi:[0,1,0]
	global_store_short v7, v122, s[6:7] offset:3136
	v_fma_mixlo_f16 v123, v35, v123, 0 op_sel_hi:[0,1,0]
	global_store_short v8, v123, s[6:7] offset:3072
	v_fma_mixlo_f16 v124, v19, v124, 0 op_sel_hi:[0,1,0]
	global_store_short v8, v124, s[6:7] offset:3136
	v_fma_mixlo_f16 v125, v36, v125, 0 op_sel_hi:[0,1,0]
	global_store_short v9, v125, s[6:7] offset:3072
	v_fma_mixlo_f16 v126, v20, v126, 0 op_sel_hi:[0,1,0]
	global_store_short v9, v126, s[6:7] offset:3136
	v_fma_mixlo_f16 v127, v37, v127, 0 op_sel_hi:[0,1,0]
	global_store_short v10, v127, s[6:7] offset:3072
	v_fma_mixlo_f16 v128, v21, v128, 0 op_sel_hi:[0,1,0]
	global_store_short v10, v128, s[6:7] offset:3136
	v_fma_mixlo_f16 v129, v38, v129, 0 op_sel_hi:[0,1,0]
	global_store_short v11, v129, s[6:7] offset:3072
	v_fma_mixlo_f16 v130, v22, v130, 0 op_sel_hi:[0,1,0]
	global_store_short v11, v130, s[6:7] offset:3136
	v_fma_mixlo_f16 v131, v39, v131, 0 op_sel_hi:[0,1,0]
	global_store_short v12, v131, s[6:7] offset:3072
	v_fma_mixlo_f16 v132, v23, v132, 0 op_sel_hi:[0,1,0]
	global_store_short v12, v132, s[6:7] offset:3136
	v_fma_mixlo_f16 v133, v40, v133, 0 op_sel_hi:[0,1,0]
	global_store_short v13, v133, s[6:7] offset:3072
	v_fma_mixlo_f16 v134, v24, v134, 0 op_sel_hi:[0,1,0]
	global_store_short v13, v134, s[6:7] offset:3136
	v_fma_mixlo_f16 v135, v41, v135, 0 op_sel_hi:[0,1,0]
	global_store_short v14, v135, s[6:7] offset:3072
	v_fma_mixlo_f16 v136, v25, v136, 0 op_sel_hi:[0,1,0]
	global_store_short v14, v136, s[6:7] offset:3136
	v_fma_mixlo_f16 v137, v42, v137, 0 op_sel_hi:[0,1,0]
	global_store_short v15, v137, s[6:7] offset:3072
	v_fma_mixlo_f16 v138, v26, v138, 0 op_sel_hi:[0,1,0]
	global_store_short v15, v138, s[6:7] offset:3136
	v_fma_mixlo_f16 v139, v43, v139, 0 op_sel_hi:[0,1,0]
	global_store_short v112, v139, s[6:7] offset:3072
	v_fma_mixlo_f16 v140, v27, v140, 0 op_sel_hi:[0,1,0]
	global_store_short v112, v140, s[6:7] offset:3136
	v_fma_mixlo_f16 v141, v44, v141, 0 op_sel_hi:[0,1,0]
	global_store_short v113, v141, s[6:7] offset:3072
	v_fma_mixlo_f16 v142, v28, v142, 0 op_sel_hi:[0,1,0]
	global_store_short v113, v142, s[6:7] offset:3136
	v_fma_mixlo_f16 v143, v45, v143, 0 op_sel_hi:[0,1,0]
	global_store_short v114, v143, s[6:7] offset:3072
	v_fma_mixlo_f16 v144, v29, v144, 0 op_sel_hi:[0,1,0]
	global_store_short v114, v144, s[6:7] offset:3136
	v_fma_mixlo_f16 v145, v46, v145, 0 op_sel_hi:[0,1,0]
	global_store_short v115, v145, s[6:7] offset:3072
	v_fma_mixlo_f16 v146, v30, v146, 0 op_sel_hi:[0,1,0]
	global_store_short v115, v146, s[6:7] offset:3136
	v_fma_mixlo_f16 v147, v47, v147, 0 op_sel_hi:[0,1,0]
	global_store_short v116, v147, s[6:7] offset:3072
	v_fma_mixlo_f16 v148, v31, v148, 0 op_sel_hi:[0,1,0]
	global_store_short v116, v148, s[6:7] offset:3136
	s_waitcnt vmcnt(0)
	s_branch .LBB0_377

; DI bf16_t cv1(float x) { return (bf16_t)(pk2(x, 0.f) & 0xffffu); }
; DI float bf2f(bf16_t v) { return (float)__builtin_bit_cast(_Float16, v); }
; DI int crow(int i, int h) { return (i & 3) + 8 * (i >> 2) + 4 * h; }
;     DI void operator()(int unit, const f32x16 (&acc)[MT][NT]) const {
;     ...
; #pragma unroll
;         for (int mi = 0; mi < MT; ++mi)
; #pragma unroll
;             for (int nj = 0; nj < NT; ++nj)
; #pragma unroll
;                 for (int i = 0; i < 16; ++i) {
;                     bf16_t* rowp = priv + (mi * 32 + crow(i, h) + (mi == 2 ? d2 : 0)) * PRIVW; const int c = unit * UW + nj * 32 + r;
;                     float v = bf2f(rowp[gcol + c]) * acc[mi][nj][i];
;                     if (SECOND) v += bf2f(rowp[PC_M + c]);
;                     rowp[PC_M + c] = cv1(v);
;                     if (i == 15) __builtin_amdgcn_sched_barrier(0);
.LBB0_402:
	s_and_saveexec_b64 s[28:29], s[4:5]
	s_cbranch_execz .LBB0_391
	s_waitcnt vmcnt(0)
	v_and_b32_e32 v2, 31, v176
	v_lshrrev_b32_e32 v3, 3, v176
	v_and_b32_e32 v3, 4, v3
	v_mul_u32_u24_e32 v3, 0x2c00, v3
	v_lshl_add_u32 v4, v2, 1, v3
	v_lshl_add_u32 v4, v232, 7, v4
	v_add_u32_e32 v5, 0x1800, v4
	global_load_ushort v117, v5, s[6:7] offset:-2048
	global_load_ushort v149, v5, s[6:7] offset:2048
	global_load_ushort v118, v5, s[6:7] offset:-1984
	global_load_ushort v150, v5, s[6:7] offset:2112
	v_add_u32_e32 v6, 0x4400, v4
	global_load_ushort v119, v6, s[6:7] offset:-2048
	global_load_ushort v151, v6, s[6:7] offset:2048
	global_load_ushort v120, v6, s[6:7] offset:-1984
	global_load_ushort v152, v6, s[6:7] offset:2112
	v_add_u32_e32 v7, 0x7000, v4
	global_load_ushort v121, v7, s[6:7] offset:-2048
	global_load_ushort v153, v7, s[6:7] offset:2048
	global_load_ushort v122, v7, s[6:7] offset:-1984
	global_load_ushort v154, v7, s[6:7] offset:2112
	v_add_u32_e32 v8, 0x9c00, v4
	global_load_ushort v123, v8, s[6:7] offset:-2048
	global_load_ushort v155, v8, s[6:7] offset:2048
	global_load_ushort v124, v8, s[6:7] offset:-1984
	global_load_ushort v166, v8, s[6:7] offset:2112
	v_add_u32_e32 v9, 0x17800, v4
	global_load_ushort v125, v9, s[6:7] offset:-2048
	global_load_ushort v167, v9, s[6:7] offset:2048
	global_load_ushort v126, v9, s[6:7] offset:-1984
	global_load_ushort v168, v9, s[6:7] offset:2112
	v_add_u32_e32 v10, 0x1a400, v4
	global_load_ushort v127, v10, s[6:7] offset:-2048
	global_load_ushort v169, v10, s[6:7] offset:2048
	global_load_ushort v128, v10, s[6:7] offset:-1984
	global_load_ushort v170, v10, s[6:7] offset:2112
	v_add_u32_e32 v11, 0x1d000, v4
	global_load_ushort v129, v11, s[6:7] offset:-2048
	global_load_ushort v171, v11, s[6:7] offset:2048
	global_load_ushort v130, v11, s[6:7] offset:-1984
	global_load_ushort v172, v11, s[6:7] offset:2112
	v_add_u32_e32 v12, 0x1fc00, v4
	global_load_ushort v131, v12, s[6:7] offset:-2048
	global_load_ushort v173, v12, s[6:7] offset:2048
	global_load_ushort v132, v12, s[6:7] offset:-1984
	global_load_ushort v174, v12, s[6:7] offset:2112
	v_add_u32_e32 v13, 0x2d800, v4
	global_load_ushort v133, v13, s[6:7] offset:-2048
	global_load_ushort v175, v13, s[6:7] offset:2048
	global_load_ushort v134, v13, s[6:7] offset:-1984
	global_load_ushort v180, v13, s[6:7] offset:2112
	v_add_u32_e32 v14, 0x30400, v4
	global_load_ushort v135, v14, s[6:7] offset:-2048
	global_load_ushort v181, v14, s[6:7] offset:2048
	global_load_ushort v136, v14, s[6:7] offset:-1984
	global_load_ushort v182, v14, s[6:7] offset:2112
	v_add_u32_e32 v15, 0x33000, v4
	global_load_ushort v137, v15, s[6:7] offset:-2048
	global_load_ushort v183, v15, s[6:7] offset:2048
	global_load_ushort v138, v15, s[6:7] offset:-1984
	global_load_ushort v184, v15, s[6:7] offset:2112
	v_add_u32_e32 v112, 0x35c00, v4
	global_load_ushort v139, v112, s[6:7] offset:-2048
	global_load_ushort v219, v112, s[6:7] offset:2048
	global_load_ushort v140, v112, s[6:7] offset:-1984
	global_load_ushort v233, v112, s[6:7] offset:2112
	v_add_u32_e32 v113, 0x43800, v4
	global_load_ushort v141, v113, s[6:7] offset:-2048
	global_load_ushort v234, v113, s[6:7] offset:2048
	global_load_ushort v142, v113, s[6:7] offset:-1984
	global_load_ushort v235, v113, s[6:7] offset:2112
	v_add_u32_e32 v114, 0x46400, v4
	global_load_ushort v143, v114, s[6:7] offset:-2048
	global_load_ushort v236, v114, s[6:7] offset:2048
	global_load_ushort v144, v114, s[6:7] offset:-1984
	global_load_ushort v237, v114, s[6:7] offset:2112
	v_add_u32_e32 v115, 0x49000, v4
	global_load_ushort v145, v115, s[6:7] offset:-2048
	global_load_ushort v238, v115, s[6:7] offset:2048
	global_load_ushort v146, v115, s[6:7] offset:-1984
	global_load_ushort v239, v115, s[6:7] offset:2112
	v_add_u32_e32 v116, 0x4bc00, v4
	global_load_ushort v147, v116, s[6:7] offset:-2048
	global_load_ushort v240, v116, s[6:7] offset:2048
	global_load_ushort v148, v116, s[6:7] offset:-1984
	global_load_ushort v241, v116, s[6:7] offset:2112
	s_waitcnt vmcnt(0)
	v_fma_mixlo_f16 v117, v96, v117, v149 op_sel_hi:[0,1,1]
	global_store_short v5, v117, s[6:7] offset:2048
	v_fma_mixlo_f16 v118, v80, v118, v150 op_sel_hi:[0,1,1]
	global_store_short v5, v118, s[6:7] offset:2112
	v_fma_mixlo_f16 v119, v97, v119, v151 op_sel_hi:[0,1,1]
	global_store_short v6, v119, s[6:7] offset:2048
	v_fma_mixlo_f16 v120, v81, v120, v152 op_sel_hi:[0,1,1]
	global_store_short v6, v120, s[6:7] offset:2112
	v_fma_mixlo_f16 v121, v98, v121, v153 op_sel_hi:[0,1,1]
	global_store_short v7, v121, s[6:7] offset:2048
	v_fma_mixlo_f16 v122, v82, v122, v154 op_sel_hi:[0,1,1]
	global_store_short v7, v122, s[6:7] offset:2112
	v_fma_mixlo_f16 v123, v99, v123, v155 op_sel_hi:[0,1,1]
	global_store_short v8, v123, s[6:7] offset:2048
	v_fma_mixlo_f16 v124, v83, v124, v166 op_sel_hi:[0,1,1]
	global_store_short v8, v124, s[6:7] offset:2112
	v_fma_mixlo_f16 v125, v100, v125, v167 op_sel_hi:[0,1,1]
	global_store_short v9, v125, s[6:7] offset:2048
	v_fma_mixlo_f16 v126, v84, v126, v168 op_sel_hi:[0,1,1]
	global_store_short v9, v126, s[6:7] offset:2112
	v_fma_mixlo_f16 v127, v101, v127, v169 op_sel_hi:[0,1,1]
	global_store_short v10, v127, s[6:7] offset:2048
	v_fma_mixlo_f16 v128, v85, v128, v170 op_sel_hi:[0,1,1]
	global_store_short v10, v128, s[6:7] offset:2112
	v_fma_mixlo_f16 v129, v102, v129, v171 op_sel_hi:[0,1,1]
	global_store_short v11, v129, s[6:7] offset:2048
	v_fma_mixlo_f16 v130, v86, v130, v172 op_sel_hi:[0,1,1]
	global_store_short v11, v130, s[6:7] offset:2112
	v_fma_mixlo_f16 v131, v103, v131, v173 op_sel_hi:[0,1,1]
	global_store_short v12, v131, s[6:7] offset:2048
; DI bf16_t cv1(float x) { return (bf16_t)(pk2(x, 0.f) & 0xffffu); }
; DI float bf2f(bf16_t v) { return (float)__builtin_bit_cast(_Float16, v); }
; DI int crow(int i, int h) { return (i & 3) + 8 * (i >> 2) + 4 * h; }
;     DI void operator()(int unit, const f32x16 (&acc)[MT][NT]) const {
;     ...
; #pragma unroll
;         for (int mi = 0; mi < MT; ++mi)
; #pragma unroll
;             for (int nj = 0; nj < NT; ++nj)
; #pragma unroll
;                 for (int i = 0; i < 16; ++i) {
;                     bf16_t* rowp = priv + (mi * 32 + crow(i, h) + (mi == 2 ? d2 : 0)) * PRIVW; const int c = unit * UW + nj * 32 + r;
;                     float v = bf2f(rowp[gcol + c]) * acc[mi][nj][i];
;                     if (SECOND) v += bf2f(rowp[PC_M + c]);
;                     rowp[PC_M + c] = cv1(v);
;                     if (i == 15) __builtin_amdgcn_sched_barrier(0);
	v_fma_mixlo_f16 v132, v87, v132, v174 op_sel_hi:[0,1,1]
	global_store_short v12, v132, s[6:7] offset:2112
	v_fma_mixlo_f16 v133, v104, v133, v175 op_sel_hi:[0,1,1]
	global_store_short v13, v133, s[6:7] offset:2048
	v_fma_mixlo_f16 v134, v88, v134, v180 op_sel_hi:[0,1,1]
	global_store_short v13, v134, s[6:7] offset:2112
	v_fma_mixlo_f16 v135, v105, v135, v181 op_sel_hi:[0,1,1]
	global_store_short v14, v135, s[6:7] offset:2048
	v_fma_mixlo_f16 v136, v89, v136, v182 op_sel_hi:[0,1,1]
	global_store_short v14, v136, s[6:7] offset:2112
	v_fma_mixlo_f16 v137, v106, v137, v183 op_sel_hi:[0,1,1]
	global_store_short v15, v137, s[6:7] offset:2048
	v_fma_mixlo_f16 v138, v90, v138, v184 op_sel_hi:[0,1,1]
	global_store_short v15, v138, s[6:7] offset:2112
	v_fma_mixlo_f16 v139, v107, v139, v219 op_sel_hi:[0,1,1]
	global_store_short v112, v139, s[6:7] offset:2048
	v_fma_mixlo_f16 v140, v91, v140, v233 op_sel_hi:[0,1,1]
	global_store_short v112, v140, s[6:7] offset:2112
	v_fma_mixlo_f16 v141, v108, v141, v234 op_sel_hi:[0,1,1]
	global_store_short v113, v141, s[6:7] offset:2048
	v_fma_mixlo_f16 v142, v92, v142, v235 op_sel_hi:[0,1,1]
	global_store_short v113, v142, s[6:7] offset:2112
	v_fma_mixlo_f16 v143, v109, v143, v236 op_sel_hi:[0,1,1]
	global_store_short v114, v143, s[6:7] offset:2048
	v_fma_mixlo_f16 v144, v93, v144, v237 op_sel_hi:[0,1,1]
	global_store_short v114, v144, s[6:7] offset:2112
	v_fma_mixlo_f16 v145, v110, v145, v238 op_sel_hi:[0,1,1]
	global_store_short v115, v145, s[6:7] offset:2048
	v_fma_mixlo_f16 v146, v94, v146, v239 op_sel_hi:[0,1,1]
	global_store_short v115, v146, s[6:7] offset:2112
	v_fma_mixlo_f16 v147, v111, v147, v240 op_sel_hi:[0,1,1]
	global_store_short v116, v147, s[6:7] offset:2048
	v_fma_mixlo_f16 v148, v95, v148, v241 op_sel_hi:[0,1,1]
	global_store_short v116, v148, s[6:7] offset:2112
	v_add_u32_e32 v5, 0x59800, v4
	global_load_ushort v117, v5, s[6:7] offset:-2048
	global_load_ushort v149, v5, s[6:7] offset:2048
	global_load_ushort v118, v5, s[6:7] offset:-1984
	global_load_ushort v150, v5, s[6:7] offset:2112
	v_add_u32_e32 v6, 0x5c400, v4
	global_load_ushort v119, v6, s[6:7] offset:-2048
	global_load_ushort v151, v6, s[6:7] offset:2048
	global_load_ushort v120, v6, s[6:7] offset:-1984
	global_load_ushort v152, v6, s[6:7] offset:2112
	v_add_u32_e32 v7, 0x5f000, v4
	global_load_ushort v121, v7, s[6:7] offset:-2048
	global_load_ushort v153, v7, s[6:7] offset:2048
	global_load_ushort v122, v7, s[6:7] offset:-1984
	global_load_ushort v154, v7, s[6:7] offset:2112
	v_add_u32_e32 v8, 0x61c00, v4
	global_load_ushort v123, v8, s[6:7] offset:-2048
	global_load_ushort v155, v8, s[6:7] offset:2048
	global_load_ushort v124, v8, s[6:7] offset:-1984
	global_load_ushort v166, v8, s[6:7] offset:2112
	v_add_u32_e32 v9, 0x6f800, v4
	global_load_ushort v125, v9, s[6:7] offset:-2048
	global_load_ushort v167, v9, s[6:7] offset:2048
	global_load_ushort v126, v9, s[6:7] offset:-1984
	global_load_ushort v168, v9, s[6:7] offset:2112
	v_add_u32_e32 v10, 0x72400, v4
	global_load_ushort v127, v10, s[6:7] offset:-2048
	global_load_ushort v169, v10, s[6:7] offset:2048
	global_load_ushort v128, v10, s[6:7] offset:-1984
	global_load_ushort v170, v10, s[6:7] offset:2112
	v_add_u32_e32 v11, 0x75000, v4
	global_load_ushort v129, v11, s[6:7] offset:-2048
	global_load_ushort v171, v11, s[6:7] offset:2048
	global_load_ushort v130, v11, s[6:7] offset:-1984
	global_load_ushort v172, v11, s[6:7] offset:2112
	v_add_u32_e32 v12, 0x77c00, v4
	global_load_ushort v131, v12, s[6:7] offset:-2048
	global_load_ushort v173, v12, s[6:7] offset:2048
	global_load_ushort v132, v12, s[6:7] offset:-1984
	global_load_ushort v174, v12, s[6:7] offset:2112
	v_add_u32_e32 v13, 0x85800, v4
	global_load_ushort v133, v13, s[6:7] offset:-2048
	global_load_ushort v175, v13, s[6:7] offset:2048
	global_load_ushort v134, v13, s[6:7] offset:-1984
	global_load_ushort v180, v13, s[6:7] offset:2112
	v_add_u32_e32 v14, 0x88400, v4
	global_load_ushort v135, v14, s[6:7] offset:-2048
	global_load_ushort v181, v14, s[6:7] offset:2048
	global_load_ushort v136, v14, s[6:7] offset:-1984
	global_load_ushort v182, v14, s[6:7] offset:2112
	v_add_u32_e32 v15, 0x8b000, v4
	global_load_ushort v137, v15, s[6:7] offset:-2048
	global_load_ushort v183, v15, s[6:7] offset:2048
	global_load_ushort v138, v15, s[6:7] offset:-1984
	global_load_ushort v184, v15, s[6:7] offset:2112
	v_add_u32_e32 v112, 0x8dc00, v4
	global_load_ushort v139, v112, s[6:7] offset:-2048
	global_load_ushort v219, v112, s[6:7] offset:2048
	global_load_ushort v140, v112, s[6:7] offset:-1984
	global_load_ushort v233, v112, s[6:7] offset:2112
	v_add_u32_e32 v113, 0x9b800, v4
	global_load_ushort v141, v113, s[6:7] offset:-2048
	global_load_ushort v234, v113, s[6:7] offset:2048
	global_load_ushort v142, v113, s[6:7] offset:-1984
	global_load_ushort v235, v113, s[6:7] offset:2112
	v_add_u32_e32 v114, 0x9e400, v4
	global_load_ushort v143, v114, s[6:7] offset:-2048
	global_load_ushort v236, v114, s[6:7] offset:2048
	global_load_ushort v144, v114, s[6:7] offset:-1984
	global_load_ushort v237, v114, s[6:7] offset:2112
	v_add_u32_e32 v115, 0xa1000, v4
	global_load_ushort v145, v115, s[6:7] offset:-2048
	global_load_ushort v238, v115, s[6:7] offset:2048
	global_load_ushort v146, v115, s[6:7] offset:-1984
	global_load_ushort v239, v115, s[6:7] offset:2112
	v_add_u32_e32 v116, 0xa3c00, v4
	global_load_ushort v147, v116, s[6:7] offset:-2048
	global_load_ushort v240, v116, s[6:7] offset:2048
	global_load_ushort v148, v116, s[6:7] offset:-1984
	global_load_ushort v241, v116, s[6:7] offset:2112
	s_waitcnt vmcnt(0)
; DI bf16_t cv1(float x) { return (bf16_t)(pk2(x, 0.f) & 0xffffu); }
; DI float bf2f(bf16_t v) { return (float)__builtin_bit_cast(_Float16, v); }
; DI int crow(int i, int h) { return (i & 3) + 8 * (i >> 2) + 4 * h; }
;     DI void operator()(int unit, const f32x16 (&acc)[MT][NT]) const {
;     ...
; #pragma unroll
;         for (int mi = 0; mi < MT; ++mi)
; #pragma unroll
;             for (int nj = 0; nj < NT; ++nj)
; #pragma unroll
;                 for (int i = 0; i < 16; ++i) {
;                     bf16_t* rowp = priv + (mi * 32 + crow(i, h) + (mi == 2 ? d2 : 0)) * PRIVW; const int c = unit * UW + nj * 32 + r;
;                     float v = bf2f(rowp[gcol + c]) * acc[mi][nj][i];
;                     if (SECOND) v += bf2f(rowp[PC_M + c]);
;                     rowp[PC_M + c] = cv1(v);
;                     if (i == 15) __builtin_amdgcn_sched_barrier(0);
	v_fma_mixlo_f16 v117, v64, v117, v149 op_sel_hi:[0,1,1]
	global_store_short v5, v117, s[6:7] offset:2048
	v_fma_mixlo_f16 v118, v48, v118, v150 op_sel_hi:[0,1,1]
	global_store_short v5, v118, s[6:7] offset:2112
	v_fma_mixlo_f16 v119, v65, v119, v151 op_sel_hi:[0,1,1]
	global_store_short v6, v119, s[6:7] offset:2048
	v_fma_mixlo_f16 v120, v49, v120, v152 op_sel_hi:[0,1,1]
	global_store_short v6, v120, s[6:7] offset:2112
	v_fma_mixlo_f16 v121, v66, v121, v153 op_sel_hi:[0,1,1]
	global_store_short v7, v121, s[6:7] offset:2048
	v_fma_mixlo_f16 v122, v50, v122, v154 op_sel_hi:[0,1,1]
	global_store_short v7, v122, s[6:7] offset:2112
	v_fma_mixlo_f16 v123, v67, v123, v155 op_sel_hi:[0,1,1]
	global_store_short v8, v123, s[6:7] offset:2048
	v_fma_mixlo_f16 v124, v51, v124, v166 op_sel_hi:[0,1,1]
	global_store_short v8, v124, s[6:7] offset:2112
	v_fma_mixlo_f16 v125, v68, v125, v167 op_sel_hi:[0,1,1]
	global_store_short v9, v125, s[6:7] offset:2048
	v_fma_mixlo_f16 v126, v52, v126, v168 op_sel_hi:[0,1,1]
	global_store_short v9, v126, s[6:7] offset:2112
	v_fma_mixlo_f16 v127, v69, v127, v169 op_sel_hi:[0,1,1]
	global_store_short v10, v127, s[6:7] offset:2048
	v_fma_mixlo_f16 v128, v53, v128, v170 op_sel_hi:[0,1,1]
	global_store_short v10, v128, s[6:7] offset:2112
	v_fma_mixlo_f16 v129, v70, v129, v171 op_sel_hi:[0,1,1]
	global_store_short v11, v129, s[6:7] offset:2048
	v_fma_mixlo_f16 v130, v54, v130, v172 op_sel_hi:[0,1,1]
	global_store_short v11, v130, s[6:7] offset:2112
	v_fma_mixlo_f16 v131, v71, v131, v173 op_sel_hi:[0,1,1]
	global_store_short v12, v131, s[6:7] offset:2048
	v_fma_mixlo_f16 v132, v55, v132, v174 op_sel_hi:[0,1,1]
	global_store_short v12, v132, s[6:7] offset:2112
	v_fma_mixlo_f16 v133, v72, v133, v175 op_sel_hi:[0,1,1]
	global_store_short v13, v133, s[6:7] offset:2048
	v_fma_mixlo_f16 v134, v56, v134, v180 op_sel_hi:[0,1,1]
	global_store_short v13, v134, s[6:7] offset:2112
	v_fma_mixlo_f16 v135, v73, v135, v181 op_sel_hi:[0,1,1]
	global_store_short v14, v135, s[6:7] offset:2048
	v_fma_mixlo_f16 v136, v57, v136, v182 op_sel_hi:[0,1,1]
	global_store_short v14, v136, s[6:7] offset:2112
	v_fma_mixlo_f16 v137, v74, v137, v183 op_sel_hi:[0,1,1]
	global_store_short v15, v137, s[6:7] offset:2048
	v_fma_mixlo_f16 v138, v58, v138, v184 op_sel_hi:[0,1,1]
	global_store_short v15, v138, s[6:7] offset:2112
	v_fma_mixlo_f16 v139, v75, v139, v219 op_sel_hi:[0,1,1]
	global_store_short v112, v139, s[6:7] offset:2048
	v_fma_mixlo_f16 v140, v59, v140, v233 op_sel_hi:[0,1,1]
	global_store_short v112, v140, s[6:7] offset:2112
	v_fma_mixlo_f16 v141, v76, v141, v234 op_sel_hi:[0,1,1]
	global_store_short v113, v141, s[6:7] offset:2048
	v_fma_mixlo_f16 v142, v60, v142, v235 op_sel_hi:[0,1,1]
	global_store_short v113, v142, s[6:7] offset:2112
	v_fma_mixlo_f16 v143, v77, v143, v236 op_sel_hi:[0,1,1]
	global_store_short v114, v143, s[6:7] offset:2048
	v_fma_mixlo_f16 v144, v61, v144, v237 op_sel_hi:[0,1,1]
	global_store_short v114, v144, s[6:7] offset:2112
	v_fma_mixlo_f16 v145, v78, v145, v238 op_sel_hi:[0,1,1]
	global_store_short v115, v145, s[6:7] offset:2048
	v_fma_mixlo_f16 v146, v62, v146, v239 op_sel_hi:[0,1,1]
	global_store_short v115, v146, s[6:7] offset:2112
	v_fma_mixlo_f16 v147, v79, v147, v240 op_sel_hi:[0,1,1]
	global_store_short v116, v147, s[6:7] offset:2048
	v_fma_mixlo_f16 v148, v63, v148, v241 op_sel_hi:[0,1,1]
	global_store_short v116, v148, s[6:7] offset:2112
	s_sub_i32 s100, 0x4000, s62
	s_mul_i32 s101, s100, 0x2c00
	v_add_u32_e32 v3, s101, v4
	v_add_u32_e32 v5, 0x1800, v3
	global_load_ushort v117, v5, s[6:7] offset:-2048
	global_load_ushort v149, v5, s[6:7] offset:2048
	global_load_ushort v118, v5, s[6:7] offset:-1984
	global_load_ushort v150, v5, s[6:7] offset:2112
	v_add_u32_e32 v6, 0x4400, v3
	global_load_ushort v119, v6, s[6:7] offset:-2048
	global_load_ushort v151, v6, s[6:7] offset:2048
	global_load_ushort v120, v6, s[6:7] offset:-1984
	global_load_ushort v152, v6, s[6:7] offset:2112
	v_add_u32_e32 v7, 0x7000, v3
	global_load_ushort v121, v7, s[6:7] offset:-2048
	global_load_ushort v153, v7, s[6:7] offset:2048
	global_load_ushort v122, v7, s[6:7] offset:-1984
	global_load_ushort v154, v7, s[6:7] offset:2112
	v_add_u32_e32 v8, 0x9c00, v3
	global_load_ushort v123, v8, s[6:7] offset:-2048
	global_load_ushort v155, v8, s[6:7] offset:2048
	global_load_ushort v124, v8, s[6:7] offset:-1984
	global_load_ushort v166, v8, s[6:7] offset:2112
	v_add_u32_e32 v9, 0x17800, v3
	global_load_ushort v125, v9, s[6:7] offset:-2048
	global_load_ushort v167, v9, s[6:7] offset:2048
	global_load_ushort v126, v9, s[6:7] offset:-1984
	global_load_ushort v168, v9, s[6:7] offset:2112
	v_add_u32_e32 v10, 0x1a400, v3
	global_load_ushort v127, v10, s[6:7] offset:-2048
	global_load_ushort v169, v10, s[6:7] offset:2048
	global_load_ushort v128, v10, s[6:7] offset:-1984
	global_load_ushort v170, v10, s[6:7] offset:2112
	v_add_u32_e32 v11, 0x1d000, v3
	global_load_ushort v129, v11, s[6:7] offset:-2048
	global_load_ushort v171, v11, s[6:7] offset:2048
	global_load_ushort v130, v11, s[6:7] offset:-1984
	global_load_ushort v172, v11, s[6:7] offset:2112
	v_add_u32_e32 v12, 0x1fc00, v3
	global_load_ushort v131, v12, s[6:7] offset:-2048
	global_load_ushort v173, v12, s[6:7] offset:2048
	global_load_ushort v132, v12, s[6:7] offset:-1984
	global_load_ushort v174, v12, s[6:7] offset:2112
; DI bf16_t cv1(float x) { return (bf16_t)(pk2(x, 0.f) & 0xffffu); }
; DI float bf2f(bf16_t v) { return (float)__builtin_bit_cast(_Float16, v); }
; DI int crow(int i, int h) { return (i & 3) + 8 * (i >> 2) + 4 * h; }
;     DI void operator()(int unit, const f32x16 (&acc)[MT][NT]) const {
;     ...
; #pragma unroll
;         for (int mi = 0; mi < MT; ++mi)
; #pragma unroll
;             for (int nj = 0; nj < NT; ++nj)
; #pragma unroll
;                 for (int i = 0; i < 16; ++i) {
;                     bf16_t* rowp = priv + (mi * 32 + crow(i, h) + (mi == 2 ? d2 : 0)) * PRIVW; const int c = unit * UW + nj * 32 + r;
;                     float v = bf2f(rowp[gcol + c]) * acc[mi][nj][i];
;                     if (SECOND) v += bf2f(rowp[PC_M + c]);
;                     rowp[PC_M + c] = cv1(v);
;                     if (i == 15) __builtin_amdgcn_sched_barrier(0);
	v_add_u32_e32 v13, 0x2d800, v3
	global_load_ushort v133, v13, s[6:7] offset:-2048
	global_load_ushort v175, v13, s[6:7] offset:2048
	global_load_ushort v134, v13, s[6:7] offset:-1984
	global_load_ushort v180, v13, s[6:7] offset:2112
	v_add_u32_e32 v14, 0x30400, v3
	global_load_ushort v135, v14, s[6:7] offset:-2048
	global_load_ushort v181, v14, s[6:7] offset:2048
	global_load_ushort v136, v14, s[6:7] offset:-1984
	global_load_ushort v182, v14, s[6:7] offset:2112
	v_add_u32_e32 v15, 0x33000, v3
	global_load_ushort v137, v15, s[6:7] offset:-2048
	global_load_ushort v183, v15, s[6:7] offset:2048
	global_load_ushort v138, v15, s[6:7] offset:-1984
	global_load_ushort v184, v15, s[6:7] offset:2112
	v_add_u32_e32 v112, 0x35c00, v3
	global_load_ushort v139, v112, s[6:7] offset:-2048
	global_load_ushort v219, v112, s[6:7] offset:2048
	global_load_ushort v140, v112, s[6:7] offset:-1984
	global_load_ushort v233, v112, s[6:7] offset:2112
	v_add_u32_e32 v113, 0x43800, v3
	global_load_ushort v141, v113, s[6:7] offset:-2048
	global_load_ushort v234, v113, s[6:7] offset:2048
	global_load_ushort v142, v113, s[6:7] offset:-1984
	global_load_ushort v235, v113, s[6:7] offset:2112
	v_add_u32_e32 v114, 0x46400, v3
	global_load_ushort v143, v114, s[6:7] offset:-2048
	global_load_ushort v236, v114, s[6:7] offset:2048
	global_load_ushort v144, v114, s[6:7] offset:-1984
	global_load_ushort v237, v114, s[6:7] offset:2112
	v_add_u32_e32 v115, 0x49000, v3
	global_load_ushort v145, v115, s[6:7] offset:-2048
	global_load_ushort v238, v115, s[6:7] offset:2048
	global_load_ushort v146, v115, s[6:7] offset:-1984
	global_load_ushort v239, v115, s[6:7] offset:2112
	v_add_u32_e32 v116, 0x4bc00, v3
	global_load_ushort v147, v116, s[6:7] offset:-2048
	global_load_ushort v240, v116, s[6:7] offset:2048
	global_load_ushort v148, v116, s[6:7] offset:-1984
	global_load_ushort v241, v116, s[6:7] offset:2112
	s_waitcnt vmcnt(0)
	v_fma_mixlo_f16 v117, v32, v117, v149 op_sel_hi:[0,1,1]
	global_store_short v5, v117, s[6:7] offset:2048
	v_fma_mixlo_f16 v118, v16, v118, v150 op_sel_hi:[0,1,1]
	global_store_short v5, v118, s[6:7] offset:2112
	v_fma_mixlo_f16 v119, v33, v119, v151 op_sel_hi:[0,1,1]
	global_store_short v6, v119, s[6:7] offset:2048
	v_fma_mixlo_f16 v120, v17, v120, v152 op_sel_hi:[0,1,1]
	global_store_short v6, v120, s[6:7] offset:2112
	v_fma_mixlo_f16 v121, v34, v121, v153 op_sel_hi:[0,1,1]
	global_store_short v7, v121, s[6:7] offset:2048
	v_fma_mixlo_f16 v122, v18, v122, v154 op_sel_hi:[0,1,1]
	global_store_short v7, v122, s[6:7] offset:2112
	v_fma_mixlo_f16 v123, v35, v123, v155 op_sel_hi:[0,1,1]
	global_store_short v8, v123, s[6:7] offset:2048
	v_fma_mixlo_f16 v124, v19, v124, v166 op_sel_hi:[0,1,1]
	global_store_short v8, v124, s[6:7] offset:2112
	v_fma_mixlo_f16 v125, v36, v125, v167 op_sel_hi:[0,1,1]
	global_store_short v9, v125, s[6:7] offset:2048
	v_fma_mixlo_f16 v126, v20, v126, v168 op_sel_hi:[0,1,1]
	global_store_short v9, v126, s[6:7] offset:2112
	v_fma_mixlo_f16 v127, v37, v127, v169 op_sel_hi:[0,1,1]
	global_store_short v10, v127, s[6:7] offset:2048
	v_fma_mixlo_f16 v128, v21, v128, v170 op_sel_hi:[0,1,1]
	global_store_short v10, v128, s[6:7] offset:2112
	v_fma_mixlo_f16 v129, v38, v129, v171 op_sel_hi:[0,1,1]
	global_store_short v11, v129, s[6:7] offset:2048
	v_fma_mixlo_f16 v130, v22, v130, v172 op_sel_hi:[0,1,1]
	global_store_short v11, v130, s[6:7] offset:2112
	v_fma_mixlo_f16 v131, v39, v131, v173 op_sel_hi:[0,1,1]
	global_store_short v12, v131, s[6:7] offset:2048
	v_fma_mixlo_f16 v132, v23, v132, v174 op_sel_hi:[0,1,1]
	global_store_short v12, v132, s[6:7] offset:2112
	v_fma_mixlo_f16 v133, v40, v133, v175 op_sel_hi:[0,1,1]
	global_store_short v13, v133, s[6:7] offset:2048
	v_fma_mixlo_f16 v134, v24, v134, v180 op_sel_hi:[0,1,1]
	global_store_short v13, v134, s[6:7] offset:2112
	v_fma_mixlo_f16 v135, v41, v135, v181 op_sel_hi:[0,1,1]
	global_store_short v14, v135, s[6:7] offset:2048
	v_fma_mixlo_f16 v136, v25, v136, v182 op_sel_hi:[0,1,1]
	global_store_short v14, v136, s[6:7] offset:2112
	v_fma_mixlo_f16 v137, v42, v137, v183 op_sel_hi:[0,1,1]
	global_store_short v15, v137, s[6:7] offset:2048
	v_fma_mixlo_f16 v138, v26, v138, v184 op_sel_hi:[0,1,1]
	global_store_short v15, v138, s[6:7] offset:2112
	v_fma_mixlo_f16 v139, v43, v139, v219 op_sel_hi:[0,1,1]
	global_store_short v112, v139, s[6:7] offset:2048
	v_fma_mixlo_f16 v140, v27, v140, v233 op_sel_hi:[0,1,1]
	global_store_short v112, v140, s[6:7] offset:2112
	v_fma_mixlo_f16 v141, v44, v141, v234 op_sel_hi:[0,1,1]
	global_store_short v113, v141, s[6:7] offset:2048
	v_fma_mixlo_f16 v142, v28, v142, v235 op_sel_hi:[0,1,1]
	global_store_short v113, v142, s[6:7] offset:2112
	v_fma_mixlo_f16 v143, v45, v143, v236 op_sel_hi:[0,1,1]
	global_store_short v114, v143, s[6:7] offset:2048
	v_fma_mixlo_f16 v144, v29, v144, v237 op_sel_hi:[0,1,1]
	global_store_short v114, v144, s[6:7] offset:2112
	v_fma_mixlo_f16 v145, v46, v145, v238 op_sel_hi:[0,1,1]
	global_store_short v115, v145, s[6:7] offset:2048
	v_fma_mixlo_f16 v146, v30, v146, v239 op_sel_hi:[0,1,1]
	global_store_short v115, v146, s[6:7] offset:2112
	v_fma_mixlo_f16 v147, v47, v147, v240 op_sel_hi:[0,1,1]
	global_store_short v116, v147, s[6:7] offset:2048
	v_fma_mixlo_f16 v148, v31, v148, v241 op_sel_hi:[0,1,1]
	global_store_short v116, v148, s[6:7] offset:2112
	s_waitcnt vmcnt(0)
	s_branch .LBB0_391

; DI int otid() { int t = threadIdx.x; asm volatile("" : "+v"(t)); return t; }
; DI int crow(int i, int h) { return (i & 3) + 8 * (i >> 2) + 4 * h; }
;     DI void operator()(int unit, const f32x16 (&acc)[MT][NT]) const {
;         const int lane = otid() & 63, r = lane & 31, h = lane >> 5;
; #pragma unroll
;         for (int mi = 0; mi < MT; ++mi)
; #pragma unroll
;             for (int nj = 0; nj < NT; ++nj)
; #pragma unroll
;                 for (int i = 0; i < 16; ++i) { float* q = x + ((mi * 32 + crow(i, h) + (mi == 2 ? d2 : 0)) * DM + unit * UW + nj * 32 + r); *q = *q + acc[mi][nj][i]; if (i == 15) __builtin_amdgcn_sched_barrier(0); }
.LBB0_416:
	s_and_saveexec_b64 s[56:57], s[4:5]
	s_cbranch_execz .LBB0_405
	s_waitcnt vmcnt(0)
	v_and_b32_e32 v2, 31, v176
	v_lshlrev_b32_e32 v3, 9, v176
	v_and_b32_e32 v3, 0x4000, v3
	v_lshl_or_b32 v4, v2, 2, v3
	v_lshl_add_u32 v4, v232, 8, v4
	v_add_u32_e32 v5, 0x1000, v4
	global_load_dword v13, v5, s[0:1] offset:-4096
	global_load_dword v14, v5, s[0:1] offset:-3968
	global_load_dword v15, v5, s[0:1] offset:0
	global_load_dword v112, v5, s[0:1] offset:128
	v_add_u32_e32 v6, 0x3000, v4
	global_load_dword v113, v6, s[0:1] offset:-4096
	global_load_dword v114, v6, s[0:1] offset:-3968
	global_load_dword v115, v6, s[0:1] offset:0
	global_load_dword v116, v6, s[0:1] offset:128
	v_add_u32_e32 v7, 0x9000, v4
	global_load_dword v117, v7, s[0:1] offset:-4096
	global_load_dword v118, v7, s[0:1] offset:-3968
	global_load_dword v119, v7, s[0:1] offset:0
	global_load_dword v120, v7, s[0:1] offset:128
	v_add_u32_e32 v8, 0xb000, v4
	global_load_dword v121, v8, s[0:1] offset:-4096
	global_load_dword v122, v8, s[0:1] offset:-3968
	global_load_dword v123, v8, s[0:1] offset:0
	global_load_dword v124, v8, s[0:1] offset:128
	v_add_u32_e32 v9, 0x11000, v4
	global_load_dword v125, v9, s[0:1] offset:-4096
	global_load_dword v126, v9, s[0:1] offset:-3968
	global_load_dword v127, v9, s[0:1] offset:0
	global_load_dword v128, v9, s[0:1] offset:128
	v_add_u32_e32 v10, 0x13000, v4
	global_load_dword v129, v10, s[0:1] offset:-4096
	global_load_dword v130, v10, s[0:1] offset:-3968
	global_load_dword v131, v10, s[0:1] offset:0
	global_load_dword v132, v10, s[0:1] offset:128
	v_add_u32_e32 v11, 0x19000, v4
	global_load_dword v133, v11, s[0:1] offset:-4096
	global_load_dword v134, v11, s[0:1] offset:-3968
	global_load_dword v135, v11, s[0:1] offset:0
	global_load_dword v136, v11, s[0:1] offset:128
	v_add_u32_e32 v12, 0x1b000, v4
	global_load_dword v137, v12, s[0:1] offset:-4096
	global_load_dword v138, v12, s[0:1] offset:-3968
	global_load_dword v139, v12, s[0:1] offset:0
	global_load_dword v140, v12, s[0:1] offset:128
	s_waitcnt vmcnt(0)
	v_add_f32_e32 v13, v96, v13
	global_store_dword v5, v13, s[0:1] offset:-4096
	v_add_f32_e32 v14, v80, v14
	global_store_dword v5, v14, s[0:1] offset:-3968
	v_add_f32_e32 v15, v97, v15
	global_store_dword v5, v15, s[0:1] offset:0
	v_add_f32_e32 v112, v81, v112
	global_store_dword v5, v112, s[0:1] offset:128
	v_add_f32_e32 v113, v98, v113
	global_store_dword v6, v113, s[0:1] offset:-4096
	v_add_f32_e32 v114, v82, v114
	global_store_dword v6, v114, s[0:1] offset:-3968
	v_add_f32_e32 v115, v99, v115
	global_store_dword v6, v115, s[0:1] offset:0
	v_add_f32_e32 v116, v83, v116
	global_store_dword v6, v116, s[0:1] offset:128
	v_add_f32_e32 v117, v100, v117
	global_store_dword v7, v117, s[0:1] offset:-4096
	v_add_f32_e32 v118, v84, v118
	global_store_dword v7, v118, s[0:1] offset:-3968
	v_add_f32_e32 v119, v101, v119
	global_store_dword v7, v119, s[0:1] offset:0
	v_add_f32_e32 v120, v85, v120
	global_store_dword v7, v120, s[0:1] offset:128
	v_add_f32_e32 v121, v102, v121
	global_store_dword v8, v121, s[0:1] offset:-4096
	v_add_f32_e32 v122, v86, v122
	global_store_dword v8, v122, s[0:1] offset:-3968
	v_add_f32_e32 v123, v103, v123
	global_store_dword v8, v123, s[0:1] offset:0
	v_add_f32_e32 v124, v87, v124
	global_store_dword v8, v124, s[0:1] offset:128
	v_add_f32_e32 v125, v104, v125
	global_store_dword v9, v125, s[0:1] offset:-4096
	v_add_f32_e32 v126, v88, v126
	global_store_dword v9, v126, s[0:1] offset:-3968
	v_add_f32_e32 v127, v105, v127
	global_store_dword v9, v127, s[0:1] offset:0
	v_add_f32_e32 v128, v89, v128
	global_store_dword v9, v128, s[0:1] offset:128
	v_add_f32_e32 v129, v106, v129
	global_store_dword v10, v129, s[0:1] offset:-4096
	v_add_f32_e32 v130, v90, v130
	global_store_dword v10, v130, s[0:1] offset:-3968
	v_add_f32_e32 v131, v107, v131
	global_store_dword v10, v131, s[0:1] offset:0
	v_add_f32_e32 v132, v91, v132
	global_store_dword v10, v132, s[0:1] offset:128
	v_add_f32_e32 v133, v108, v133
	global_store_dword v11, v133, s[0:1] offset:-4096
	v_add_f32_e32 v134, v92, v134
	global_store_dword v11, v134, s[0:1] offset:-3968
	v_add_f32_e32 v135, v109, v135
	global_store_dword v11, v135, s[0:1] offset:0
	v_add_f32_e32 v136, v93, v136
	global_store_dword v11, v136, s[0:1] offset:128
	v_add_f32_e32 v137, v110, v137
	global_store_dword v12, v137, s[0:1] offset:-4096
	v_add_f32_e32 v138, v94, v138
	global_store_dword v12, v138, s[0:1] offset:-3968
	v_add_f32_e32 v139, v111, v139
	global_store_dword v12, v139, s[0:1] offset:0
	v_add_f32_e32 v140, v95, v140
	global_store_dword v12, v140, s[0:1] offset:128
	v_add_u32_e32 v5, 0x21000, v4
	global_load_dword v13, v5, s[0:1] offset:-4096
	global_load_dword v14, v5, s[0:1] offset:-3968
	global_load_dword v15, v5, s[0:1] offset:0
	global_load_dword v112, v5, s[0:1] offset:128
	v_add_u32_e32 v6, 0x23000, v4
	global_load_dword v113, v6, s[0:1] offset:-4096
	global_load_dword v114, v6, s[0:1] offset:-3968
	global_load_dword v115, v6, s[0:1] offset:0
	global_load_dword v116, v6, s[0:1] offset:128
	v_add_u32_e32 v7, 0x29000, v4
	global_load_dword v117, v7, s[0:1] offset:-4096
	global_load_dword v118, v7, s[0:1] offset:-3968
	global_load_dword v119, v7, s[0:1] offset:0
	global_load_dword v120, v7, s[0:1] offset:128
	v_add_u32_e32 v8, 0x2b000, v4
	global_load_dword v121, v8, s[0:1] offset:-4096
	global_load_dword v122, v8, s[0:1] offset:-3968
	global_load_dword v123, v8, s[0:1] offset:0
	global_load_dword v124, v8, s[0:1] offset:128
	v_add_u32_e32 v9, 0x31000, v4
	global_load_dword v125, v9, s[0:1] offset:-4096
	global_load_dword v126, v9, s[0:1] offset:-3968
	global_load_dword v127, v9, s[0:1] offset:0
	global_load_dword v128, v9, s[0:1] offset:128
	v_add_u32_e32 v10, 0x33000, v4
	global_load_dword v129, v10, s[0:1] offset:-4096
	global_load_dword v130, v10, s[0:1] offset:-3968
	global_load_dword v131, v10, s[0:1] offset:0
	global_load_dword v132, v10, s[0:1] offset:128
	v_add_u32_e32 v11, 0x39000, v4
	global_load_dword v133, v11, s[0:1] offset:-4096
	global_load_dword v134, v11, s[0:1] offset:-3968
	global_load_dword v135, v11, s[0:1] offset:0
	global_load_dword v136, v11, s[0:1] offset:128
	v_add_u32_e32 v12, 0x3b000, v4
	global_load_dword v137, v12, s[0:1] offset:-4096
	global_load_dword v138, v12, s[0:1] offset:-3968
	global_load_dword v139, v12, s[0:1] offset:0
	global_load_dword v140, v12, s[0:1] offset:128
	s_waitcnt vmcnt(0)
; DI int otid() { int t = threadIdx.x; asm volatile("" : "+v"(t)); return t; }
; DI int crow(int i, int h) { return (i & 3) + 8 * (i >> 2) + 4 * h; }
;     DI void operator()(int unit, const f32x16 (&acc)[MT][NT]) const {
;         const int lane = otid() & 63, r = lane & 31, h = lane >> 5;
; #pragma unroll
;         for (int mi = 0; mi < MT; ++mi)
; #pragma unroll
;             for (int nj = 0; nj < NT; ++nj)
; #pragma unroll
;                 for (int i = 0; i < 16; ++i) { float* q = x + ((mi * 32 + crow(i, h) + (mi == 2 ? d2 : 0)) * DM + unit * UW + nj * 32 + r); *q = *q + acc[mi][nj][i]; if (i == 15) __builtin_amdgcn_sched_barrier(0); }
	v_add_f32_e32 v13, v64, v13
	global_store_dword v5, v13, s[0:1] offset:-4096
	v_add_f32_e32 v14, v48, v14
	global_store_dword v5, v14, s[0:1] offset:-3968
	v_add_f32_e32 v15, v65, v15
	global_store_dword v5, v15, s[0:1] offset:0
	v_add_f32_e32 v112, v49, v112
	global_store_dword v5, v112, s[0:1] offset:128
	v_add_f32_e32 v113, v66, v113
	global_store_dword v6, v113, s[0:1] offset:-4096
	v_add_f32_e32 v114, v50, v114
	global_store_dword v6, v114, s[0:1] offset:-3968
	v_add_f32_e32 v115, v67, v115
	global_store_dword v6, v115, s[0:1] offset:0
	v_add_f32_e32 v116, v51, v116
	global_store_dword v6, v116, s[0:1] offset:128
	v_add_f32_e32 v117, v68, v117
	global_store_dword v7, v117, s[0:1] offset:-4096
	v_add_f32_e32 v118, v52, v118
	global_store_dword v7, v118, s[0:1] offset:-3968
	v_add_f32_e32 v119, v69, v119
	global_store_dword v7, v119, s[0:1] offset:0
	v_add_f32_e32 v120, v53, v120
	global_store_dword v7, v120, s[0:1] offset:128
	v_add_f32_e32 v121, v70, v121
	global_store_dword v8, v121, s[0:1] offset:-4096
	v_add_f32_e32 v122, v54, v122
	global_store_dword v8, v122, s[0:1] offset:-3968
	v_add_f32_e32 v123, v71, v123
	global_store_dword v8, v123, s[0:1] offset:0
	v_add_f32_e32 v124, v55, v124
	global_store_dword v8, v124, s[0:1] offset:128
	v_add_f32_e32 v125, v72, v125
	global_store_dword v9, v125, s[0:1] offset:-4096
	v_add_f32_e32 v126, v56, v126
	global_store_dword v9, v126, s[0:1] offset:-3968
	v_add_f32_e32 v127, v73, v127
	global_store_dword v9, v127, s[0:1] offset:0
	v_add_f32_e32 v128, v57, v128
	global_store_dword v9, v128, s[0:1] offset:128
	v_add_f32_e32 v129, v74, v129
	global_store_dword v10, v129, s[0:1] offset:-4096
	v_add_f32_e32 v130, v58, v130
	global_store_dword v10, v130, s[0:1] offset:-3968
	v_add_f32_e32 v131, v75, v131
	global_store_dword v10, v131, s[0:1] offset:0
	v_add_f32_e32 v132, v59, v132
	global_store_dword v10, v132, s[0:1] offset:128
	v_add_f32_e32 v133, v76, v133
	global_store_dword v11, v133, s[0:1] offset:-4096
	v_add_f32_e32 v134, v60, v134
	global_store_dword v11, v134, s[0:1] offset:-3968
	v_add_f32_e32 v135, v77, v135
	global_store_dword v11, v135, s[0:1] offset:0
	v_add_f32_e32 v136, v61, v136
	global_store_dword v11, v136, s[0:1] offset:128
	v_add_f32_e32 v137, v78, v137
	global_store_dword v12, v137, s[0:1] offset:-4096
	v_add_f32_e32 v138, v62, v138
	global_store_dword v12, v138, s[0:1] offset:-3968
	v_add_f32_e32 v139, v79, v139
	global_store_dword v12, v139, s[0:1] offset:0
	v_add_f32_e32 v140, v63, v140
	global_store_dword v12, v140, s[0:1] offset:128
	v_lshl_add_u32 v3, s59, 12, v4
	v_add_u32_e32 v5, 0x1000, v3
	global_load_dword v13, v5, s[0:1] offset:-4096
	global_load_dword v14, v5, s[0:1] offset:-3968
	global_load_dword v15, v5, s[0:1] offset:0
	global_load_dword v112, v5, s[0:1] offset:128
	v_add_u32_e32 v6, 0x3000, v3
	global_load_dword v113, v6, s[0:1] offset:-4096
	global_load_dword v114, v6, s[0:1] offset:-3968
	global_load_dword v115, v6, s[0:1] offset:0
	global_load_dword v116, v6, s[0:1] offset:128
	v_add_u32_e32 v7, 0x9000, v3
	global_load_dword v117, v7, s[0:1] offset:-4096
	global_load_dword v118, v7, s[0:1] offset:-3968
	global_load_dword v119, v7, s[0:1] offset:0
	global_load_dword v120, v7, s[0:1] offset:128
	v_add_u32_e32 v8, 0xb000, v3
	global_load_dword v121, v8, s[0:1] offset:-4096
	global_load_dword v122, v8, s[0:1] offset:-3968
	global_load_dword v123, v8, s[0:1] offset:0
	global_load_dword v124, v8, s[0:1] offset:128
	v_add_u32_e32 v9, 0x11000, v3
	global_load_dword v125, v9, s[0:1] offset:-4096
	global_load_dword v126, v9, s[0:1] offset:-3968
	global_load_dword v127, v9, s[0:1] offset:0
	global_load_dword v128, v9, s[0:1] offset:128
	v_add_u32_e32 v10, 0x13000, v3
	global_load_dword v129, v10, s[0:1] offset:-4096
	global_load_dword v130, v10, s[0:1] offset:-3968
	global_load_dword v131, v10, s[0:1] offset:0
	global_load_dword v132, v10, s[0:1] offset:128
	v_add_u32_e32 v11, 0x19000, v3
	global_load_dword v133, v11, s[0:1] offset:-4096
	global_load_dword v134, v11, s[0:1] offset:-3968
	global_load_dword v135, v11, s[0:1] offset:0
	global_load_dword v136, v11, s[0:1] offset:128
	v_add_u32_e32 v12, 0x1b000, v3
	global_load_dword v137, v12, s[0:1] offset:-4096
	global_load_dword v138, v12, s[0:1] offset:-3968
	global_load_dword v139, v12, s[0:1] offset:0
	global_load_dword v140, v12, s[0:1] offset:128
	s_waitcnt vmcnt(0)
	v_add_f32_e32 v13, v32, v13
	global_store_dword v5, v13, s[0:1] offset:-4096
	v_add_f32_e32 v14, v16, v14
	global_store_dword v5, v14, s[0:1] offset:-3968
	v_add_f32_e32 v15, v33, v15
	global_store_dword v5, v15, s[0:1] offset:0
	v_add_f32_e32 v112, v17, v112
	global_store_dword v5, v112, s[0:1] offset:128
	v_add_f32_e32 v113, v34, v113
	global_store_dword v6, v113, s[0:1] offset:-4096
	v_add_f32_e32 v114, v18, v114
	global_store_dword v6, v114, s[0:1] offset:-3968
	v_add_f32_e32 v115, v35, v115
	global_store_dword v6, v115, s[0:1] offset:0
	v_add_f32_e32 v116, v19, v116
	global_store_dword v6, v116, s[0:1] offset:128
	v_add_f32_e32 v117, v36, v117
	global_store_dword v7, v117, s[0:1] offset:-4096
	v_add_f32_e32 v118, v20, v118
	global_store_dword v7, v118, s[0:1] offset:-3968
	v_add_f32_e32 v119, v37, v119
	global_store_dword v7, v119, s[0:1] offset:0
	v_add_f32_e32 v120, v21, v120
	global_store_dword v7, v120, s[0:1] offset:128
	v_add_f32_e32 v121, v38, v121
	global_store_dword v8, v121, s[0:1] offset:-4096
	v_add_f32_e32 v122, v22, v122
	global_store_dword v8, v122, s[0:1] offset:-3968
	v_add_f32_e32 v123, v39, v123
	global_store_dword v8, v123, s[0:1] offset:0
	v_add_f32_e32 v124, v23, v124
	global_store_dword v8, v124, s[0:1] offset:128
	v_add_f32_e32 v125, v40, v125
	global_store_dword v9, v125, s[0:1] offset:-4096
	v_add_f32_e32 v126, v24, v126
	global_store_dword v9, v126, s[0:1] offset:-3968
	v_add_f32_e32 v127, v41, v127
	global_store_dword v9, v127, s[0:1] offset:0
	v_add_f32_e32 v128, v25, v128
	global_store_dword v9, v128, s[0:1] offset:128
	v_add_f32_e32 v129, v42, v129
	global_store_dword v10, v129, s[0:1] offset:-4096
	v_add_f32_e32 v130, v26, v130
	global_store_dword v10, v130, s[0:1] offset:-3968
	v_add_f32_e32 v131, v43, v131
	global_store_dword v10, v131, s[0:1] offset:0
	v_add_f32_e32 v132, v27, v132
	global_store_dword v10, v132, s[0:1] offset:128
	v_add_f32_e32 v133, v44, v133
	global_store_dword v11, v133, s[0:1] offset:-4096
	v_add_f32_e32 v134, v28, v134
	global_store_dword v11, v134, s[0:1] offset:-3968
	v_add_f32_e32 v135, v45, v135
	global_store_dword v11, v135, s[0:1] offset:0
	v_add_f32_e32 v136, v29, v136
	global_store_dword v11, v136, s[0:1] offset:128
	v_add_f32_e32 v137, v46, v137
	global_store_dword v12, v137, s[0:1] offset:-4096
	v_add_f32_e32 v138, v30, v138
	global_store_dword v12, v138, s[0:1] offset:-3968
	v_add_f32_e32 v139, v47, v139
	global_store_dword v12, v139, s[0:1] offset:0
	v_add_f32_e32 v140, v31, v140
	global_store_dword v12, v140, s[0:1] offset:128
	s_waitcnt vmcnt(0)
	s_branch .LBB0_405

; DI int otid() { int t = threadIdx.x; asm volatile("" : "+v"(t)); return t; }
; DI int crow(int i, int h) { return (i & 3) + 8 * (i >> 2) + 4 * h; }
;     DI void operator()(int unit, const f32x16 (&acc)[MT][NT]) const {
;         const int lane = otid() & 63, r = lane & 31, h = lane >> 5;
; #pragma unroll
;         for (int mi = 0; mi < MT; ++mi)
; #pragma unroll
;             for (int nj = 0; nj < NT; ++nj)
; #pragma unroll
;                 for (int i = 0; i < 16; ++i) { float* q = x + ((mi * 32 + crow(i, h) + (mi == 2 ? d2 : 0)) * DM + unit * UW + nj * 32 + r); *q = *q + acc[mi][nj][i]; if (i == 15) __builtin_amdgcn_sched_barrier(0); }
.LBB0_455:
	s_and_saveexec_b64 s[28:29], s[4:5]
	s_cbranch_execz .LBB0_444
	s_waitcnt vmcnt(0)
	v_and_b32_e32 v2, 31, v176
	v_lshlrev_b32_e32 v3, 9, v176
	v_and_b32_e32 v3, 0x4000, v3
	v_lshl_or_b32 v4, v2, 2, v3
	v_lshl_add_u32 v4, v238, 8, v4
	v_add_u32_e32 v5, 0x1000, v4
	global_load_dword v13, v5, s[0:1] offset:-4096
	global_load_dword v14, v5, s[0:1] offset:-3968
	global_load_dword v15, v5, s[0:1] offset:0
	global_load_dword v112, v5, s[0:1] offset:128
	v_add_u32_e32 v6, 0x3000, v4
	global_load_dword v113, v6, s[0:1] offset:-4096
	global_load_dword v114, v6, s[0:1] offset:-3968
	global_load_dword v115, v6, s[0:1] offset:0
	global_load_dword v116, v6, s[0:1] offset:128
	v_add_u32_e32 v7, 0x9000, v4
	global_load_dword v117, v7, s[0:1] offset:-4096
	global_load_dword v118, v7, s[0:1] offset:-3968
	global_load_dword v119, v7, s[0:1] offset:0
	global_load_dword v120, v7, s[0:1] offset:128
	v_add_u32_e32 v8, 0xb000, v4
	global_load_dword v121, v8, s[0:1] offset:-4096
	global_load_dword v122, v8, s[0:1] offset:-3968
	global_load_dword v123, v8, s[0:1] offset:0
	global_load_dword v124, v8, s[0:1] offset:128
	v_add_u32_e32 v9, 0x11000, v4
	global_load_dword v125, v9, s[0:1] offset:-4096
	global_load_dword v126, v9, s[0:1] offset:-3968
	global_load_dword v127, v9, s[0:1] offset:0
	global_load_dword v128, v9, s[0:1] offset:128
	v_add_u32_e32 v10, 0x13000, v4
	global_load_dword v129, v10, s[0:1] offset:-4096
	global_load_dword v130, v10, s[0:1] offset:-3968
	global_load_dword v131, v10, s[0:1] offset:0
	global_load_dword v132, v10, s[0:1] offset:128
	v_add_u32_e32 v11, 0x19000, v4
	global_load_dword v133, v11, s[0:1] offset:-4096
	global_load_dword v134, v11, s[0:1] offset:-3968
	global_load_dword v135, v11, s[0:1] offset:0
	global_load_dword v136, v11, s[0:1] offset:128
	v_add_u32_e32 v12, 0x1b000, v4
	global_load_dword v137, v12, s[0:1] offset:-4096
	global_load_dword v138, v12, s[0:1] offset:-3968
	global_load_dword v139, v12, s[0:1] offset:0
	global_load_dword v140, v12, s[0:1] offset:128
	s_waitcnt vmcnt(0)
	v_add_f32_e32 v13, v96, v13
	global_store_dword v5, v13, s[0:1] offset:-4096
	v_add_f32_e32 v14, v80, v14
	global_store_dword v5, v14, s[0:1] offset:-3968
	v_add_f32_e32 v15, v97, v15
	global_store_dword v5, v15, s[0:1] offset:0
	v_add_f32_e32 v112, v81, v112
	global_store_dword v5, v112, s[0:1] offset:128
	v_add_f32_e32 v113, v98, v113
	global_store_dword v6, v113, s[0:1] offset:-4096
	v_add_f32_e32 v114, v82, v114
	global_store_dword v6, v114, s[0:1] offset:-3968
	v_add_f32_e32 v115, v99, v115
	global_store_dword v6, v115, s[0:1] offset:0
	v_add_f32_e32 v116, v83, v116
	global_store_dword v6, v116, s[0:1] offset:128
	v_add_f32_e32 v117, v100, v117
	global_store_dword v7, v117, s[0:1] offset:-4096
	v_add_f32_e32 v118, v84, v118
	global_store_dword v7, v118, s[0:1] offset:-3968
	v_add_f32_e32 v119, v101, v119
	global_store_dword v7, v119, s[0:1] offset:0
	v_add_f32_e32 v120, v85, v120
	global_store_dword v7, v120, s[0:1] offset:128
	v_add_f32_e32 v121, v102, v121
	global_store_dword v8, v121, s[0:1] offset:-4096
	v_add_f32_e32 v122, v86, v122
	global_store_dword v8, v122, s[0:1] offset:-3968
	v_add_f32_e32 v123, v103, v123
	global_store_dword v8, v123, s[0:1] offset:0
	v_add_f32_e32 v124, v87, v124
	global_store_dword v8, v124, s[0:1] offset:128
	v_add_f32_e32 v125, v104, v125
	global_store_dword v9, v125, s[0:1] offset:-4096
	v_add_f32_e32 v126, v88, v126
	global_store_dword v9, v126, s[0:1] offset:-3968
	v_add_f32_e32 v127, v105, v127
	global_store_dword v9, v127, s[0:1] offset:0
	v_add_f32_e32 v128, v89, v128
	global_store_dword v9, v128, s[0:1] offset:128
	v_add_f32_e32 v129, v106, v129
	global_store_dword v10, v129, s[0:1] offset:-4096
	v_add_f32_e32 v130, v90, v130
	global_store_dword v10, v130, s[0:1] offset:-3968
	v_add_f32_e32 v131, v107, v131
	global_store_dword v10, v131, s[0:1] offset:0
	v_add_f32_e32 v132, v91, v132
	global_store_dword v10, v132, s[0:1] offset:128
	v_add_f32_e32 v133, v108, v133
	global_store_dword v11, v133, s[0:1] offset:-4096
	v_add_f32_e32 v134, v92, v134
	global_store_dword v11, v134, s[0:1] offset:-3968
	v_add_f32_e32 v135, v109, v135
	global_store_dword v11, v135, s[0:1] offset:0
	v_add_f32_e32 v136, v93, v136
	global_store_dword v11, v136, s[0:1] offset:128
	v_add_f32_e32 v137, v110, v137
	global_store_dword v12, v137, s[0:1] offset:-4096
	v_add_f32_e32 v138, v94, v138
	global_store_dword v12, v138, s[0:1] offset:-3968
	v_add_f32_e32 v139, v111, v139
	global_store_dword v12, v139, s[0:1] offset:0
	v_add_f32_e32 v140, v95, v140
	global_store_dword v12, v140, s[0:1] offset:128
	v_add_u32_e32 v5, 0x21000, v4
	global_load_dword v13, v5, s[0:1] offset:-4096
	global_load_dword v14, v5, s[0:1] offset:-3968
	global_load_dword v15, v5, s[0:1] offset:0
	global_load_dword v112, v5, s[0:1] offset:128
	v_add_u32_e32 v6, 0x23000, v4
	global_load_dword v113, v6, s[0:1] offset:-4096
	global_load_dword v114, v6, s[0:1] offset:-3968
	global_load_dword v115, v6, s[0:1] offset:0
	global_load_dword v116, v6, s[0:1] offset:128
	v_add_u32_e32 v7, 0x29000, v4
	global_load_dword v117, v7, s[0:1] offset:-4096
	global_load_dword v118, v7, s[0:1] offset:-3968
	global_load_dword v119, v7, s[0:1] offset:0
	global_load_dword v120, v7, s[0:1] offset:128
	v_add_u32_e32 v8, 0x2b000, v4
	global_load_dword v121, v8, s[0:1] offset:-4096
	global_load_dword v122, v8, s[0:1] offset:-3968
	global_load_dword v123, v8, s[0:1] offset:0
	global_load_dword v124, v8, s[0:1] offset:128
	v_add_u32_e32 v9, 0x31000, v4
	global_load_dword v125, v9, s[0:1] offset:-4096
	global_load_dword v126, v9, s[0:1] offset:-3968
	global_load_dword v127, v9, s[0:1] offset:0
	global_load_dword v128, v9, s[0:1] offset:128
	v_add_u32_e32 v10, 0x33000, v4
	global_load_dword v129, v10, s[0:1] offset:-4096
	global_load_dword v130, v10, s[0:1] offset:-3968
	global_load_dword v131, v10, s[0:1] offset:0
	global_load_dword v132, v10, s[0:1] offset:128
	v_add_u32_e32 v11, 0x39000, v4
	global_load_dword v133, v11, s[0:1] offset:-4096
	global_load_dword v134, v11, s[0:1] offset:-3968
	global_load_dword v135, v11, s[0:1] offset:0
	global_load_dword v136, v11, s[0:1] offset:128
	v_add_u32_e32 v12, 0x3b000, v4
	global_load_dword v137, v12, s[0:1] offset:-4096
	global_load_dword v138, v12, s[0:1] offset:-3968
	global_load_dword v139, v12, s[0:1] offset:0
	global_load_dword v140, v12, s[0:1] offset:128
	s_waitcnt vmcnt(0)
; DI int otid() { int t = threadIdx.x; asm volatile("" : "+v"(t)); return t; }
; DI int crow(int i, int h) { return (i & 3) + 8 * (i >> 2) + 4 * h; }
;     DI void operator()(int unit, const f32x16 (&acc)[MT][NT]) const {
;         const int lane = otid() & 63, r = lane & 31, h = lane >> 5;
; #pragma unroll
;         for (int mi = 0; mi < MT; ++mi)
; #pragma unroll
;             for (int nj = 0; nj < NT; ++nj)
; #pragma unroll
;                 for (int i = 0; i < 16; ++i) { float* q = x + ((mi * 32 + crow(i, h) + (mi == 2 ? d2 : 0)) * DM + unit * UW + nj * 32 + r); *q = *q + acc[mi][nj][i]; if (i == 15) __builtin_amdgcn_sched_barrier(0); }
	v_add_f32_e32 v13, v64, v13
	global_store_dword v5, v13, s[0:1] offset:-4096
	v_add_f32_e32 v14, v48, v14
	global_store_dword v5, v14, s[0:1] offset:-3968
	v_add_f32_e32 v15, v65, v15
	global_store_dword v5, v15, s[0:1] offset:0
	v_add_f32_e32 v112, v49, v112
	global_store_dword v5, v112, s[0:1] offset:128
	v_add_f32_e32 v113, v66, v113
	global_store_dword v6, v113, s[0:1] offset:-4096
	v_add_f32_e32 v114, v50, v114
	global_store_dword v6, v114, s[0:1] offset:-3968
	v_add_f32_e32 v115, v67, v115
	global_store_dword v6, v115, s[0:1] offset:0
	v_add_f32_e32 v116, v51, v116
	global_store_dword v6, v116, s[0:1] offset:128
	v_add_f32_e32 v117, v68, v117
	global_store_dword v7, v117, s[0:1] offset:-4096
	v_add_f32_e32 v118, v52, v118
	global_store_dword v7, v118, s[0:1] offset:-3968
	v_add_f32_e32 v119, v69, v119
	global_store_dword v7, v119, s[0:1] offset:0
	v_add_f32_e32 v120, v53, v120
	global_store_dword v7, v120, s[0:1] offset:128
	v_add_f32_e32 v121, v70, v121
	global_store_dword v8, v121, s[0:1] offset:-4096
	v_add_f32_e32 v122, v54, v122
	global_store_dword v8, v122, s[0:1] offset:-3968
	v_add_f32_e32 v123, v71, v123
	global_store_dword v8, v123, s[0:1] offset:0
	v_add_f32_e32 v124, v55, v124
	global_store_dword v8, v124, s[0:1] offset:128
	v_add_f32_e32 v125, v72, v125
	global_store_dword v9, v125, s[0:1] offset:-4096
	v_add_f32_e32 v126, v56, v126
	global_store_dword v9, v126, s[0:1] offset:-3968
	v_add_f32_e32 v127, v73, v127
	global_store_dword v9, v127, s[0:1] offset:0
	v_add_f32_e32 v128, v57, v128
	global_store_dword v9, v128, s[0:1] offset:128
	v_add_f32_e32 v129, v74, v129
	global_store_dword v10, v129, s[0:1] offset:-4096
	v_add_f32_e32 v130, v58, v130
	global_store_dword v10, v130, s[0:1] offset:-3968
	v_add_f32_e32 v131, v75, v131
	global_store_dword v10, v131, s[0:1] offset:0
	v_add_f32_e32 v132, v59, v132
	global_store_dword v10, v132, s[0:1] offset:128
	v_add_f32_e32 v133, v76, v133
	global_store_dword v11, v133, s[0:1] offset:-4096
	v_add_f32_e32 v134, v60, v134
	global_store_dword v11, v134, s[0:1] offset:-3968
	v_add_f32_e32 v135, v77, v135
	global_store_dword v11, v135, s[0:1] offset:0
	v_add_f32_e32 v136, v61, v136
	global_store_dword v11, v136, s[0:1] offset:128
	v_add_f32_e32 v137, v78, v137
	global_store_dword v12, v137, s[0:1] offset:-4096
	v_add_f32_e32 v138, v62, v138
	global_store_dword v12, v138, s[0:1] offset:-3968
	v_add_f32_e32 v139, v79, v139
	global_store_dword v12, v139, s[0:1] offset:0
	v_add_f32_e32 v140, v63, v140
	global_store_dword v12, v140, s[0:1] offset:128
	v_lshl_add_u32 v3, s59, 12, v4
	v_add_u32_e32 v5, 0x1000, v3
	global_load_dword v13, v5, s[0:1] offset:-4096
	global_load_dword v14, v5, s[0:1] offset:-3968
	global_load_dword v15, v5, s[0:1] offset:0
	global_load_dword v112, v5, s[0:1] offset:128
	v_add_u32_e32 v6, 0x3000, v3
	global_load_dword v113, v6, s[0:1] offset:-4096
	global_load_dword v114, v6, s[0:1] offset:-3968
	global_load_dword v115, v6, s[0:1] offset:0
	global_load_dword v116, v6, s[0:1] offset:128
	v_add_u32_e32 v7, 0x9000, v3
	global_load_dword v117, v7, s[0:1] offset:-4096
	global_load_dword v118, v7, s[0:1] offset:-3968
	global_load_dword v119, v7, s[0:1] offset:0
	global_load_dword v120, v7, s[0:1] offset:128
	v_add_u32_e32 v8, 0xb000, v3
	global_load_dword v121, v8, s[0:1] offset:-4096
	global_load_dword v122, v8, s[0:1] offset:-3968
	global_load_dword v123, v8, s[0:1] offset:0
	global_load_dword v124, v8, s[0:1] offset:128
	v_add_u32_e32 v9, 0x11000, v3
	global_load_dword v125, v9, s[0:1] offset:-4096
	global_load_dword v126, v9, s[0:1] offset:-3968
	global_load_dword v127, v9, s[0:1] offset:0
	global_load_dword v128, v9, s[0:1] offset:128
	v_add_u32_e32 v10, 0x13000, v3
	global_load_dword v129, v10, s[0:1] offset:-4096
	global_load_dword v130, v10, s[0:1] offset:-3968
	global_load_dword v131, v10, s[0:1] offset:0
	global_load_dword v132, v10, s[0:1] offset:128
	v_add_u32_e32 v11, 0x19000, v3
	global_load_dword v133, v11, s[0:1] offset:-4096
	global_load_dword v134, v11, s[0:1] offset:-3968
	global_load_dword v135, v11, s[0:1] offset:0
	global_load_dword v136, v11, s[0:1] offset:128
	v_add_u32_e32 v12, 0x1b000, v3
	global_load_dword v137, v12, s[0:1] offset:-4096
	global_load_dword v138, v12, s[0:1] offset:-3968
	global_load_dword v139, v12, s[0:1] offset:0
	global_load_dword v140, v12, s[0:1] offset:128
	s_waitcnt vmcnt(0)
	v_add_f32_e32 v13, v32, v13
	global_store_dword v5, v13, s[0:1] offset:-4096
	v_add_f32_e32 v14, v16, v14
	global_store_dword v5, v14, s[0:1] offset:-3968
	v_add_f32_e32 v15, v33, v15
	global_store_dword v5, v15, s[0:1] offset:0
	v_add_f32_e32 v112, v17, v112
	global_store_dword v5, v112, s[0:1] offset:128
	v_add_f32_e32 v113, v34, v113
	global_store_dword v6, v113, s[0:1] offset:-4096
	v_add_f32_e32 v114, v18, v114
	global_store_dword v6, v114, s[0:1] offset:-3968
	v_add_f32_e32 v115, v35, v115
	global_store_dword v6, v115, s[0:1] offset:0
	v_add_f32_e32 v116, v19, v116
	global_store_dword v6, v116, s[0:1] offset:128
	v_add_f32_e32 v117, v36, v117
	global_store_dword v7, v117, s[0:1] offset:-4096
	v_add_f32_e32 v118, v20, v118
	global_store_dword v7, v118, s[0:1] offset:-3968
	v_add_f32_e32 v119, v37, v119
	global_store_dword v7, v119, s[0:1] offset:0
	v_add_f32_e32 v120, v21, v120
	global_store_dword v7, v120, s[0:1] offset:128
	v_add_f32_e32 v121, v38, v121
	global_store_dword v8, v121, s[0:1] offset:-4096
	v_add_f32_e32 v122, v22, v122
	global_store_dword v8, v122, s[0:1] offset:-3968
	v_add_f32_e32 v123, v39, v123
	global_store_dword v8, v123, s[0:1] offset:0
	v_add_f32_e32 v124, v23, v124
	global_store_dword v8, v124, s[0:1] offset:128
	v_add_f32_e32 v125, v40, v125
	global_store_dword v9, v125, s[0:1] offset:-4096
	v_add_f32_e32 v126, v24, v126
	global_store_dword v9, v126, s[0:1] offset:-3968
	v_add_f32_e32 v127, v41, v127
	global_store_dword v9, v127, s[0:1] offset:0
	v_add_f32_e32 v128, v25, v128
	global_store_dword v9, v128, s[0:1] offset:128
	v_add_f32_e32 v129, v42, v129
	global_store_dword v10, v129, s[0:1] offset:-4096
	v_add_f32_e32 v130, v26, v130
	global_store_dword v10, v130, s[0:1] offset:-3968
	v_add_f32_e32 v131, v43, v131
	global_store_dword v10, v131, s[0:1] offset:0
	v_add_f32_e32 v132, v27, v132
	global_store_dword v10, v132, s[0:1] offset:128
	v_add_f32_e32 v133, v44, v133
	global_store_dword v11, v133, s[0:1] offset:-4096
	v_add_f32_e32 v134, v28, v134
	global_store_dword v11, v134, s[0:1] offset:-3968
	v_add_f32_e32 v135, v45, v135
	global_store_dword v11, v135, s[0:1] offset:0
	v_add_f32_e32 v136, v29, v136
	global_store_dword v11, v136, s[0:1] offset:128
	v_add_f32_e32 v137, v46, v137
	global_store_dword v12, v137, s[0:1] offset:-4096
	v_add_f32_e32 v138, v30, v138
	global_store_dword v12, v138, s[0:1] offset:-3968
	v_add_f32_e32 v139, v47, v139
	global_store_dword v12, v139, s[0:1] offset:0
	v_add_f32_e32 v140, v31, v140
	global_store_dword v12, v140, s[0:1] offset:128
	s_waitcnt vmcnt(0)
	s_branch .LBB0_444
; DI int otid() { int t = threadIdx.x; asm volatile("" : "+v"(t)); return t; }
; template <int MODE, int MT> DI void norm_rows(const float* src, const float* src2, float* x, int d2, bf16_t* xb, const float* __restrict__ g) {
;     const int tid_ = otid(), wave = tid_ >> 6, lane = tid_ & 63;
;     for (int rb = 0; rb < MT; ++rb) {
;         f32x4 v[4][4]; float ss[4];
; #pragma unroll
;         for (int q = 0; q < 4; ++q) {
;             const int row = wave * (MT * 4) + rb * 4 + q, grow = row + (row >= 64 ? d2 : 0);
;             const float* s = x + (size_t)grow * DM;
;             if (MODE == 0) { s = src + (size_t)row * DM; if (MT == 3 && row >= 64) s = src2 + (size_t)(row - 64) * DM; }
;             ss[q] = 0.f;
; #pragma unroll
;             for (int i = 0; i < 4; ++i) { v[q][i] = *(const f32x4*)(s + i * 256 + lane * 4); ss[q] += v[q][i][0] * v[q][i][0] + v[q][i][1] * v[q][i][1] + v[q][i][2] * v[q][i][2] + v[q][i][3] * v[q][i][3]; }
;         }
; #pragma unroll
;         for (int o = 32; o >= 1; o >>= 1)
; #pragma unroll
;             for (int q = 0; q < 4; ++q) ss[q] += __shfl_xor(ss[q], o);
; #pragma unroll
;         for (int q = 0; q < 4; ++q) {
;             const int row = wave * (MT * 4) + rb * 4 + q, grow = row + (row >= 64 ? d2 : 0);
;             const float rstd = rsqrtf(ss[q] * (1.f / DM) + 1e-6f);
.Ltramp_555:
	s_branch .LBB0_555
.LBB0_457:
	v_mov_b32_e32 v2, v176
	s_waitcnt lgkmcnt(0)
	s_barrier
	v_mov_b32_e32 v3, v1
	v_ashrrev_i32_e32 v94, 6, v2
	v_lshlrev_b32_e32 v2, 2, v2
	v_and_b32_e32 v4, 0xfc, v2
	v_lshlrev_b32_e32 v2, 2, v4
	v_lshl_add_u64 v[68:69], s[0:1], 0, v[2:3]
	v_lshlrev_b32_e32 v2, 1, v4
	v_cmp_lt_i32_e32 vcc, 5, v94
	v_mov_b32_e32 v95, s24
	v_mul_lo_u32 v0, v94, 12
	v_lshl_add_u64 v[66:67], s[34:35], 0, v[2:3]
	v_cndmask_b32_e32 v2, 0, v95, vcc
	v_add_u32_e32 v92, v2, v0
	v_ashrrev_i32_e32 v93, 31, v92
	v_lshlrev_b64 v[2:3], 12, v[92:93]
	v_lshl_add_u64 v[2:3], v[68:69], 0, v[2:3]
	global_load_dwordx4 v[18:21], v[2:3], off
	global_load_dwordx4 v[10:13], v[2:3], off offset:1024
	global_load_dwordx4 v[38:41], v[2:3], off offset:2048
	global_load_dwordx4 v[30:33], v[2:3], off offset:3072
	v_add_u32_e32 v74, 1, v92
	v_ashrrev_i32_e32 v75, 31, v74
	s_mov_b32 s0, 0x358637bd
	s_mov_b32 s4, 0x3a800000
	s_mov_b32 s3, 0x800000
	v_lshlrev_b64 v[92:93], 11, v[92:93]
	v_lshl_add_u64 v[92:93], v[66:67], 0, v[92:93]
	s_mov_b32 s2, 0
	s_mov_b32 s31, 0
	s_waitcnt vmcnt(3)
	v_mov_b32_e32 v6, v19
	s_waitcnt vmcnt(2)
	v_mov_b32_e32 v7, v11
	v_mov_b32_e32 v4, v18
	v_mov_b32_e32 v5, v10
	v_pk_mul_f32 v[6:7], v[6:7], v[6:7]
	s_waitcnt vmcnt(1)
	v_mov_b32_e32 v2, v38
	v_pk_fma_f32 v[4:5], v[4:5], v[4:5], v[6:7]
	v_mov_b32_e32 v6, v20
	v_mov_b32_e32 v7, v12
	v_pk_fma_f32 v[4:5], v[6:7], v[6:7], v[4:5]
	v_mov_b32_e32 v6, v21
	v_mov_b32_e32 v7, v13
	v_pk_fma_f32 v[70:71], v[6:7], v[6:7], v[4:5]
	v_mov_b32_e32 v4, v39
	s_waitcnt vmcnt(0)
	v_mov_b32_e32 v5, v31
	v_mov_b32_e32 v3, v30
	v_pk_mul_f32 v[4:5], v[4:5], v[4:5]
	s_nop 0
	v_pk_fma_f32 v[2:3], v[2:3], v[2:3], v[4:5]
	v_mov_b32_e32 v4, v40
	v_mov_b32_e32 v5, v32
	v_pk_fma_f32 v[2:3], v[4:5], v[4:5], v[2:3]
	v_mov_b32_e32 v4, v41
	v_mov_b32_e32 v5, v33
	v_pk_fma_f32 v[82:83], v[4:5], v[4:5], v[2:3]
	v_lshlrev_b64 v[2:3], 12, v[74:75]
	v_lshl_add_u64 v[2:3], v[68:69], 0, v[2:3]
	global_load_dwordx4 v[50:53], v[2:3], off
	global_load_dwordx4 v[46:49], v[2:3], off offset:1024
	global_load_dwordx4 v[62:65], v[2:3], off offset:2048
	global_load_dwordx4 v[58:61], v[2:3], off offset:3072
	s_waitcnt vmcnt(3)
	v_mov_b32_e32 v6, v51
	s_waitcnt vmcnt(2)
	v_mov_b32_e32 v7, v47
	v_mov_b32_e32 v4, v50
	v_mov_b32_e32 v5, v46
	v_pk_mul_f32 v[6:7], v[6:7], v[6:7]
	s_waitcnt vmcnt(1)
	v_mov_b32_e32 v2, v62
	v_pk_fma_f32 v[4:5], v[4:5], v[4:5], v[6:7]
	v_mov_b32_e32 v6, v52
	v_mov_b32_e32 v7, v48
	v_pk_fma_f32 v[4:5], v[6:7], v[6:7], v[4:5]
	v_mov_b32_e32 v6, v53
	v_mov_b32_e32 v7, v49
	v_pk_fma_f32 v[86:87], v[6:7], v[6:7], v[4:5]
	v_mov_b32_e32 v4, v63
	s_waitcnt vmcnt(0)
	v_mov_b32_e32 v5, v59
	v_mov_b32_e32 v3, v58
	v_pk_mul_f32 v[4:5], v[4:5], v[4:5]
	s_nop 0
	v_pk_fma_f32 v[2:3], v[2:3], v[2:3], v[4:5]
	v_mov_b32_e32 v4, v64
	v_mov_b32_e32 v5, v60
	v_pk_fma_f32 v[2:3], v[4:5], v[4:5], v[2:3]
	v_mov_b32_e32 v4, v65
	v_mov_b32_e32 v5, v61
	v_pk_fma_f32 v[90:91], v[4:5], v[4:5], v[2:3]
	v_or_b32_e32 v2, 2, v0
	v_cmp_lt_i32_e32 vcc, 63, v2
	s_nop 1
	v_cndmask_b32_e32 v3, 0, v95, vcc
	v_add_u32_e32 v80, v3, v2
	v_ashrrev_i32_e32 v81, 31, v80
	v_lshlrev_b64 v[2:3], 12, v[80:81]
	v_lshl_add_u64 v[14:15], v[68:69], 0, v[2:3]
	global_load_dwordx4 v[6:9], v[14:15], off
	global_load_dwordx4 v[2:5], v[14:15], off offset:1024
	s_waitcnt vmcnt(1)
	v_mov_b32_e32 v22, v7
	s_waitcnt vmcnt(0)
	v_mov_b32_e32 v23, v3
	v_mov_b32_e32 v16, v6
	v_mov_b32_e32 v17, v2
	v_pk_mul_f32 v[22:23], v[22:23], v[22:23]
	s_nop 0
	v_pk_fma_f32 v[16:17], v[16:17], v[16:17], v[22:23]
	v_mov_b32_e32 v22, v8
	v_mov_b32_e32 v23, v4
	v_pk_fma_f32 v[16:17], v[22:23], v[22:23], v[16:17]
	v_mov_b32_e32 v22, v9
	v_mov_b32_e32 v23, v5
	v_pk_fma_f32 v[76:77], v[22:23], v[22:23], v[16:17]
	global_load_dwordx4 v[22:25], v[14:15], off offset:2048
	s_nop 0
	global_load_dwordx4 v[14:17], v[14:15], off offset:3072
	s_waitcnt vmcnt(1)
	v_mov_b32_e32 v28, v23
	s_waitcnt vmcnt(0)
	v_mov_b32_e32 v29, v15
	v_mov_b32_e32 v26, v22
	v_mov_b32_e32 v27, v14
	v_pk_mul_f32 v[28:29], v[28:29], v[28:29]
	s_nop 0
	v_pk_fma_f32 v[26:27], v[26:27], v[26:27], v[28:29]
	v_mov_b32_e32 v28, v24
	v_mov_b32_e32 v29, v16
	v_pk_fma_f32 v[26:27], v[28:29], v[28:29], v[26:27]
	v_mov_b32_e32 v28, v25
	v_mov_b32_e32 v29, v17
	v_pk_fma_f32 v[78:79], v[28:29], v[28:29], v[26:27]
	v_or_b32_e32 v26, 3, v0
	v_cmp_lt_i32_e32 vcc, 63, v26
	s_nop 1
	v_cndmask_b32_e32 v27, 0, v95, vcc
	v_add_u32_e32 v72, v27, v26
	v_ashrrev_i32_e32 v73, 31, v72
	v_lshlrev_b64 v[26:27], 12, v[72:73]
	v_lshl_add_u64 v[42:43], v[68:69], 0, v[26:27]
	global_load_dwordx4 v[34:37], v[42:43], off
	global_load_dwordx4 v[26:29], v[42:43], off offset:1024
	s_waitcnt vmcnt(1)
	v_mov_b32_e32 v54, v35
	s_waitcnt vmcnt(0)
	v_mov_b32_e32 v55, v27
	v_mov_b32_e32 v44, v34
	v_mov_b32_e32 v45, v26
	v_pk_mul_f32 v[54:55], v[54:55], v[54:55]
	s_nop 0
	v_pk_fma_f32 v[44:45], v[44:45], v[44:45], v[54:55]
	v_mov_b32_e32 v54, v36
	v_mov_b32_e32 v55, v28
	v_pk_fma_f32 v[44:45], v[54:55], v[54:55], v[44:45]
	v_mov_b32_e32 v54, v37
	v_mov_b32_e32 v55, v29
	v_pk_fma_f32 v[84:85], v[54:55], v[54:55], v[44:45]
	global_load_dwordx4 v[54:57], v[42:43], off offset:2048
	s_nop 0
	global_load_dwordx4 v[42:45], v[42:43], off offset:3072
	s_waitcnt vmcnt(1)
	v_mov_b32_e32 v96, v55
	s_waitcnt vmcnt(0)
; DI unsigned pk2(float lo, float hi) { f32x2 v = {lo, hi}; bf2_t b = __builtin_convertvector(v, bf2_t); return __builtin_bit_cast(unsigned, b); }
; template <int MODE, int MT> DI void norm_rows(const float* src, const float* src2, float* x, int d2, bf16_t* xb, const float* __restrict__ g) {
;     ...
;             for (int i = 0; i < 4; ++i) { v[q][i] = *(const f32x4*)(s + i * 256 + lane * 4); ss[q] += v[q][i][0] * v[q][i][0] + v[q][i][1] * v[q][i][1] + v[q][i][2] * v[q][i][2] + v[q][i][3] * v[q][i][3]; }
;         }
; #pragma unroll
;         for (int o = 32; o >= 1; o >>= 1)
; #pragma unroll
;             for (int q = 0; q < 4; ++q) ss[q] += __shfl_xor(ss[q], o);
; #pragma unroll
;         for (int q = 0; q < 4; ++q) {
;             const int row = wave * (MT * 4) + rb * 4 + q, grow = row + (row >= 64 ? d2 : 0);
;             const float rstd = rsqrtf(ss[q] * (1.f / DM) + 1e-6f);
; #pragma unroll
;             for (int i = 0; i < 4; ++i) {
;                 if (MODE == 0) *(f32x4*)(x + (size_t)grow * DM + i * 256 + lane * 4) = v[q][i];
;                 if (MODE == 2) { f32x4 gg = *(const f32x4*)(g + i * 256 + lane * 4); *(f32x4*)(x + (size_t)grow * DM + i * 256 + lane * 4) = v[q][i] * rstd * gg; }
;                 else { u32x2 o = {pk2(v[q][i][0] * rstd, v[q][i][1] * rstd), pk2(v[q][i][2] * rstd, v[q][i][3] * rstd)}; *(u32x2*)(xb + (size_t)grow * DM + i * 256 + lane * 4) = o; }
;             }
;         }
	v_mov_b32_e32 v97, v43
	v_mov_b32_e32 v88, v54
	v_mov_b32_e32 v89, v42
	v_pk_mul_f32 v[96:97], v[96:97], v[96:97]
	s_nop 0
	v_pk_fma_f32 v[88:89], v[88:89], v[88:89], v[96:97]
	v_mov_b32_e32 v96, v56
	v_mov_b32_e32 v97, v44
	v_pk_fma_f32 v[88:89], v[96:97], v[96:97], v[88:89]
	v_mov_b32_e32 v96, v57
	v_mov_b32_e32 v97, v45
	v_pk_fma_f32 v[88:89], v[96:97], v[96:97], v[88:89]
	v_mov_b32_e32 v96, v86
	v_mov_b32_e32 v97, v70
	v_mov_b32_e32 v70, v87
	v_pk_add_f32 v[70:71], v[96:97], v[70:71]
	v_mov_b32_e32 v86, v90
	v_mov_b32_e32 v87, v82
	v_pk_add_f32 v[70:71], v[70:71], v[86:87]
	v_mov_b32_e32 v82, v91
	v_pk_add_f32 v[70:71], v[70:71], v[82:83]
	ds_bpermute_b32 v83, v224, v71
	ds_bpermute_b32 v82, v224, v70
	s_waitcnt lgkmcnt(0)
	v_pk_add_f32 v[70:71], v[70:71], v[82:83]
	ds_bpermute_b32 v83, v228, v71
	ds_bpermute_b32 v82, v228, v70
	s_waitcnt lgkmcnt(0)
	v_pk_add_f32 v[70:71], v[70:71], v[82:83]
	ds_bpermute_b32 v83, v227, v71
	ds_bpermute_b32 v82, v227, v70
	s_waitcnt lgkmcnt(0)
	v_pk_add_f32 v[70:71], v[70:71], v[82:83]
	ds_bpermute_b32 v83, v226, v71
	ds_bpermute_b32 v82, v226, v70
	s_waitcnt lgkmcnt(0)
	v_pk_add_f32 v[70:71], v[70:71], v[82:83]
	ds_bpermute_b32 v83, v225, v71
	ds_bpermute_b32 v82, v225, v70
	s_waitcnt lgkmcnt(0)
	v_pk_add_f32 v[70:71], v[70:71], v[82:83]
	ds_bpermute_b32 v83, v223, v71
	ds_bpermute_b32 v82, v223, v70
	s_waitcnt lgkmcnt(0)
	v_pk_add_f32 v[82:83], v[70:71], v[82:83]
	v_mov_b64_e32 v[70:71], s[0:1]
	v_pk_fma_f32 v[82:83], v[82:83], s[4:5], v[70:71] op_sel_hi:[1,0,0]
	s_nop 0
	v_mul_f32_e32 v86, 0x4b800000, v83
	v_cmp_gt_f32_e64 s[0:1], s3, v83
	v_cmp_gt_f32_e32 vcc, s3, v82
	s_nop 0
	v_cndmask_b32_e64 v83, v83, v86, s[0:1]
	v_rsq_f32_e32 v83, v83
	s_nop 0
	v_mul_f32_e32 v86, 0x45800000, v83
	v_cndmask_b32_e64 v86, v83, v86, s[0:1]
	v_pk_mul_f32 v[10:11], v[10:11], v[86:87] op_sel_hi:[1,0]
	v_pk_mul_f32 v[12:13], v[12:13], v[86:87] op_sel_hi:[1,0]
	v_cvt_pk_f16_f32 v10, v10, v11
	v_cvt_pk_f16_f32 v11, v12, v13
	global_store_dwordx2 v[92:93], v[10:11], off offset:512
	v_pk_mul_f32 v[10:11], v[38:39], v[86:87] op_sel_hi:[1,0]
	v_pk_mul_f32 v[12:13], v[40:41], v[86:87] op_sel_hi:[1,0]
	v_cvt_pk_f16_f32 v10, v10, v11
	v_cvt_pk_f16_f32 v11, v12, v13
	global_store_dwordx2 v[92:93], v[10:11], off offset:1024
	v_pk_mul_f32 v[10:11], v[30:31], v[86:87] op_sel_hi:[1,0]
	v_pk_mul_f32 v[12:13], v[32:33], v[86:87] op_sel_hi:[1,0]
	v_cvt_pk_f16_f32 v10, v10, v11
	v_cvt_pk_f16_f32 v11, v12, v13
	global_store_dwordx2 v[92:93], v[10:11], off offset:1536
	v_mul_f32_e32 v10, 0x4b800000, v82
	v_cndmask_b32_e32 v10, v82, v10, vcc
	v_rsq_f32_e32 v10, v10
	v_pk_mul_f32 v[18:19], v[18:19], v[86:87] op_sel_hi:[1,0]
	v_pk_mul_f32 v[20:21], v[20:21], v[86:87] op_sel_hi:[1,0]
	v_cvt_pk_f16_f32 v18, v18, v19
	v_mul_f32_e32 v11, 0x45800000, v10
	v_cvt_pk_f16_f32 v19, v20, v21
	v_cndmask_b32_e32 v10, v10, v11, vcc
	global_store_dwordx2 v[92:93], v[18:19], off
	v_lshlrev_b64 v[12:13], 11, v[74:75]
	v_pk_mul_f32 v[18:19], v[50:51], v[10:11] op_sel_hi:[1,0]
	v_pk_mul_f32 v[20:21], v[52:53], v[10:11] op_sel_hi:[1,0]
	v_lshl_add_u64 v[12:13], v[66:67], 0, v[12:13]
	v_cvt_pk_f16_f32 v18, v18, v19
	v_cvt_pk_f16_f32 v19, v20, v21
	global_store_dwordx2 v[12:13], v[18:19], off
	v_pk_mul_f32 v[18:19], v[46:47], v[10:11] op_sel_hi:[1,0]
	v_pk_mul_f32 v[20:21], v[48:49], v[10:11] op_sel_hi:[1,0]
	v_cvt_pk_f16_f32 v18, v18, v19
	v_cvt_pk_f16_f32 v19, v20, v21
	global_store_dwordx2 v[12:13], v[18:19], off offset:512
	v_pk_mul_f32 v[18:19], v[62:63], v[10:11] op_sel_hi:[1,0]
	v_pk_mul_f32 v[20:21], v[64:65], v[10:11] op_sel_hi:[1,0]
	v_cvt_pk_f16_f32 v18, v18, v19
	v_cvt_pk_f16_f32 v19, v20, v21
	global_store_dwordx2 v[12:13], v[18:19], off offset:1024
	v_pk_mul_f32 v[18:19], v[58:59], v[10:11] op_sel_hi:[1,0]
	v_pk_mul_f32 v[10:11], v[60:61], v[10:11] op_sel_hi:[1,0]
	v_cvt_pk_f16_f32 v18, v18, v19
	v_cvt_pk_f16_f32 v19, v10, v11
	global_store_dwordx2 v[12:13], v[18:19], off offset:1536
	v_mov_b32_e32 v12, v84
	v_mov_b32_e32 v13, v76
	v_mov_b32_e32 v76, v85
	v_pk_add_f32 v[12:13], v[12:13], v[76:77]
	v_mov_b32_e32 v18, v88
	v_mov_b32_e32 v19, v78
	v_pk_add_f32 v[12:13], v[12:13], v[18:19]
	v_mov_b32_e32 v78, v89
	v_pk_add_f32 v[12:13], v[12:13], v[78:79]
	ds_bpermute_b32 v19, v224, v13
	ds_bpermute_b32 v18, v224, v12
	v_lshlrev_b64 v[10:11], 11, v[80:81]
	v_lshl_add_u64 v[10:11], v[66:67], 0, v[10:11]
	s_waitcnt lgkmcnt(0)
	v_pk_add_f32 v[12:13], v[12:13], v[18:19]
	ds_bpermute_b32 v19, v228, v13
	ds_bpermute_b32 v18, v228, v12
	s_waitcnt lgkmcnt(0)
	v_pk_add_f32 v[12:13], v[12:13], v[18:19]
	ds_bpermute_b32 v19, v227, v13
	ds_bpermute_b32 v18, v227, v12
	s_waitcnt lgkmcnt(0)
	v_pk_add_f32 v[12:13], v[12:13], v[18:19]
	ds_bpermute_b32 v19, v226, v13
	ds_bpermute_b32 v18, v226, v12
	s_waitcnt lgkmcnt(0)
	v_pk_add_f32 v[12:13], v[12:13], v[18:19]
	ds_bpermute_b32 v19, v225, v13
	ds_bpermute_b32 v18, v225, v12
	s_waitcnt lgkmcnt(0)
	v_pk_add_f32 v[12:13], v[12:13], v[18:19]
	ds_bpermute_b32 v19, v223, v13
	ds_bpermute_b32 v18, v223, v12
	s_waitcnt lgkmcnt(0)
; DI unsigned pk2(float lo, float hi) { f32x2 v = {lo, hi}; bf2_t b = __builtin_convertvector(v, bf2_t); return __builtin_bit_cast(unsigned, b); }
; template <int MODE, int MT> DI void norm_rows(const float* src, const float* src2, float* x, int d2, bf16_t* xb, const float* __restrict__ g) {
;     ...
;             for (int i = 0; i < 4; ++i) { v[q][i] = *(const f32x4*)(s + i * 256 + lane * 4); ss[q] += v[q][i][0] * v[q][i][0] + v[q][i][1] * v[q][i][1] + v[q][i][2] * v[q][i][2] + v[q][i][3] * v[q][i][3]; }
;         }
; #pragma unroll
;         for (int o = 32; o >= 1; o >>= 1)
; #pragma unroll
;             for (int q = 0; q < 4; ++q) ss[q] += __shfl_xor(ss[q], o);
; #pragma unroll
;         for (int q = 0; q < 4; ++q) {
;             const int row = wave * (MT * 4) + rb * 4 + q, grow = row + (row >= 64 ? d2 : 0);
;             const float rstd = rsqrtf(ss[q] * (1.f / DM) + 1e-6f);
; #pragma unroll
;             for (int i = 0; i < 4; ++i) {
;                 if (MODE == 0) *(f32x4*)(x + (size_t)grow * DM + i * 256 + lane * 4) = v[q][i];
;                 if (MODE == 2) { f32x4 gg = *(const f32x4*)(g + i * 256 + lane * 4); *(f32x4*)(x + (size_t)grow * DM + i * 256 + lane * 4) = v[q][i] * rstd * gg; }
;                 else { u32x2 o = {pk2(v[q][i][0] * rstd, v[q][i][1] * rstd), pk2(v[q][i][2] * rstd, v[q][i][3] * rstd)}; *(u32x2*)(xb + (size_t)grow * DM + i * 256 + lane * 4) = o; }
;             }
;         }
	v_pk_add_f32 v[12:13], v[12:13], v[18:19]
	s_nop 0
	v_pk_fma_f32 v[12:13], v[12:13], s[4:5], v[70:71] op_sel_hi:[1,0,0]
	s_nop 0
	v_mul_f32_e32 v18, 0x4b800000, v13
	v_cmp_gt_f32_e64 s[0:1], s3, v13
	v_cmp_gt_f32_e32 vcc, s3, v12
	s_nop 0
	v_cndmask_b32_e64 v13, v13, v18, s[0:1]
	v_rsq_f32_e32 v13, v13
	s_nop 0
	v_mul_f32_e32 v18, 0x45800000, v13
	v_cndmask_b32_e64 v18, v13, v18, s[0:1]
	v_pk_mul_f32 v[2:3], v[2:3], v[18:19] op_sel_hi:[1,0]
	v_pk_mul_f32 v[4:5], v[4:5], v[18:19] op_sel_hi:[1,0]
	v_cvt_pk_f16_f32 v2, v2, v3
	v_cvt_pk_f16_f32 v3, v4, v5
	global_store_dwordx2 v[10:11], v[2:3], off offset:512
	v_pk_mul_f32 v[2:3], v[22:23], v[18:19] op_sel_hi:[1,0]
	v_pk_mul_f32 v[4:5], v[24:25], v[18:19] op_sel_hi:[1,0]
	v_cvt_pk_f16_f32 v2, v2, v3
	v_cvt_pk_f16_f32 v3, v4, v5
	global_store_dwordx2 v[10:11], v[2:3], off offset:1024
	v_pk_mul_f32 v[2:3], v[14:15], v[18:19] op_sel_hi:[1,0]
	v_pk_mul_f32 v[4:5], v[16:17], v[18:19] op_sel_hi:[1,0]
	v_cvt_pk_f16_f32 v2, v2, v3
	v_cvt_pk_f16_f32 v3, v4, v5
	global_store_dwordx2 v[10:11], v[2:3], off offset:1536
	v_mul_f32_e32 v2, 0x4b800000, v12
	v_cndmask_b32_e32 v2, v12, v2, vcc
	v_rsq_f32_e32 v2, v2
	v_pk_mul_f32 v[6:7], v[6:7], v[18:19] op_sel_hi:[1,0]
	v_pk_mul_f32 v[8:9], v[8:9], v[18:19] op_sel_hi:[1,0]
	v_cvt_pk_f16_f32 v6, v6, v7
	v_mul_f32_e32 v3, 0x45800000, v2
	v_cvt_pk_f16_f32 v7, v8, v9
	v_cndmask_b32_e32 v2, v2, v3, vcc
	global_store_dwordx2 v[10:11], v[6:7], off
	v_lshlrev_b64 v[4:5], 11, v[72:73]
	v_pk_mul_f32 v[6:7], v[34:35], v[2:3] op_sel_hi:[1,0]
	v_pk_mul_f32 v[8:9], v[36:37], v[2:3] op_sel_hi:[1,0]
	v_lshl_add_u64 v[4:5], v[66:67], 0, v[4:5]
	v_cvt_pk_f16_f32 v6, v6, v7
	v_cvt_pk_f16_f32 v7, v8, v9
	global_store_dwordx2 v[4:5], v[6:7], off
	v_pk_mul_f32 v[6:7], v[26:27], v[2:3] op_sel_hi:[1,0]
	v_pk_mul_f32 v[8:9], v[28:29], v[2:3] op_sel_hi:[1,0]
	v_cvt_pk_f16_f32 v6, v6, v7
	v_cvt_pk_f16_f32 v7, v8, v9
	global_store_dwordx2 v[4:5], v[6:7], off offset:512
	v_pk_mul_f32 v[6:7], v[54:55], v[2:3] op_sel_hi:[1,0]
	v_pk_mul_f32 v[8:9], v[56:57], v[2:3] op_sel_hi:[1,0]
	v_cvt_pk_f16_f32 v6, v6, v7
	v_cvt_pk_f16_f32 v7, v8, v9
	global_store_dwordx2 v[4:5], v[6:7], off offset:1024
	v_pk_mul_f32 v[6:7], v[42:43], v[2:3] op_sel_hi:[1,0]
	v_pk_mul_f32 v[2:3], v[44:45], v[2:3] op_sel_hi:[1,0]
	v_cmp_lt_i32_e32 vcc, 4, v94
	v_cvt_pk_f16_f32 v6, v6, v7
	v_cvt_pk_f16_f32 v7, v2, v3
	v_cndmask_b32_e32 v2, 0, v95, vcc
	v_add_u32_e32 v0, v2, v0
	v_add_u32_e32 v92, 4, v0
	v_ashrrev_i32_e32 v93, 31, v92
	v_lshlrev_b64 v[2:3], 12, v[92:93]
	global_store_dwordx2 v[4:5], v[6:7], off offset:1536
	v_lshl_add_u64 v[2:3], v[68:69], 0, v[2:3]
	global_load_dwordx4 v[18:21], v[2:3], off
	global_load_dwordx4 v[10:13], v[2:3], off offset:1024
	global_load_dwordx4 v[34:37], v[2:3], off offset:2048
	global_load_dwordx4 v[26:29], v[2:3], off offset:3072
	v_add_u32_e32 v74, 5, v0
	v_ashrrev_i32_e32 v75, 31, v74
	v_add_u32_e32 v82, 6, v0
	v_ashrrev_i32_e32 v83, 31, v82
	v_add_u32_e32 v72, 7, v0
	v_ashrrev_i32_e32 v73, 31, v72
	v_lshlrev_b64 v[92:93], 11, v[92:93]
	v_lshl_add_u64 v[92:93], v[66:67], 0, v[92:93]
	s_waitcnt vmcnt(3)
	v_mov_b32_e32 v6, v19
	s_waitcnt vmcnt(2)
	v_mov_b32_e32 v7, v11
	v_mov_b32_e32 v4, v18
	v_mov_b32_e32 v5, v10
	v_pk_mul_f32 v[6:7], v[6:7], v[6:7]
	s_waitcnt vmcnt(1)
	v_mov_b32_e32 v2, v34
	v_pk_fma_f32 v[4:5], v[4:5], v[4:5], v[6:7]
	v_mov_b32_e32 v6, v20
	v_mov_b32_e32 v7, v12
	v_pk_fma_f32 v[4:5], v[6:7], v[6:7], v[4:5]
	v_mov_b32_e32 v6, v21
	v_mov_b32_e32 v7, v13
	v_pk_fma_f32 v[78:79], v[6:7], v[6:7], v[4:5]
	v_mov_b32_e32 v4, v35
	s_waitcnt vmcnt(0)
	v_mov_b32_e32 v5, v27
	v_mov_b32_e32 v3, v26
	v_pk_mul_f32 v[4:5], v[4:5], v[4:5]
	s_nop 0
	v_pk_fma_f32 v[2:3], v[2:3], v[2:3], v[4:5]
	v_mov_b32_e32 v4, v36
	v_mov_b32_e32 v5, v28
	v_pk_fma_f32 v[2:3], v[4:5], v[4:5], v[2:3]
	v_mov_b32_e32 v4, v37
	v_mov_b32_e32 v5, v29
	v_pk_fma_f32 v[84:85], v[4:5], v[4:5], v[2:3]
	v_lshlrev_b64 v[2:3], 12, v[74:75]
	v_lshl_add_u64 v[2:3], v[68:69], 0, v[2:3]
	global_load_dwordx4 v[46:49], v[2:3], off
	global_load_dwordx4 v[42:45], v[2:3], off offset:1024
	global_load_dwordx4 v[54:57], v[2:3], off offset:2048
	global_load_dwordx4 v[50:53], v[2:3], off offset:3072
	s_waitcnt vmcnt(3)
	v_mov_b32_e32 v6, v47
	s_waitcnt vmcnt(2)
	v_mov_b32_e32 v7, v43
	v_mov_b32_e32 v4, v46
	v_mov_b32_e32 v5, v42
	v_pk_mul_f32 v[6:7], v[6:7], v[6:7]
	s_waitcnt vmcnt(1)
	v_mov_b32_e32 v2, v54
	v_pk_fma_f32 v[4:5], v[4:5], v[4:5], v[6:7]
	v_mov_b32_e32 v6, v48
	v_mov_b32_e32 v7, v44
	v_pk_fma_f32 v[4:5], v[6:7], v[6:7], v[4:5]
	v_mov_b32_e32 v6, v49
	v_mov_b32_e32 v7, v45
	v_pk_fma_f32 v[88:89], v[6:7], v[6:7], v[4:5]
	v_mov_b32_e32 v4, v55
	s_waitcnt vmcnt(0)
	v_mov_b32_e32 v5, v51
	v_mov_b32_e32 v3, v50
	v_pk_mul_f32 v[4:5], v[4:5], v[4:5]
	s_nop 0
	v_pk_fma_f32 v[2:3], v[2:3], v[2:3], v[4:5]
	v_mov_b32_e32 v4, v56
	v_mov_b32_e32 v5, v52
	v_pk_fma_f32 v[2:3], v[4:5], v[4:5], v[2:3]
	v_mov_b32_e32 v4, v57
	v_mov_b32_e32 v5, v53
	v_pk_fma_f32 v[90:91], v[4:5], v[4:5], v[2:3]
	v_lshlrev_b64 v[2:3], 12, v[82:83]
	v_lshl_add_u64 v[14:15], v[68:69], 0, v[2:3]
	global_load_dwordx4 v[6:9], v[14:15], off
	global_load_dwordx4 v[2:5], v[14:15], off offset:1024
	s_waitcnt vmcnt(1)
	v_mov_b32_e32 v22, v7
	s_waitcnt vmcnt(0)
	v_mov_b32_e32 v23, v3
	v_mov_b32_e32 v16, v6
	v_mov_b32_e32 v17, v2
	v_pk_mul_f32 v[22:23], v[22:23], v[22:23]
	s_nop 0
	v_pk_fma_f32 v[16:17], v[16:17], v[16:17], v[22:23]
	v_mov_b32_e32 v22, v8
	v_mov_b32_e32 v23, v4
	v_pk_fma_f32 v[16:17], v[22:23], v[22:23], v[16:17]
	v_mov_b32_e32 v22, v9
	v_mov_b32_e32 v23, v5
	v_pk_fma_f32 v[76:77], v[22:23], v[22:23], v[16:17]
	global_load_dwordx4 v[22:25], v[14:15], off offset:2048
	s_nop 0
	global_load_dwordx4 v[14:17], v[14:15], off offset:3072
	s_waitcnt vmcnt(1)
; DI unsigned pk2(float lo, float hi) { f32x2 v = {lo, hi}; bf2_t b = __builtin_convertvector(v, bf2_t); return __builtin_bit_cast(unsigned, b); }
; template <int MODE, int MT> DI void norm_rows(const float* src, const float* src2, float* x, int d2, bf16_t* xb, const float* __restrict__ g) {
;     ...
;             for (int i = 0; i < 4; ++i) { v[q][i] = *(const f32x4*)(s + i * 256 + lane * 4); ss[q] += v[q][i][0] * v[q][i][0] + v[q][i][1] * v[q][i][1] + v[q][i][2] * v[q][i][2] + v[q][i][3] * v[q][i][3]; }
;         }
; #pragma unroll
;         for (int o = 32; o >= 1; o >>= 1)
; #pragma unroll
;             for (int q = 0; q < 4; ++q) ss[q] += __shfl_xor(ss[q], o);
; #pragma unroll
;         for (int q = 0; q < 4; ++q) {
;             const int row = wave * (MT * 4) + rb * 4 + q, grow = row + (row >= 64 ? d2 : 0);
;             const float rstd = rsqrtf(ss[q] * (1.f / DM) + 1e-6f);
; #pragma unroll
;             for (int i = 0; i < 4; ++i) {
;                 if (MODE == 0) *(f32x4*)(x + (size_t)grow * DM + i * 256 + lane * 4) = v[q][i];
;                 if (MODE == 2) { f32x4 gg = *(const f32x4*)(g + i * 256 + lane * 4); *(f32x4*)(x + (size_t)grow * DM + i * 256 + lane * 4) = v[q][i] * rstd * gg; }
;                 else { u32x2 o = {pk2(v[q][i][0] * rstd, v[q][i][1] * rstd), pk2(v[q][i][2] * rstd, v[q][i][3] * rstd)}; *(u32x2*)(xb + (size_t)grow * DM + i * 256 + lane * 4) = o; }
;             }
;         }
	v_mov_b32_e32 v32, v23
	s_waitcnt vmcnt(0)
	v_mov_b32_e32 v33, v15
	v_mov_b32_e32 v30, v22
	v_mov_b32_e32 v31, v14
	v_pk_mul_f32 v[32:33], v[32:33], v[32:33]
	s_nop 0
	v_pk_fma_f32 v[30:31], v[30:31], v[30:31], v[32:33]
	v_mov_b32_e32 v32, v24
	v_mov_b32_e32 v33, v16
	v_pk_fma_f32 v[30:31], v[32:33], v[32:33], v[30:31]
	v_mov_b32_e32 v32, v25
	v_mov_b32_e32 v33, v17
	v_pk_fma_f32 v[80:81], v[32:33], v[32:33], v[30:31]
	v_lshlrev_b64 v[30:31], 12, v[72:73]
	v_lshl_add_u64 v[58:59], v[68:69], 0, v[30:31]
	global_load_dwordx4 v[38:41], v[58:59], off
	global_load_dwordx4 v[30:33], v[58:59], off offset:1024
	s_waitcnt vmcnt(1)
	v_mov_b32_e32 v62, v39
	s_waitcnt vmcnt(0)
	v_mov_b32_e32 v63, v31
	v_mov_b32_e32 v60, v38
	v_mov_b32_e32 v61, v30
	v_pk_mul_f32 v[62:63], v[62:63], v[62:63]
	s_nop 0
	v_pk_fma_f32 v[60:61], v[60:61], v[60:61], v[62:63]
	v_mov_b32_e32 v62, v40
	v_mov_b32_e32 v63, v32
	v_pk_fma_f32 v[60:61], v[62:63], v[62:63], v[60:61]
	v_mov_b32_e32 v62, v41
	v_mov_b32_e32 v63, v33
	v_pk_fma_f32 v[86:87], v[62:63], v[62:63], v[60:61]
	global_load_dwordx4 v[62:65], v[58:59], off offset:2048
	s_nop 0
	global_load_dwordx4 v[58:61], v[58:59], off offset:3072
	s_waitcnt vmcnt(1)
	v_mov_b32_e32 v96, v63
	s_waitcnt vmcnt(0)
	v_mov_b32_e32 v97, v59
	v_mov_b32_e32 v94, v62
	v_mov_b32_e32 v95, v58
	v_pk_mul_f32 v[96:97], v[96:97], v[96:97]
	s_nop 0
	v_pk_fma_f32 v[94:95], v[94:95], v[94:95], v[96:97]
	v_mov_b32_e32 v96, v64
	v_mov_b32_e32 v97, v60
	v_pk_fma_f32 v[94:95], v[96:97], v[96:97], v[94:95]
	v_mov_b32_e32 v96, v65
	v_mov_b32_e32 v97, v61
	v_pk_fma_f32 v[94:95], v[96:97], v[96:97], v[94:95]
	v_mov_b32_e32 v96, v88
	v_mov_b32_e32 v97, v78
	v_mov_b32_e32 v78, v89
	v_pk_add_f32 v[78:79], v[96:97], v[78:79]
	v_mov_b32_e32 v88, v90
	v_mov_b32_e32 v89, v84
	v_pk_add_f32 v[78:79], v[78:79], v[88:89]
	v_mov_b32_e32 v84, v91
	v_pk_add_f32 v[78:79], v[78:79], v[84:85]
	ds_bpermute_b32 v85, v224, v79
	ds_bpermute_b32 v84, v224, v78
	v_add_u32_e32 v90, 8, v0
	v_ashrrev_i32_e32 v91, 31, v90
	s_waitcnt lgkmcnt(0)
	v_pk_add_f32 v[78:79], v[78:79], v[84:85]
	ds_bpermute_b32 v85, v228, v79
	ds_bpermute_b32 v84, v228, v78
	s_waitcnt lgkmcnt(0)
	v_pk_add_f32 v[78:79], v[78:79], v[84:85]
	ds_bpermute_b32 v85, v227, v79
	ds_bpermute_b32 v84, v227, v78
	s_waitcnt lgkmcnt(0)
	v_pk_add_f32 v[78:79], v[78:79], v[84:85]
	ds_bpermute_b32 v85, v226, v79
	ds_bpermute_b32 v84, v226, v78
	s_waitcnt lgkmcnt(0)
	v_pk_add_f32 v[78:79], v[78:79], v[84:85]
	ds_bpermute_b32 v85, v225, v79
	ds_bpermute_b32 v84, v225, v78
	s_waitcnt lgkmcnt(0)
	v_pk_add_f32 v[78:79], v[78:79], v[84:85]
	ds_bpermute_b32 v85, v223, v79
	ds_bpermute_b32 v84, v223, v78
	s_waitcnt lgkmcnt(0)
	v_pk_add_f32 v[78:79], v[78:79], v[84:85]
	s_nop 0
	v_pk_fma_f32 v[78:79], v[78:79], s[4:5], v[70:71] op_sel_hi:[1,0,0]
	s_nop 0
	v_mul_f32_e32 v84, 0x4b800000, v79
	v_cmp_gt_f32_e64 s[0:1], s3, v79
	v_cmp_gt_f32_e32 vcc, s3, v78
	s_nop 0
	v_cndmask_b32_e64 v79, v79, v84, s[0:1]
	v_rsq_f32_e32 v79, v79
	s_nop 0
	v_mul_f32_e32 v84, 0x45800000, v79
	v_cndmask_b32_e64 v84, v79, v84, s[0:1]
	v_pk_mul_f32 v[10:11], v[10:11], v[84:85] op_sel_hi:[1,0]
	v_pk_mul_f32 v[12:13], v[12:13], v[84:85] op_sel_hi:[1,0]
	v_cvt_pk_f16_f32 v10, v10, v11
	v_cvt_pk_f16_f32 v11, v12, v13
	global_store_dwordx2 v[92:93], v[10:11], off offset:512
	v_pk_mul_f32 v[10:11], v[34:35], v[84:85] op_sel_hi:[1,0]
	v_pk_mul_f32 v[12:13], v[36:37], v[84:85] op_sel_hi:[1,0]
	v_cvt_pk_f16_f32 v10, v10, v11
	v_cvt_pk_f16_f32 v11, v12, v13
	global_store_dwordx2 v[92:93], v[10:11], off offset:1024
	v_pk_mul_f32 v[10:11], v[26:27], v[84:85] op_sel_hi:[1,0]
	v_pk_mul_f32 v[12:13], v[28:29], v[84:85] op_sel_hi:[1,0]
	v_cvt_pk_f16_f32 v10, v10, v11
	v_cvt_pk_f16_f32 v11, v12, v13
	global_store_dwordx2 v[92:93], v[10:11], off offset:1536
	v_mul_f32_e32 v10, 0x4b800000, v78
	v_cndmask_b32_e32 v10, v78, v10, vcc
	v_rsq_f32_e32 v10, v10
	v_pk_mul_f32 v[18:19], v[18:19], v[84:85] op_sel_hi:[1,0]
	v_pk_mul_f32 v[20:21], v[20:21], v[84:85] op_sel_hi:[1,0]
	v_cvt_pk_f16_f32 v18, v18, v19
	v_mul_f32_e32 v11, 0x45800000, v10
	v_cvt_pk_f16_f32 v19, v20, v21
	v_cndmask_b32_e32 v10, v10, v11, vcc
	global_store_dwordx2 v[92:93], v[18:19], off
	v_lshlrev_b64 v[12:13], 11, v[74:75]
	v_pk_mul_f32 v[18:19], v[46:47], v[10:11] op_sel_hi:[1,0]
	v_pk_mul_f32 v[20:21], v[48:49], v[10:11] op_sel_hi:[1,0]
	v_lshl_add_u64 v[12:13], v[66:67], 0, v[12:13]
	v_cvt_pk_f16_f32 v18, v18, v19
	v_cvt_pk_f16_f32 v19, v20, v21
	global_store_dwordx2 v[12:13], v[18:19], off
	v_pk_mul_f32 v[18:19], v[42:43], v[10:11] op_sel_hi:[1,0]
	v_pk_mul_f32 v[20:21], v[44:45], v[10:11] op_sel_hi:[1,0]
	v_cvt_pk_f16_f32 v18, v18, v19
	v_cvt_pk_f16_f32 v19, v20, v21
	global_store_dwordx2 v[12:13], v[18:19], off offset:512
	v_pk_mul_f32 v[18:19], v[54:55], v[10:11] op_sel_hi:[1,0]
	v_pk_mul_f32 v[20:21], v[56:57], v[10:11] op_sel_hi:[1,0]
	v_cvt_pk_f16_f32 v18, v18, v19
	v_cvt_pk_f16_f32 v19, v20, v21
	global_store_dwordx2 v[12:13], v[18:19], off offset:1024
	v_pk_mul_f32 v[18:19], v[50:51], v[10:11] op_sel_hi:[1,0]
	v_pk_mul_f32 v[10:11], v[52:53], v[10:11] op_sel_hi:[1,0]
	v_cvt_pk_f16_f32 v18, v18, v19
	v_cvt_pk_f16_f32 v19, v10, v11
	global_store_dwordx2 v[12:13], v[18:19], off offset:1536
	v_mov_b32_e32 v12, v86
	v_mov_b32_e32 v13, v76
	v_mov_b32_e32 v76, v87
	v_pk_add_f32 v[12:13], v[12:13], v[76:77]
	v_mov_b32_e32 v18, v94
	v_mov_b32_e32 v19, v80
	v_pk_add_f32 v[12:13], v[12:13], v[18:19]
	v_mov_b32_e32 v80, v95
	v_pk_add_f32 v[12:13], v[12:13], v[80:81]
	ds_bpermute_b32 v19, v224, v13
	ds_bpermute_b32 v18, v224, v12
	v_lshlrev_b64 v[10:11], 11, v[82:83]
	v_lshl_add_u64 v[10:11], v[66:67], 0, v[10:11]
	v_add_u32_e32 v74, 9, v0
	v_ashrrev_i32_e32 v75, 31, v74
	s_waitcnt lgkmcnt(0)
; DI unsigned pk2(float lo, float hi) { f32x2 v = {lo, hi}; bf2_t b = __builtin_convertvector(v, bf2_t); return __builtin_bit_cast(unsigned, b); }
; template <int MODE, int MT> DI void norm_rows(const float* src, const float* src2, float* x, int d2, bf16_t* xb, const float* __restrict__ g) {
;     ...
;             for (int i = 0; i < 4; ++i) { v[q][i] = *(const f32x4*)(s + i * 256 + lane * 4); ss[q] += v[q][i][0] * v[q][i][0] + v[q][i][1] * v[q][i][1] + v[q][i][2] * v[q][i][2] + v[q][i][3] * v[q][i][3]; }
;         }
; #pragma unroll
;         for (int o = 32; o >= 1; o >>= 1)
; #pragma unroll
;             for (int q = 0; q < 4; ++q) ss[q] += __shfl_xor(ss[q], o);
; #pragma unroll
;         for (int q = 0; q < 4; ++q) {
;             const int row = wave * (MT * 4) + rb * 4 + q, grow = row + (row >= 64 ? d2 : 0);
;             const float rstd = rsqrtf(ss[q] * (1.f / DM) + 1e-6f);
; #pragma unroll
;             for (int i = 0; i < 4; ++i) {
;                 if (MODE == 0) *(f32x4*)(x + (size_t)grow * DM + i * 256 + lane * 4) = v[q][i];
;                 if (MODE == 2) { f32x4 gg = *(const f32x4*)(g + i * 256 + lane * 4); *(f32x4*)(x + (size_t)grow * DM + i * 256 + lane * 4) = v[q][i] * rstd * gg; }
;                 else { u32x2 o = {pk2(v[q][i][0] * rstd, v[q][i][1] * rstd), pk2(v[q][i][2] * rstd, v[q][i][3] * rstd)}; *(u32x2*)(xb + (size_t)grow * DM + i * 256 + lane * 4) = o; }
;             }
;         }
	v_pk_add_f32 v[12:13], v[12:13], v[18:19]
	ds_bpermute_b32 v19, v228, v13
	ds_bpermute_b32 v18, v228, v12
	v_add_u32_e32 v82, 10, v0
	v_ashrrev_i32_e32 v83, 31, v82
	s_waitcnt lgkmcnt(0)
	v_pk_add_f32 v[12:13], v[12:13], v[18:19]
	ds_bpermute_b32 v19, v227, v13
	ds_bpermute_b32 v18, v227, v12
	s_waitcnt lgkmcnt(0)
	v_pk_add_f32 v[12:13], v[12:13], v[18:19]
	ds_bpermute_b32 v19, v226, v13
	ds_bpermute_b32 v18, v226, v12
	s_waitcnt lgkmcnt(0)
	v_pk_add_f32 v[12:13], v[12:13], v[18:19]
	ds_bpermute_b32 v19, v225, v13
	ds_bpermute_b32 v18, v225, v12
	s_waitcnt lgkmcnt(0)
	v_pk_add_f32 v[12:13], v[12:13], v[18:19]
	ds_bpermute_b32 v19, v223, v13
	ds_bpermute_b32 v18, v223, v12
	s_waitcnt lgkmcnt(0)
	v_pk_add_f32 v[12:13], v[12:13], v[18:19]
	s_nop 0
	v_pk_fma_f32 v[12:13], v[12:13], s[4:5], v[70:71] op_sel_hi:[1,0,0]
	s_nop 0
	v_mul_f32_e32 v18, 0x4b800000, v13
	v_cmp_gt_f32_e64 s[0:1], s3, v13
	v_cmp_gt_f32_e32 vcc, s3, v12
	s_nop 0
	v_cndmask_b32_e64 v13, v13, v18, s[0:1]
	v_rsq_f32_e32 v13, v13
	s_nop 0
	v_mul_f32_e32 v18, 0x45800000, v13
	v_cndmask_b32_e64 v18, v13, v18, s[0:1]
	v_pk_mul_f32 v[2:3], v[2:3], v[18:19] op_sel_hi:[1,0]
	v_pk_mul_f32 v[4:5], v[4:5], v[18:19] op_sel_hi:[1,0]
	v_cvt_pk_f16_f32 v2, v2, v3
	v_cvt_pk_f16_f32 v3, v4, v5
	global_store_dwordx2 v[10:11], v[2:3], off offset:512
	v_pk_mul_f32 v[2:3], v[22:23], v[18:19] op_sel_hi:[1,0]
	v_pk_mul_f32 v[4:5], v[24:25], v[18:19] op_sel_hi:[1,0]
	v_cvt_pk_f16_f32 v2, v2, v3
	v_cvt_pk_f16_f32 v3, v4, v5
	global_store_dwordx2 v[10:11], v[2:3], off offset:1024
	v_pk_mul_f32 v[2:3], v[14:15], v[18:19] op_sel_hi:[1,0]
	v_pk_mul_f32 v[4:5], v[16:17], v[18:19] op_sel_hi:[1,0]
	v_cvt_pk_f16_f32 v2, v2, v3
	v_cvt_pk_f16_f32 v3, v4, v5
	global_store_dwordx2 v[10:11], v[2:3], off offset:1536
	v_mul_f32_e32 v2, 0x4b800000, v12
	v_cndmask_b32_e32 v2, v12, v2, vcc
	v_rsq_f32_e32 v2, v2
	v_pk_mul_f32 v[6:7], v[6:7], v[18:19] op_sel_hi:[1,0]
	v_pk_mul_f32 v[8:9], v[8:9], v[18:19] op_sel_hi:[1,0]
	v_cvt_pk_f16_f32 v6, v6, v7
	v_mul_f32_e32 v3, 0x45800000, v2
	v_cvt_pk_f16_f32 v7, v8, v9
	v_cndmask_b32_e32 v2, v2, v3, vcc
	global_store_dwordx2 v[10:11], v[6:7], off
	v_lshlrev_b64 v[4:5], 11, v[72:73]
	v_pk_mul_f32 v[6:7], v[38:39], v[2:3] op_sel_hi:[1,0]
	v_pk_mul_f32 v[8:9], v[40:41], v[2:3] op_sel_hi:[1,0]
	v_lshl_add_u64 v[4:5], v[66:67], 0, v[4:5]
	v_cvt_pk_f16_f32 v6, v6, v7
	v_cvt_pk_f16_f32 v7, v8, v9
	global_store_dwordx2 v[4:5], v[6:7], off
	v_pk_mul_f32 v[6:7], v[30:31], v[2:3] op_sel_hi:[1,0]
	v_pk_mul_f32 v[8:9], v[32:33], v[2:3] op_sel_hi:[1,0]
	v_cvt_pk_f16_f32 v6, v6, v7
	v_cvt_pk_f16_f32 v7, v8, v9
	global_store_dwordx2 v[4:5], v[6:7], off offset:512
	v_pk_mul_f32 v[6:7], v[62:63], v[2:3] op_sel_hi:[1,0]
	v_pk_mul_f32 v[8:9], v[64:65], v[2:3] op_sel_hi:[1,0]
	v_cvt_pk_f16_f32 v6, v6, v7
	v_cvt_pk_f16_f32 v7, v8, v9
	global_store_dwordx2 v[4:5], v[6:7], off offset:1024
	v_pk_mul_f32 v[6:7], v[58:59], v[2:3] op_sel_hi:[1,0]
	v_pk_mul_f32 v[2:3], v[60:61], v[2:3] op_sel_hi:[1,0]
	v_cvt_pk_f16_f32 v6, v6, v7
	v_cvt_pk_f16_f32 v7, v2, v3
	v_lshlrev_b64 v[2:3], 12, v[90:91]
	global_store_dwordx2 v[4:5], v[6:7], off offset:1536
	v_lshl_add_u64 v[2:3], v[68:69], 0, v[2:3]
	global_load_dwordx4 v[18:21], v[2:3], off
	global_load_dwordx4 v[10:13], v[2:3], off offset:1024
	global_load_dwordx4 v[34:37], v[2:3], off offset:2048
	global_load_dwordx4 v[26:29], v[2:3], off offset:3072
	v_add_u32_e32 v72, 11, v0
	v_ashrrev_i32_e32 v73, 31, v72
	v_lshlrev_b64 v[90:91], 11, v[90:91]
	v_lshl_add_u64 v[90:91], v[66:67], 0, v[90:91]
	s_waitcnt vmcnt(3)
	v_mov_b32_e32 v6, v19
	s_waitcnt vmcnt(2)
	v_mov_b32_e32 v7, v11
	v_mov_b32_e32 v4, v18
	v_mov_b32_e32 v5, v10
	v_pk_mul_f32 v[6:7], v[6:7], v[6:7]
	s_waitcnt vmcnt(1)
	v_mov_b32_e32 v2, v34
	v_pk_fma_f32 v[4:5], v[4:5], v[4:5], v[6:7]
	v_mov_b32_e32 v6, v20
	v_mov_b32_e32 v7, v12
	v_pk_fma_f32 v[4:5], v[6:7], v[6:7], v[4:5]
	v_mov_b32_e32 v6, v21
	v_mov_b32_e32 v7, v13
	v_pk_fma_f32 v[78:79], v[6:7], v[6:7], v[4:5]
	v_mov_b32_e32 v4, v35
	s_waitcnt vmcnt(0)
	v_mov_b32_e32 v5, v27
	v_mov_b32_e32 v3, v26
	v_pk_mul_f32 v[4:5], v[4:5], v[4:5]
	s_nop 0
	v_pk_fma_f32 v[2:3], v[2:3], v[2:3], v[4:5]
	v_mov_b32_e32 v4, v36
	v_mov_b32_e32 v5, v28
	v_pk_fma_f32 v[2:3], v[4:5], v[4:5], v[2:3]
	v_mov_b32_e32 v4, v37
	v_mov_b32_e32 v5, v29
	v_pk_fma_f32 v[84:85], v[4:5], v[4:5], v[2:3]
	v_lshlrev_b64 v[2:3], 12, v[74:75]
	v_lshl_add_u64 v[2:3], v[68:69], 0, v[2:3]
	global_load_dwordx4 v[46:49], v[2:3], off
	global_load_dwordx4 v[42:45], v[2:3], off offset:1024
	global_load_dwordx4 v[54:57], v[2:3], off offset:2048
	global_load_dwordx4 v[50:53], v[2:3], off offset:3072
	s_waitcnt vmcnt(3)
	v_mov_b32_e32 v6, v47
	s_waitcnt vmcnt(2)
	v_mov_b32_e32 v7, v43
	v_mov_b32_e32 v4, v46
	v_mov_b32_e32 v5, v42
	v_pk_mul_f32 v[6:7], v[6:7], v[6:7]
	s_waitcnt vmcnt(1)
	v_mov_b32_e32 v2, v54
	v_pk_fma_f32 v[4:5], v[4:5], v[4:5], v[6:7]
	v_mov_b32_e32 v6, v48
	v_mov_b32_e32 v7, v44
	v_pk_fma_f32 v[4:5], v[6:7], v[6:7], v[4:5]
	v_mov_b32_e32 v6, v49
	v_mov_b32_e32 v7, v45
	v_pk_fma_f32 v[86:87], v[6:7], v[6:7], v[4:5]
	v_mov_b32_e32 v4, v55
	s_waitcnt vmcnt(0)
	v_mov_b32_e32 v5, v51
	v_mov_b32_e32 v3, v50
	v_pk_mul_f32 v[4:5], v[4:5], v[4:5]
	s_nop 0
	v_pk_fma_f32 v[2:3], v[2:3], v[2:3], v[4:5]
	v_mov_b32_e32 v4, v56
	v_mov_b32_e32 v5, v52
	v_pk_fma_f32 v[2:3], v[4:5], v[4:5], v[2:3]
	v_mov_b32_e32 v4, v57
	v_mov_b32_e32 v5, v53
	v_pk_fma_f32 v[88:89], v[4:5], v[4:5], v[2:3]
	v_lshlrev_b64 v[2:3], 12, v[82:83]
	v_lshl_add_u64 v[14:15], v[68:69], 0, v[2:3]
	global_load_dwordx4 v[6:9], v[14:15], off
	global_load_dwordx4 v[2:5], v[14:15], off offset:1024
	s_waitcnt vmcnt(1)
; DI unsigned pk2(float lo, float hi) { f32x2 v = {lo, hi}; bf2_t b = __builtin_convertvector(v, bf2_t); return __builtin_bit_cast(unsigned, b); }
; template <int MODE, int MT> DI void norm_rows(const float* src, const float* src2, float* x, int d2, bf16_t* xb, const float* __restrict__ g) {
;     ...
;             for (int i = 0; i < 4; ++i) { v[q][i] = *(const f32x4*)(s + i * 256 + lane * 4); ss[q] += v[q][i][0] * v[q][i][0] + v[q][i][1] * v[q][i][1] + v[q][i][2] * v[q][i][2] + v[q][i][3] * v[q][i][3]; }
;         }
; #pragma unroll
;         for (int o = 32; o >= 1; o >>= 1)
; #pragma unroll
;             for (int q = 0; q < 4; ++q) ss[q] += __shfl_xor(ss[q], o);
; #pragma unroll
;         for (int q = 0; q < 4; ++q) {
;             const int row = wave * (MT * 4) + rb * 4 + q, grow = row + (row >= 64 ? d2 : 0);
;             const float rstd = rsqrtf(ss[q] * (1.f / DM) + 1e-6f);
; #pragma unroll
;             for (int i = 0; i < 4; ++i) {
;                 if (MODE == 0) *(f32x4*)(x + (size_t)grow * DM + i * 256 + lane * 4) = v[q][i];
;                 if (MODE == 2) { f32x4 gg = *(const f32x4*)(g + i * 256 + lane * 4); *(f32x4*)(x + (size_t)grow * DM + i * 256 + lane * 4) = v[q][i] * rstd * gg; }
;                 else { u32x2 o = {pk2(v[q][i][0] * rstd, v[q][i][1] * rstd), pk2(v[q][i][2] * rstd, v[q][i][3] * rstd)}; *(u32x2*)(xb + (size_t)grow * DM + i * 256 + lane * 4) = o; }
;             }
;         }
	v_mov_b32_e32 v22, v7
	s_waitcnt vmcnt(0)
	v_mov_b32_e32 v23, v3
	v_mov_b32_e32 v16, v6
	v_mov_b32_e32 v17, v2
	v_pk_mul_f32 v[22:23], v[22:23], v[22:23]
	s_nop 0
	v_pk_fma_f32 v[16:17], v[16:17], v[16:17], v[22:23]
	v_mov_b32_e32 v22, v8
	v_mov_b32_e32 v23, v4
	v_pk_fma_f32 v[16:17], v[22:23], v[22:23], v[16:17]
	v_mov_b32_e32 v22, v9
	v_mov_b32_e32 v23, v5
	v_pk_fma_f32 v[76:77], v[22:23], v[22:23], v[16:17]
	global_load_dwordx4 v[22:25], v[14:15], off offset:2048
	s_nop 0
	global_load_dwordx4 v[14:17], v[14:15], off offset:3072
	s_waitcnt vmcnt(1)
	v_mov_b32_e32 v32, v23
	s_waitcnt vmcnt(0)
	v_mov_b32_e32 v33, v15
	v_mov_b32_e32 v30, v22
	v_mov_b32_e32 v31, v14
	v_pk_mul_f32 v[32:33], v[32:33], v[32:33]
	s_nop 0
	v_pk_fma_f32 v[30:31], v[30:31], v[30:31], v[32:33]
	v_mov_b32_e32 v32, v24
	v_mov_b32_e32 v33, v16
	v_pk_fma_f32 v[30:31], v[32:33], v[32:33], v[30:31]
	v_mov_b32_e32 v32, v25
	v_mov_b32_e32 v33, v17
	v_pk_fma_f32 v[80:81], v[32:33], v[32:33], v[30:31]
	v_lshlrev_b64 v[30:31], 12, v[72:73]
	v_lshl_add_u64 v[58:59], v[68:69], 0, v[30:31]
	global_load_dwordx4 v[38:41], v[58:59], off
	global_load_dwordx4 v[30:33], v[58:59], off offset:1024
	s_waitcnt vmcnt(1)
	v_mov_b32_e32 v62, v39
	s_waitcnt vmcnt(0)
	v_mov_b32_e32 v63, v31
	v_mov_b32_e32 v60, v38
	v_mov_b32_e32 v61, v30
	v_pk_mul_f32 v[62:63], v[62:63], v[62:63]
	s_nop 0
	v_pk_fma_f32 v[60:61], v[60:61], v[60:61], v[62:63]
	v_mov_b32_e32 v62, v40
	v_mov_b32_e32 v63, v32
	v_pk_fma_f32 v[60:61], v[62:63], v[62:63], v[60:61]
	v_mov_b32_e32 v62, v41
	v_mov_b32_e32 v63, v33
	v_pk_fma_f32 v[68:69], v[62:63], v[62:63], v[60:61]
	global_load_dwordx4 v[62:65], v[58:59], off offset:2048
	s_nop 0
	global_load_dwordx4 v[58:61], v[58:59], off offset:3072
	s_waitcnt vmcnt(1)
	v_mov_b32_e32 v94, v63
	s_waitcnt vmcnt(0)
	v_mov_b32_e32 v95, v59
	v_mov_b32_e32 v92, v62
	v_mov_b32_e32 v93, v58
	v_pk_mul_f32 v[94:95], v[94:95], v[94:95]
	s_nop 0
	v_pk_fma_f32 v[92:93], v[92:93], v[92:93], v[94:95]
	v_mov_b32_e32 v94, v64
	v_mov_b32_e32 v95, v60
	v_pk_fma_f32 v[92:93], v[94:95], v[94:95], v[92:93]
	v_mov_b32_e32 v94, v65
	v_mov_b32_e32 v95, v61
	v_pk_fma_f32 v[92:93], v[94:95], v[94:95], v[92:93]
	v_mov_b32_e32 v94, v86
	v_mov_b32_e32 v95, v78
	v_mov_b32_e32 v78, v87
	v_pk_add_f32 v[78:79], v[94:95], v[78:79]
	v_mov_b32_e32 v86, v88
	v_mov_b32_e32 v87, v84
	v_pk_add_f32 v[78:79], v[78:79], v[86:87]
	v_mov_b32_e32 v84, v89
	v_pk_add_f32 v[78:79], v[78:79], v[84:85]
	ds_bpermute_b32 v85, v224, v79
	ds_bpermute_b32 v84, v224, v78
	s_waitcnt lgkmcnt(0)
	v_pk_add_f32 v[78:79], v[78:79], v[84:85]
	ds_bpermute_b32 v85, v228, v79
	ds_bpermute_b32 v84, v228, v78
	s_waitcnt lgkmcnt(0)
	v_pk_add_f32 v[78:79], v[78:79], v[84:85]
	ds_bpermute_b32 v85, v227, v79
	ds_bpermute_b32 v84, v227, v78
	s_waitcnt lgkmcnt(0)
	v_pk_add_f32 v[78:79], v[78:79], v[84:85]
	ds_bpermute_b32 v85, v226, v79
	ds_bpermute_b32 v84, v226, v78
	s_waitcnt lgkmcnt(0)
	v_pk_add_f32 v[78:79], v[78:79], v[84:85]
	ds_bpermute_b32 v85, v225, v79
	ds_bpermute_b32 v84, v225, v78
	s_waitcnt lgkmcnt(0)
	v_pk_add_f32 v[78:79], v[78:79], v[84:85]
	ds_bpermute_b32 v85, v223, v79
	ds_bpermute_b32 v84, v223, v78
	s_waitcnt lgkmcnt(0)
	v_pk_add_f32 v[78:79], v[78:79], v[84:85]
	s_nop 0
	v_pk_fma_f32 v[78:79], v[78:79], s[4:5], v[70:71] op_sel_hi:[1,0,0]
	s_nop 0
	v_mul_f32_e32 v0, 0x4b800000, v79
	v_cmp_gt_f32_e64 s[0:1], s3, v79
	v_cmp_gt_f32_e32 vcc, s3, v78
	s_nop 0
	v_cndmask_b32_e64 v0, v79, v0, s[0:1]
	v_rsq_f32_e32 v0, v0
	s_nop 0
	v_mul_f32_e32 v79, 0x45800000, v0
	v_cndmask_b32_e64 v0, v0, v79, s[0:1]
	v_pk_mul_f32 v[10:11], v[10:11], v[0:1] op_sel_hi:[1,0]
	v_pk_mul_f32 v[12:13], v[12:13], v[0:1] op_sel_hi:[1,0]
	v_cvt_pk_f16_f32 v10, v10, v11
	v_cvt_pk_f16_f32 v11, v12, v13
	global_store_dwordx2 v[90:91], v[10:11], off offset:512
	v_pk_mul_f32 v[10:11], v[34:35], v[0:1] op_sel_hi:[1,0]
	v_pk_mul_f32 v[12:13], v[36:37], v[0:1] op_sel_hi:[1,0]
	v_cvt_pk_f16_f32 v10, v10, v11
	v_cvt_pk_f16_f32 v11, v12, v13
	v_pk_mul_f32 v[18:19], v[18:19], v[0:1] op_sel_hi:[1,0]
	v_pk_mul_f32 v[20:21], v[20:21], v[0:1] op_sel_hi:[1,0]
	global_store_dwordx2 v[90:91], v[10:11], off offset:1024
	v_pk_mul_f32 v[10:11], v[26:27], v[0:1] op_sel_hi:[1,0]
	v_pk_mul_f32 v[12:13], v[28:29], v[0:1] op_sel_hi:[1,0]
	v_mul_f32_e32 v0, 0x4b800000, v78
	v_cndmask_b32_e32 v0, v78, v0, vcc
	v_rsq_f32_e32 v0, v0
	v_cvt_pk_f16_f32 v10, v10, v11
	v_cvt_pk_f16_f32 v11, v12, v13
	global_store_dwordx2 v[90:91], v[10:11], off offset:1536
	v_mul_f32_e32 v10, 0x45800000, v0
	v_cvt_pk_f16_f32 v18, v18, v19
	v_cvt_pk_f16_f32 v19, v20, v21
	v_cndmask_b32_e32 v0, v0, v10, vcc
	global_store_dwordx2 v[90:91], v[18:19], off
	v_lshlrev_b64 v[10:11], 11, v[74:75]
	v_pk_mul_f32 v[12:13], v[46:47], v[0:1] op_sel_hi:[1,0]
	v_pk_mul_f32 v[18:19], v[48:49], v[0:1] op_sel_hi:[1,0]
	v_lshl_add_u64 v[10:11], v[66:67], 0, v[10:11]
	v_cvt_pk_f16_f32 v12, v12, v13
	v_cvt_pk_f16_f32 v13, v18, v19
	global_store_dwordx2 v[10:11], v[12:13], off
	v_pk_mul_f32 v[12:13], v[42:43], v[0:1] op_sel_hi:[1,0]
	v_pk_mul_f32 v[18:19], v[44:45], v[0:1] op_sel_hi:[1,0]
	v_cvt_pk_f16_f32 v12, v12, v13
	v_cvt_pk_f16_f32 v13, v18, v19
	global_store_dwordx2 v[10:11], v[12:13], off offset:512
	v_pk_mul_f32 v[12:13], v[54:55], v[0:1] op_sel_hi:[1,0]
	v_pk_mul_f32 v[18:19], v[56:57], v[0:1] op_sel_hi:[1,0]
	v_cvt_pk_f16_f32 v12, v12, v13
	v_cvt_pk_f16_f32 v13, v18, v19
	global_store_dwordx2 v[10:11], v[12:13], off offset:1024
	v_pk_mul_f32 v[12:13], v[50:51], v[0:1] op_sel_hi:[1,0]
	v_pk_mul_f32 v[18:19], v[52:53], v[0:1] op_sel_hi:[1,0]
	v_cvt_pk_f16_f32 v12, v12, v13
	v_cvt_pk_f16_f32 v13, v18, v19
	global_store_dwordx2 v[10:11], v[12:13], off offset:1536
	v_mov_b32_e32 v12, v68
	v_mov_b32_e32 v13, v76
	v_mov_b32_e32 v76, v69
	v_pk_add_f32 v[12:13], v[12:13], v[76:77]
	v_mov_b32_e32 v18, v92
	v_mov_b32_e32 v19, v80
	v_pk_add_f32 v[12:13], v[12:13], v[18:19]
	v_mov_b32_e32 v80, v93
	v_pk_add_f32 v[12:13], v[12:13], v[80:81]
	ds_bpermute_b32 v19, v224, v13
	ds_bpermute_b32 v18, v224, v12
	v_lshlrev_b64 v[10:11], 11, v[82:83]
	v_lshl_add_u64 v[10:11], v[66:67], 0, v[10:11]
	s_waitcnt lgkmcnt(0)
; DI unsigned pk2(float lo, float hi) { f32x2 v = {lo, hi}; bf2_t b = __builtin_convertvector(v, bf2_t); return __builtin_bit_cast(unsigned, b); }
; DI const bf16_t* wp(const Params& p, int l, size_t off) { return (const bf16_t*)(p.ws + OFF_WP) + (size_t)l * PW_LAYER + off; }
; template <int MODE, int MT> DI void norm_rows(const float* src, const float* src2, float* x, int d2, bf16_t* xb, const float* __restrict__ g) {
;     ...
;         for (int o = 32; o >= 1; o >>= 1)
; #pragma unroll
;             for (int q = 0; q < 4; ++q) ss[q] += __shfl_xor(ss[q], o);
; #pragma unroll
;         for (int q = 0; q < 4; ++q) {
;             const int row = wave * (MT * 4) + rb * 4 + q, grow = row + (row >= 64 ? d2 : 0);
;             const float rstd = rsqrtf(ss[q] * (1.f / DM) + 1e-6f);
; #pragma unroll
;             for (int i = 0; i < 4; ++i) {
;                 if (MODE == 0) *(f32x4*)(x + (size_t)grow * DM + i * 256 + lane * 4) = v[q][i];
;                 if (MODE == 2) { f32x4 gg = *(const f32x4*)(g + i * 256 + lane * 4); *(f32x4*)(x + (size_t)grow * DM + i * 256 + lane * 4) = v[q][i] * rstd * gg; }
;                 else { u32x2 o = {pk2(v[q][i][0] * rstd, v[q][i][1] * rstd), pk2(v[q][i][2] * rstd, v[q][i][3] * rstd)}; *(u32x2*)(xb + (size_t)grow * DM + i * 256 + lane * 4) = o; }
;             }
;         }
; template <int MT> DI void phaseB(const Params& p, int l, int t, unsigned char* lds) {
;     ...
;     EpiUp<MT> eu; eu.priv = priv; eu.d2 = d2;
;     eu.halo = (float*)(ws + OFF_UHALO) + (size_t)t * 2 * DFF2;
;     eu.pconv = t == NTILE - 1 ? p.out + O_PCONV + (size_t)l * 2 * DFF2 : nullptr;
;     eu.sconv = p.out + O_SCONV + ((size_t)l * 8 + 2 * t) * 2 * DFF2;
;     gemm64<1024, MT>(xb, DM, d2, wp(p, l, PW_UP), DFF2 / UW, lds, eu);
	v_pk_add_f32 v[12:13], v[12:13], v[18:19]
	ds_bpermute_b32 v19, v228, v13
	ds_bpermute_b32 v18, v228, v12
	s_waitcnt lgkmcnt(0)
	v_pk_add_f32 v[12:13], v[12:13], v[18:19]
	ds_bpermute_b32 v19, v227, v13
	ds_bpermute_b32 v18, v227, v12
	s_waitcnt lgkmcnt(0)
	v_pk_add_f32 v[12:13], v[12:13], v[18:19]
	ds_bpermute_b32 v19, v226, v13
	ds_bpermute_b32 v18, v226, v12
	s_waitcnt lgkmcnt(0)
	v_pk_add_f32 v[12:13], v[12:13], v[18:19]
	ds_bpermute_b32 v19, v225, v13
	ds_bpermute_b32 v18, v225, v12
	s_waitcnt lgkmcnt(0)
	v_pk_add_f32 v[12:13], v[12:13], v[18:19]
	ds_bpermute_b32 v19, v223, v13
	ds_bpermute_b32 v18, v223, v12
	s_waitcnt lgkmcnt(0)
	v_pk_add_f32 v[12:13], v[12:13], v[18:19]
	s_nop 0
	v_pk_fma_f32 v[12:13], v[12:13], s[4:5], v[70:71] op_sel_hi:[1,0,0]
	s_nop 0
	v_mul_f32_e32 v0, 0x4b800000, v13
	v_cmp_gt_f32_e64 s[0:1], s3, v13
	v_cmp_gt_f32_e32 vcc, s3, v12
	v_readlane_b32 s3, v252, 45
	v_cndmask_b32_e64 v0, v13, v0, s[0:1]
	v_rsq_f32_e32 v0, v0
	s_nop 0
	v_mul_f32_e32 v13, 0x45800000, v0
	v_cndmask_b32_e64 v0, v0, v13, s[0:1]
	v_pk_mul_f32 v[2:3], v[2:3], v[0:1] op_sel_hi:[1,0]
	v_pk_mul_f32 v[4:5], v[4:5], v[0:1] op_sel_hi:[1,0]
	v_cvt_pk_f16_f32 v2, v2, v3
	v_cvt_pk_f16_f32 v3, v4, v5
	global_store_dwordx2 v[10:11], v[2:3], off offset:512
	v_pk_mul_f32 v[2:3], v[22:23], v[0:1] op_sel_hi:[1,0]
	v_pk_mul_f32 v[4:5], v[24:25], v[0:1] op_sel_hi:[1,0]
	v_cvt_pk_f16_f32 v2, v2, v3
	v_cvt_pk_f16_f32 v3, v4, v5
	v_pk_mul_f32 v[6:7], v[6:7], v[0:1] op_sel_hi:[1,0]
	v_pk_mul_f32 v[8:9], v[8:9], v[0:1] op_sel_hi:[1,0]
	global_store_dwordx2 v[10:11], v[2:3], off offset:1024
	v_pk_mul_f32 v[2:3], v[14:15], v[0:1] op_sel_hi:[1,0]
	v_pk_mul_f32 v[4:5], v[16:17], v[0:1] op_sel_hi:[1,0]
	v_mul_f32_e32 v0, 0x4b800000, v12
	v_cndmask_b32_e32 v0, v12, v0, vcc
	v_rsq_f32_e32 v0, v0
	v_cvt_pk_f16_f32 v2, v2, v3
	v_cvt_pk_f16_f32 v3, v4, v5
	global_store_dwordx2 v[10:11], v[2:3], off offset:1536
	v_mul_f32_e32 v2, 0x45800000, v0
	v_cvt_pk_f16_f32 v6, v6, v7
	v_cvt_pk_f16_f32 v7, v8, v9
	v_cndmask_b32_e32 v0, v0, v2, vcc
	global_store_dwordx2 v[10:11], v[6:7], off
	v_lshlrev_b64 v[2:3], 11, v[72:73]
	v_pk_mul_f32 v[4:5], v[38:39], v[0:1] op_sel_hi:[1,0]
	v_pk_mul_f32 v[6:7], v[40:41], v[0:1] op_sel_hi:[1,0]
	v_lshl_add_u64 v[2:3], v[66:67], 0, v[2:3]
	v_cvt_pk_f16_f32 v4, v4, v5
	v_cvt_pk_f16_f32 v5, v6, v7
	global_store_dwordx2 v[2:3], v[4:5], off
	v_pk_mul_f32 v[4:5], v[30:31], v[0:1] op_sel_hi:[1,0]
	v_pk_mul_f32 v[6:7], v[32:33], v[0:1] op_sel_hi:[1,0]
	v_cvt_pk_f16_f32 v4, v4, v5
	v_cvt_pk_f16_f32 v5, v6, v7
	global_store_dwordx2 v[2:3], v[4:5], off offset:512
	v_pk_mul_f32 v[4:5], v[62:63], v[0:1] op_sel_hi:[1,0]
	v_pk_mul_f32 v[6:7], v[64:65], v[0:1] op_sel_hi:[1,0]
	v_cvt_pk_f16_f32 v4, v4, v5
	v_cvt_pk_f16_f32 v5, v6, v7
	s_mul_i32 s1, s73, 0xb000
	global_store_dwordx2 v[2:3], v[4:5], off offset:1024
	v_pk_mul_f32 v[4:5], v[58:59], v[0:1] op_sel_hi:[1,0]
	v_pk_mul_f32 v[6:7], v[60:61], v[0:1] op_sel_hi:[1,0]
	s_mul_hi_i32 s0, s73, 0xb000
	s_add_u32 s8, s3, s1
	v_readlane_b32 s1, v252, 46
	v_cvt_pk_f16_f32 v4, v4, v5
	v_cvt_pk_f16_f32 v5, v6, v7
	s_addc_u32 s9, s1, s0
	s_mul_hi_i32 s0, s74, 0xb000
	s_mul_i32 s74, s74, 0xb000
	v_readlane_b32 s1, v255, 46
	v_mov_b32_e32 v0, v176
	global_store_dwordx2 v[2:3], v[4:5], off offset:1536
	s_add_u32 s28, s1, s74
	v_readlane_b32 s1, v255, 47
	s_addc_u32 s29, s1, s0
	v_lshlrev_b32_e32 v5, 3, v0
	v_and_b32_e32 v2, 63, v0
	v_readlane_b32 s0, v255, 44
	v_and_b32_e32 v10, 0x78, v5
	v_lshlrev_b32_e32 v5, 4, v0
	v_lshlrev_b32_e32 v2, 4, v2
	v_mov_b32_e32 v3, v1
	v_readlane_b32 s1, v255, 45
	v_and_b32_e32 v224, 0xf0, v5
	v_lshrrev_b32_e32 v5, 1, v0
	v_and_b32_e32 v4, 31, v0
	v_lshl_add_u64 v[156:157], s[0:1], 0, v[2:3]
	v_and_b32_e32 v5, 16, v5
	s_movk_i32 s0, 0x110
	v_ashrrev_i32_e32 v11, 4, v0
	v_mad_u32_u24 v225, v4, s0, v5
	v_lshl_or_b32 v4, v11, 10, v10
	v_ashrrev_i32_e32 v5, 31, v4
	v_lshl_add_u64 v[158:159], v[4:5], 1, s[34:35]
	v_add_u32_e32 v5, 0x200, v0
	v_ashrrev_i32_e32 v5, 4, v5
	v_ashrrev_i32_e32 v223, 6, v0
	v_lshl_or_b32 v6, v5, 10, v10
	v_add_u32_e32 v0, 0x400, v0
	v_ashrrev_i32_e32 v7, 31, v6
	v_ashrrev_i32_e32 v0, 4, v0
	v_lshl_add_u64 v[160:161], v[6:7], 1, s[34:35]
	v_add_u32_e32 v7, s24, v0
	v_mul_lo_u32 v226, v11, s0
	v_mul_lo_u32 v227, v5, s0
	v_mul_lo_u32 v228, v0, s0
	v_readlane_b32 s0, v255, 23
	v_lshl_or_b32 v8, v7, 10, v10
	v_readlane_b32 s1, v255, 24
	v_ashrrev_i32_e32 v9, 31, v8
	v_add_lshl_u32 v0, v0, s55, 10
	v_lshl_add_u64 v[164:165], s[0:1], 0, v[2:3]
	s_movk_i32 s0, 0x80
	v_lshl_add_u64 v[162:163], v[8:9], 1, s[34:35]
	v_or_b32_e32 v229, 0x80, v4
	v_or3_b32 v230, v0, v10, s0
	v_or_b32_e32 v231, 0x80, v6
	v_mov_b32_e32 v232, v223
	s_branch .LBB0_459

; #define MFMA32(a, b, c) __builtin_amdgcn_mfma_f32_32x32x16_f16((a), (b), (c), 0, 0, 0)
; DI int otid() { int t = threadIdx.x; asm volatile("" : "+v"(t)); return t; }
; DI bf16_t cv1(float x) { return (bf16_t)(pk2(x, 0.f) & 0xffffu); }
; DI float bf2f(bf16_t v) { return (float)__builtin_bit_cast(_Float16, v); }
; DI int crow(int i, int h) { return (i & 3) + 8 * (i >> 2) + 4 * h; }
; template <int K, class Epi>
; DI void gemm64_res(const bf16_t* A, int lda, const bf16_t* Wp, int NU, unsigned char* lds, const Epi& epi) {
;     ...
;         for (int kk = 0; kk < KS; kk += PD) {
; #pragma unroll
;             for (int s = 0; s < PD; ++s) {
;                 const int ks = kk + s, ksr = (ks + rot) & (KS - 1);
;                 const bf16x8 a0 = *(const bf16x8*)(ab + ksr * 32), a1 = *(const bf16x8*)(ab + 32 * LD + ksr * 32);
; #pragma unroll
;                 for (int j = 0; j < NT; ++j) { acc[0][j] = MFMA32(a0, __builtin_bit_cast(bf16x8, bq[s][j]), acc[0][j]); acc[1][j] = MFMA32(a1, __builtin_bit_cast(bf16x8, bq[s][j]), acc[1][j]); }
;                 int nk = ks + PD; nk = nk < KS ? nk : KS - 1; nk = (nk + rot) & (KS - 1);
; #pragma unroll
;                 for (int j = 0; j < NT; ++j) bq[s][j] = bp[(size_t)nk * kstr + j * 64];
;             }
;     DI void operator()(int unit, const f32x16 (&acc)[MT][NT]) const {
;         const int lane = otid() & 63, r = lane & 31, h = lane >> 5;
; #pragma unroll
;         for (int mi = 0; mi < MT; ++mi)
; #pragma unroll
;             for (int nj = 0; nj < NT; ++nj)
; #pragma unroll
;                 for (int i = 0; i < 16; ++i) {
;                     bf16_t* rowp = priv + (mi * 32 + crow(i, h) + (mi == 2 ? d2 : 0)) * PRIVW; const int c = unit * UW + nj * 32 + r;
;                     float v = bf2f(rowp[gcol + c]) * acc[mi][nj][i];
;                     if (SECOND) v += bf2f(rowp[PC_M + c]);
;                     rowp[PC_M + c] = cv1(v);
.LBB0_506:
	s_and_b32 s7, s7, 0xf800
	s_lshl_b32 s64, s7, 4
	s_and_b32 s6, s6, 0xf800
	v_lshl_add_u64 v[98:99], v[68:69], 0, s[64:65]
	s_lshl_b32 s64, s6, 4
	s_and_b32 s5, s5, 0xf800
	v_lshl_add_u64 v[90:91], v[68:69], 0, s[64:65]
	s_lshl_b32 s64, s5, 4
	s_and_b32 s5, s4, 0xf800
	v_lshl_add_u64 v[82:83], v[68:69], 0, s[64:65]
	s_lshl_b32 s64, s5, 4
	v_lshl_add_u64 v[74:75], v[68:69], 0, s[64:65]
	global_load_dwordx4 v[70:73], v[74:75], off
	s_nop 0
	global_load_dwordx4 v[74:77], v[74:75], off offset:1024
	s_nop 0
	global_load_dwordx4 v[78:81], v[82:83], off
	s_nop 0
	global_load_dwordx4 v[82:85], v[82:83], off offset:1024
	s_nop 0
	global_load_dwordx4 v[86:89], v[90:91], off
	s_nop 0
	global_load_dwordx4 v[90:93], v[90:91], off offset:1024
	s_nop 0
	global_load_dwordx4 v[94:97], v[98:99], off
	s_nop 0
	global_load_dwordx4 v[98:101], v[98:99], off offset:1024
	s_and_b32 s5, s3, 0x3e0
	v_add_u32_e32 v0, s5, v124
	ds_read_b128 v[102:105], v0
	ds_read_b128 v[106:109], v0 offset:33280
	s_add_i32 s6, s3, 32
	s_and_b32 s6, s6, 0x3e0
	v_add_u32_e32 v0, s6, v124
	s_add_i32 s7, s3, 64
	s_and_b32 s7, s7, 0x3e0
	s_add_i32 s8, s3, 0x60
	s_and_b32 s8, s8, 0x3e0
	s_add_i32 s5, s2, 5
	s_add_i32 s6, s2, 6
	s_min_u32 s5, s5, 27
	s_min_u32 s6, s6, 27
	s_add_i32 s5, s5, s33
	s_add_i32 s6, s6, s33
	s_lshl_b32 s5, s5, 11
	s_lshl_b32 s6, s6, 11
	s_addk_i32 s4, 0x2000
	s_addk_i32 s3, 0x80
	s_waitcnt vmcnt(7) lgkmcnt(1)
	v_mfma_f32_32x32x16_f16 v[50:65], v[102:105], v[70:73], v[50:65]
	s_waitcnt lgkmcnt(0)
	v_mfma_f32_32x32x16_f16 v[18:33], v[106:109], v[70:73], v[18:33]
	s_waitcnt vmcnt(6)
	v_mfma_f32_32x32x16_f16 v[34:49], v[102:105], v[74:77], v[34:49]
	v_mfma_f32_32x32x16_f16 v[2:17], v[106:109], v[74:77], v[2:17]
	ds_read_b128 v[70:73], v0
	ds_read_b128 v[74:77], v0 offset:33280
	v_add_u32_e32 v0, s7, v124
	s_add_i32 s7, s2, 7
	s_min_u32 s7, s7, 27
	s_add_i32 s7, s7, s33
	s_lshl_b32 s7, s7, 11
	s_add_i32 s2, s2, 4
	s_waitcnt vmcnt(5) lgkmcnt(1)
	v_mfma_f32_32x32x16_f16 v[50:65], v[70:73], v[78:81], v[50:65]
	s_cmp_lt_u32 s2, 28
	s_waitcnt lgkmcnt(0)
	v_mfma_f32_32x32x16_f16 v[18:33], v[74:77], v[78:81], v[18:33]
	s_waitcnt vmcnt(4)
	v_mfma_f32_32x32x16_f16 v[34:49], v[70:73], v[82:85], v[34:49]
	v_mfma_f32_32x32x16_f16 v[2:17], v[74:77], v[82:85], v[2:17]
	ds_read_b128 v[70:73], v0
	ds_read_b128 v[74:77], v0 offset:33280
	v_add_u32_e32 v0, s8, v124
	s_waitcnt vmcnt(3) lgkmcnt(1)
	v_mfma_f32_32x32x16_f16 v[50:65], v[70:73], v[86:89], v[50:65]
	s_waitcnt lgkmcnt(0)
	v_mfma_f32_32x32x16_f16 v[18:33], v[74:77], v[86:89], v[18:33]
	s_waitcnt vmcnt(2)
	v_mfma_f32_32x32x16_f16 v[34:49], v[70:73], v[90:93], v[34:49]
	v_mfma_f32_32x32x16_f16 v[2:17], v[74:77], v[90:93], v[2:17]
	ds_read_b128 v[70:73], v0
	ds_read_b128 v[74:77], v0 offset:33280
	s_waitcnt vmcnt(1) lgkmcnt(1)
	v_mfma_f32_32x32x16_f16 v[50:65], v[70:73], v[94:97], v[50:65]
	s_waitcnt lgkmcnt(0)
	v_mfma_f32_32x32x16_f16 v[18:33], v[74:77], v[94:97], v[18:33]
	s_waitcnt vmcnt(0)
	v_mfma_f32_32x32x16_f16 v[34:49], v[70:73], v[98:101], v[34:49]
	v_mfma_f32_32x32x16_f16 v[2:17], v[74:77], v[98:101], v[2:17]
	s_cbranch_scc1 .LBB0_506
	s_waitcnt vmcnt(0)
	v_and_b32_e32 v68, 31, v176
	v_lshrrev_b32_e32 v69, 3, v176
	v_and_b32_e32 v69, 4, v69
	v_mul_u32_u24_e32 v69, 0x2c00, v69
	v_lshl_add_u32 v70, v68, 1, v69
	v_lshl_add_u32 v70, s1, 7, v70
	v_add_u32_e32 v71, 0x1400, v70
	global_load_ushort v87, v71, s[34:35] offset:-3072
	global_load_ushort v88, v71, s[34:35] offset:-3008
	v_add_u32_e32 v72, 0x4000, v70
	global_load_ushort v89, v72, s[34:35] offset:-3072
	global_load_ushort v90, v72, s[34:35] offset:-3008
	v_add_u32_e32 v73, 0x6c00, v70
	global_load_ushort v91, v73, s[34:35] offset:-3072
	global_load_ushort v92, v73, s[34:35] offset:-3008
	v_add_u32_e32 v74, 0x9800, v70
	global_load_ushort v93, v74, s[34:35] offset:-3072
	global_load_ushort v94, v74, s[34:35] offset:-3008
	v_add_u32_e32 v75, 0x17400, v70
	global_load_ushort v95, v75, s[34:35] offset:-3072
	global_load_ushort v96, v75, s[34:35] offset:-3008
	v_add_u32_e32 v76, 0x1a000, v70
	global_load_ushort v97, v76, s[34:35] offset:-3072
	global_load_ushort v98, v76, s[34:35] offset:-3008
	v_add_u32_e32 v77, 0x1cc00, v70
	global_load_ushort v99, v77, s[34:35] offset:-3072
	global_load_ushort v100, v77, s[34:35] offset:-3008
	v_add_u32_e32 v78, 0x1f800, v70
	global_load_ushort v101, v78, s[34:35] offset:-3072
	global_load_ushort v102, v78, s[34:35] offset:-3008
	v_add_u32_e32 v79, 0x2d400, v70
	global_load_ushort v103, v79, s[34:35] offset:-3072
	global_load_ushort v104, v79, s[34:35] offset:-3008
	v_add_u32_e32 v80, 0x30000, v70
	global_load_ushort v105, v80, s[34:35] offset:-3072
	global_load_ushort v106, v80, s[34:35] offset:-3008
	v_add_u32_e32 v81, 0x32c00, v70
	global_load_ushort v107, v81, s[34:35] offset:-3072
	global_load_ushort v108, v81, s[34:35] offset:-3008
	v_add_u32_e32 v82, 0x35800, v70
	global_load_ushort v109, v82, s[34:35] offset:-3072
	global_load_ushort v110, v82, s[34:35] offset:-3008
	v_add_u32_e32 v83, 0x43400, v70
	global_load_ushort v111, v83, s[34:35] offset:-3072
	global_load_ushort v112, v83, s[34:35] offset:-3008
	v_add_u32_e32 v84, 0x46000, v70
	global_load_ushort v113, v84, s[34:35] offset:-3072
	global_load_ushort v114, v84, s[34:35] offset:-3008
	v_add_u32_e32 v85, 0x48c00, v70
	global_load_ushort v116, v85, s[34:35] offset:-3072
	global_load_ushort v117, v85, s[34:35] offset:-3008
	v_add_u32_e32 v86, 0x4b800, v70
	global_load_ushort v118, v86, s[34:35] offset:-3072
	global_load_ushort v119, v86, s[34:35] offset:-3008
	s_waitcnt vmcnt(0)
; DI int otid() { int t = threadIdx.x; asm volatile("" : "+v"(t)); return t; }
; DI bf16_t cv1(float x) { return (bf16_t)(pk2(x, 0.f) & 0xffffu); }
; DI float bf2f(bf16_t v) { return (float)__builtin_bit_cast(_Float16, v); }
; DI int crow(int i, int h) { return (i & 3) + 8 * (i >> 2) + 4 * h; }
;     DI void operator()(int unit, const f32x16 (&acc)[MT][NT]) const {
;         const int lane = otid() & 63, r = lane & 31, h = lane >> 5;
; #pragma unroll
;         for (int mi = 0; mi < MT; ++mi)
; #pragma unroll
;             for (int nj = 0; nj < NT; ++nj)
; #pragma unroll
;                 for (int i = 0; i < 16; ++i) {
;                     bf16_t* rowp = priv + (mi * 32 + crow(i, h) + (mi == 2 ? d2 : 0)) * PRIVW; const int c = unit * UW + nj * 32 + r;
;                     float v = bf2f(rowp[gcol + c]) * acc[mi][nj][i];
;                     if (SECOND) v += bf2f(rowp[PC_M + c]);
;                     rowp[PC_M + c] = cv1(v);
;                     if (i == 15) __builtin_amdgcn_sched_barrier(0);
;                 }
;     }
	v_fma_mixlo_f16 v87, v50, v87, 0 op_sel_hi:[0,1,0]
	global_store_short v71, v87, s[34:35] offset:3072
	v_fma_mixlo_f16 v88, v34, v88, 0 op_sel_hi:[0,1,0]
	global_store_short v71, v88, s[34:35] offset:3136
	v_fma_mixlo_f16 v89, v51, v89, 0 op_sel_hi:[0,1,0]
	global_store_short v72, v89, s[34:35] offset:3072
	v_fma_mixlo_f16 v90, v35, v90, 0 op_sel_hi:[0,1,0]
	global_store_short v72, v90, s[34:35] offset:3136
	v_fma_mixlo_f16 v91, v52, v91, 0 op_sel_hi:[0,1,0]
	global_store_short v73, v91, s[34:35] offset:3072
	v_fma_mixlo_f16 v92, v36, v92, 0 op_sel_hi:[0,1,0]
	global_store_short v73, v92, s[34:35] offset:3136
	v_fma_mixlo_f16 v93, v53, v93, 0 op_sel_hi:[0,1,0]
	global_store_short v74, v93, s[34:35] offset:3072
	v_fma_mixlo_f16 v94, v37, v94, 0 op_sel_hi:[0,1,0]
	global_store_short v74, v94, s[34:35] offset:3136
	v_fma_mixlo_f16 v95, v54, v95, 0 op_sel_hi:[0,1,0]
	global_store_short v75, v95, s[34:35] offset:3072
	v_fma_mixlo_f16 v96, v38, v96, 0 op_sel_hi:[0,1,0]
	global_store_short v75, v96, s[34:35] offset:3136
	v_fma_mixlo_f16 v97, v55, v97, 0 op_sel_hi:[0,1,0]
	global_store_short v76, v97, s[34:35] offset:3072
	v_fma_mixlo_f16 v98, v39, v98, 0 op_sel_hi:[0,1,0]
	global_store_short v76, v98, s[34:35] offset:3136
	v_fma_mixlo_f16 v99, v56, v99, 0 op_sel_hi:[0,1,0]
	global_store_short v77, v99, s[34:35] offset:3072
	v_fma_mixlo_f16 v100, v40, v100, 0 op_sel_hi:[0,1,0]
	global_store_short v77, v100, s[34:35] offset:3136
	v_fma_mixlo_f16 v101, v57, v101, 0 op_sel_hi:[0,1,0]
	global_store_short v78, v101, s[34:35] offset:3072
	v_fma_mixlo_f16 v102, v41, v102, 0 op_sel_hi:[0,1,0]
	global_store_short v78, v102, s[34:35] offset:3136
	v_fma_mixlo_f16 v103, v58, v103, 0 op_sel_hi:[0,1,0]
	global_store_short v79, v103, s[34:35] offset:3072
	v_fma_mixlo_f16 v104, v42, v104, 0 op_sel_hi:[0,1,0]
	global_store_short v79, v104, s[34:35] offset:3136
	v_fma_mixlo_f16 v105, v59, v105, 0 op_sel_hi:[0,1,0]
	global_store_short v80, v105, s[34:35] offset:3072
	v_fma_mixlo_f16 v106, v43, v106, 0 op_sel_hi:[0,1,0]
	global_store_short v80, v106, s[34:35] offset:3136
	v_fma_mixlo_f16 v107, v60, v107, 0 op_sel_hi:[0,1,0]
	global_store_short v81, v107, s[34:35] offset:3072
	v_fma_mixlo_f16 v108, v44, v108, 0 op_sel_hi:[0,1,0]
	global_store_short v81, v108, s[34:35] offset:3136
	v_fma_mixlo_f16 v109, v61, v109, 0 op_sel_hi:[0,1,0]
	global_store_short v82, v109, s[34:35] offset:3072
	v_fma_mixlo_f16 v110, v45, v110, 0 op_sel_hi:[0,1,0]
	global_store_short v82, v110, s[34:35] offset:3136
	v_fma_mixlo_f16 v111, v62, v111, 0 op_sel_hi:[0,1,0]
	global_store_short v83, v111, s[34:35] offset:3072
	v_fma_mixlo_f16 v112, v46, v112, 0 op_sel_hi:[0,1,0]
	global_store_short v83, v112, s[34:35] offset:3136
	v_fma_mixlo_f16 v113, v63, v113, 0 op_sel_hi:[0,1,0]
	global_store_short v84, v113, s[34:35] offset:3072
	v_fma_mixlo_f16 v114, v47, v114, 0 op_sel_hi:[0,1,0]
	global_store_short v84, v114, s[34:35] offset:3136
	v_fma_mixlo_f16 v116, v64, v116, 0 op_sel_hi:[0,1,0]
	global_store_short v85, v116, s[34:35] offset:3072
	v_fma_mixlo_f16 v117, v48, v117, 0 op_sel_hi:[0,1,0]
	global_store_short v85, v117, s[34:35] offset:3136
	v_fma_mixlo_f16 v118, v65, v118, 0 op_sel_hi:[0,1,0]
	global_store_short v86, v118, s[34:35] offset:3072
	v_fma_mixlo_f16 v119, v49, v119, 0 op_sel_hi:[0,1,0]
	global_store_short v86, v119, s[34:35] offset:3136
	v_add_u32_e32 v71, 0x59400, v70
	global_load_ushort v87, v71, s[34:35] offset:-3072
	global_load_ushort v88, v71, s[34:35] offset:-3008
	v_add_u32_e32 v72, 0x5c000, v70
	global_load_ushort v89, v72, s[34:35] offset:-3072
	global_load_ushort v90, v72, s[34:35] offset:-3008
	v_add_u32_e32 v73, 0x5ec00, v70
	global_load_ushort v91, v73, s[34:35] offset:-3072
	global_load_ushort v92, v73, s[34:35] offset:-3008
	v_add_u32_e32 v74, 0x61800, v70
	global_load_ushort v93, v74, s[34:35] offset:-3072
	global_load_ushort v94, v74, s[34:35] offset:-3008
	v_add_u32_e32 v75, 0x6f400, v70
	global_load_ushort v95, v75, s[34:35] offset:-3072
	global_load_ushort v96, v75, s[34:35] offset:-3008
	v_add_u32_e32 v76, 0x72000, v70
	global_load_ushort v97, v76, s[34:35] offset:-3072
	global_load_ushort v98, v76, s[34:35] offset:-3008
	v_add_u32_e32 v77, 0x74c00, v70
	global_load_ushort v99, v77, s[34:35] offset:-3072
	global_load_ushort v100, v77, s[34:35] offset:-3008
	v_add_u32_e32 v78, 0x77800, v70
	global_load_ushort v101, v78, s[34:35] offset:-3072
	global_load_ushort v102, v78, s[34:35] offset:-3008
	v_add_u32_e32 v79, 0x85400, v70
	global_load_ushort v103, v79, s[34:35] offset:-3072
	global_load_ushort v104, v79, s[34:35] offset:-3008
	v_add_u32_e32 v80, 0x88000, v70
	global_load_ushort v105, v80, s[34:35] offset:-3072
	global_load_ushort v106, v80, s[34:35] offset:-3008
	v_add_u32_e32 v81, 0x8ac00, v70
	global_load_ushort v107, v81, s[34:35] offset:-3072
	global_load_ushort v108, v81, s[34:35] offset:-3008
	v_add_u32_e32 v82, 0x8d800, v70
	global_load_ushort v109, v82, s[34:35] offset:-3072
	global_load_ushort v110, v82, s[34:35] offset:-3008
	v_add_u32_e32 v83, 0x9b400, v70
	global_load_ushort v111, v83, s[34:35] offset:-3072
	global_load_ushort v112, v83, s[34:35] offset:-3008
	v_add_u32_e32 v84, 0x9e000, v70
	global_load_ushort v113, v84, s[34:35] offset:-3072
	global_load_ushort v114, v84, s[34:35] offset:-3008
	v_add_u32_e32 v85, 0xa0c00, v70
	global_load_ushort v116, v85, s[34:35] offset:-3072
	global_load_ushort v117, v85, s[34:35] offset:-3008
	v_add_u32_e32 v86, 0xa3800, v70
	global_load_ushort v118, v86, s[34:35] offset:-3072
	global_load_ushort v119, v86, s[34:35] offset:-3008
	s_waitcnt vmcnt(0)
; #define MFMA32(a, b, c) __builtin_amdgcn_mfma_f32_32x32x16_f16((a), (b), (c), 0, 0, 0)
; DI bf16_t cv1(float x) { return (bf16_t)(pk2(x, 0.f) & 0xffffu); }
; template <int K, class Epi>
; DI void gemm64_res(const bf16_t* A, int lda, const bf16_t* Wp, int NU, unsigned char* lds, const Epi& epi) {
;     ...
;     for (int unit = wave; unit < NU; unit += NWAVE) {
;         const u32x4* bp = Bw + (size_t)(unit * NT) * 64 + lane;
;         f32x16 acc[2][NT];
; #pragma unroll
;         for (int mi = 0; mi < 2; ++mi)
; #pragma unroll
;             for (int nj = 0; nj < NT; ++nj)
; #pragma unroll
;                 for (int i = 0; i < 16; ++i) acc[mi][nj][i] = 0.f;
;         u32x4 bq[PD][NT];
; #pragma unroll
;         for (int s = 0; s < PD; ++s)
; #pragma unroll
;             for (int j = 0; j < NT; ++j) bq[s][j] = bp[(size_t)((s + rot) & (KS - 1)) * kstr + j * 64];
; #pragma unroll 1
;         for (int kk = 0; kk < KS; kk += PD) {
; #pragma unroll
;             for (int s = 0; s < PD; ++s) {
;                 const int ks = kk + s, ksr = (ks + rot) & (KS - 1);
;                 const bf16x8 a0 = *(const bf16x8*)(ab + ksr * 32), a1 = *(const bf16x8*)(ab + 32 * LD + ksr * 32);
; #pragma unroll
;                 for (int j = 0; j < NT; ++j) { acc[0][j] = MFMA32(a0, __builtin_bit_cast(bf16x8, bq[s][j]), acc[0][j]); acc[1][j] = MFMA32(a1, __builtin_bit_cast(bf16x8, bq[s][j]), acc[1][j]); }
;                 int nk = ks + PD; nk = nk < KS ? nk : KS - 1; nk = (nk + rot) & (KS - 1);
; #pragma unroll
;                 for (int j = 0; j < NT; ++j) bq[s][j] = bp[(size_t)nk * kstr + j * 64];
;             }
;         }
;         epi(unit, acc);
;     }
;     DI void operator()(int unit, const f32x16 (&acc)[MT][NT]) const {
;         const int lane = otid() & 63, r = lane & 31, h = lane >> 5;
; #pragma unroll
;         for (int mi = 0; mi < MT; ++mi)
; #pragma unroll
;             for (int nj = 0; nj < NT; ++nj)
; #pragma unroll
;                 for (int i = 0; i < 16; ++i) {
;                     bf16_t* rowp = priv + (mi * 32 + crow(i, h) + (mi == 2 ? d2 : 0)) * PRIVW; const int c = unit * UW + nj * 32 + r;
;                     float v = bf2f(rowp[gcol + c]) * acc[mi][nj][i];
;                     if (SECOND) v += bf2f(rowp[PC_M + c]);
;                     rowp[PC_M + c] = cv1(v);
;                     if (i == 15) __builtin_amdgcn_sched_barrier(0);
;                 }
;     }
	v_fma_mixlo_f16 v87, v18, v87, 0 op_sel_hi:[0,1,0]
	global_store_short v71, v87, s[34:35] offset:3072
	v_fma_mixlo_f16 v88, v2, v88, 0 op_sel_hi:[0,1,0]
	global_store_short v71, v88, s[34:35] offset:3136
	v_fma_mixlo_f16 v89, v19, v89, 0 op_sel_hi:[0,1,0]
	global_store_short v72, v89, s[34:35] offset:3072
	v_fma_mixlo_f16 v90, v3, v90, 0 op_sel_hi:[0,1,0]
	global_store_short v72, v90, s[34:35] offset:3136
	v_fma_mixlo_f16 v91, v20, v91, 0 op_sel_hi:[0,1,0]
	global_store_short v73, v91, s[34:35] offset:3072
	v_fma_mixlo_f16 v92, v4, v92, 0 op_sel_hi:[0,1,0]
	global_store_short v73, v92, s[34:35] offset:3136
	v_fma_mixlo_f16 v93, v21, v93, 0 op_sel_hi:[0,1,0]
	global_store_short v74, v93, s[34:35] offset:3072
	v_fma_mixlo_f16 v94, v5, v94, 0 op_sel_hi:[0,1,0]
	global_store_short v74, v94, s[34:35] offset:3136
	v_fma_mixlo_f16 v95, v22, v95, 0 op_sel_hi:[0,1,0]
	global_store_short v75, v95, s[34:35] offset:3072
	v_fma_mixlo_f16 v96, v6, v96, 0 op_sel_hi:[0,1,0]
	global_store_short v75, v96, s[34:35] offset:3136
	v_fma_mixlo_f16 v97, v23, v97, 0 op_sel_hi:[0,1,0]
	global_store_short v76, v97, s[34:35] offset:3072
	v_fma_mixlo_f16 v98, v7, v98, 0 op_sel_hi:[0,1,0]
	global_store_short v76, v98, s[34:35] offset:3136
	v_fma_mixlo_f16 v99, v24, v99, 0 op_sel_hi:[0,1,0]
	global_store_short v77, v99, s[34:35] offset:3072
	v_fma_mixlo_f16 v100, v8, v100, 0 op_sel_hi:[0,1,0]
	global_store_short v77, v100, s[34:35] offset:3136
	v_fma_mixlo_f16 v101, v25, v101, 0 op_sel_hi:[0,1,0]
	global_store_short v78, v101, s[34:35] offset:3072
	v_fma_mixlo_f16 v102, v9, v102, 0 op_sel_hi:[0,1,0]
	global_store_short v78, v102, s[34:35] offset:3136
	v_fma_mixlo_f16 v103, v26, v103, 0 op_sel_hi:[0,1,0]
	global_store_short v79, v103, s[34:35] offset:3072
	v_fma_mixlo_f16 v104, v10, v104, 0 op_sel_hi:[0,1,0]
	global_store_short v79, v104, s[34:35] offset:3136
	v_fma_mixlo_f16 v105, v27, v105, 0 op_sel_hi:[0,1,0]
	global_store_short v80, v105, s[34:35] offset:3072
	v_fma_mixlo_f16 v106, v11, v106, 0 op_sel_hi:[0,1,0]
	global_store_short v80, v106, s[34:35] offset:3136
	v_fma_mixlo_f16 v107, v28, v107, 0 op_sel_hi:[0,1,0]
	global_store_short v81, v107, s[34:35] offset:3072
	v_fma_mixlo_f16 v108, v12, v108, 0 op_sel_hi:[0,1,0]
	global_store_short v81, v108, s[34:35] offset:3136
	v_fma_mixlo_f16 v109, v29, v109, 0 op_sel_hi:[0,1,0]
	global_store_short v82, v109, s[34:35] offset:3072
	v_fma_mixlo_f16 v110, v13, v110, 0 op_sel_hi:[0,1,0]
	global_store_short v82, v110, s[34:35] offset:3136
	v_fma_mixlo_f16 v111, v30, v111, 0 op_sel_hi:[0,1,0]
	global_store_short v83, v111, s[34:35] offset:3072
	v_fma_mixlo_f16 v112, v14, v112, 0 op_sel_hi:[0,1,0]
	global_store_short v83, v112, s[34:35] offset:3136
	v_fma_mixlo_f16 v113, v31, v113, 0 op_sel_hi:[0,1,0]
	global_store_short v84, v113, s[34:35] offset:3072
	v_fma_mixlo_f16 v114, v15, v114, 0 op_sel_hi:[0,1,0]
	global_store_short v84, v114, s[34:35] offset:3136
	v_fma_mixlo_f16 v116, v32, v116, 0 op_sel_hi:[0,1,0]
	global_store_short v85, v116, s[34:35] offset:3072
	v_fma_mixlo_f16 v117, v16, v117, 0 op_sel_hi:[0,1,0]
	global_store_short v85, v117, s[34:35] offset:3136
	v_fma_mixlo_f16 v118, v33, v118, 0 op_sel_hi:[0,1,0]
	global_store_short v86, v118, s[34:35] offset:3072
	v_fma_mixlo_f16 v119, v17, v119, 0 op_sel_hi:[0,1,0]
	global_store_short v86, v119, s[34:35] offset:3136
	s_waitcnt vmcnt(0)
	s_add_i32 s2, s1, 8
	s_cmp_lt_i32 s1, 8
	s_mov_b32 s1, s2
	s_cbranch_scc1 .LBB0_505
	s_movk_i32 s17, 0x810
	s_movk_i32 s64, 0x3fff

; #define MFMA32(a, b, c) __builtin_amdgcn_mfma_f32_32x32x16_f16((a), (b), (c), 0, 0, 0)
; DI int otid() { int t = threadIdx.x; asm volatile("" : "+v"(t)); return t; }
; DI bf16_t cv1(float x) { return (bf16_t)(pk2(x, 0.f) & 0xffffu); }
; DI float bf2f(bf16_t v) { return (float)__builtin_bit_cast(_Float16, v); }
; DI int crow(int i, int h) { return (i & 3) + 8 * (i >> 2) + 4 * h; }
; template <int K, class Epi>
; DI void gemm64_res(const bf16_t* A, int lda, const bf16_t* Wp, int NU, unsigned char* lds, const Epi& epi) {
;     ...
; #pragma unroll 1
;         for (int kk = 0; kk < KS; kk += PD) {
; #pragma unroll
;             for (int s = 0; s < PD; ++s) {
;                 const int ks = kk + s, ksr = (ks + rot) & (KS - 1);
;                 const bf16x8 a0 = *(const bf16x8*)(ab + ksr * 32), a1 = *(const bf16x8*)(ab + 32 * LD + ksr * 32);
; #pragma unroll
;                 for (int j = 0; j < NT; ++j) { acc[0][j] = MFMA32(a0, __builtin_bit_cast(bf16x8, bq[s][j]), acc[0][j]); acc[1][j] = MFMA32(a1, __builtin_bit_cast(bf16x8, bq[s][j]), acc[1][j]); }
;                 int nk = ks + PD; nk = nk < KS ? nk : KS - 1; nk = (nk + rot) & (KS - 1);
; #pragma unroll
;                 for (int j = 0; j < NT; ++j) bq[s][j] = bp[(size_t)nk * kstr + j * 64];
;             }
;         }
;     DI void operator()(int unit, const f32x16 (&acc)[MT][NT]) const {
;         const int lane = otid() & 63, r = lane & 31, h = lane >> 5;
; #pragma unroll
;         for (int mi = 0; mi < MT; ++mi)
; #pragma unroll
;             for (int nj = 0; nj < NT; ++nj)
; #pragma unroll
;                 for (int i = 0; i < 16; ++i) {
;                     bf16_t* rowp = priv + (mi * 32 + crow(i, h) + (mi == 2 ? d2 : 0)) * PRIVW; const int c = unit * UW + nj * 32 + r;
;                     float v = bf2f(rowp[gcol + c]) * acc[mi][nj][i];
;                     if (SECOND) v += bf2f(rowp[PC_M + c]);
;                     rowp[PC_M + c] = cv1(v);
;                     if (i == 15) __builtin_amdgcn_sched_barrier(0);
;                 }
;     }
.LBB0_512:
	s_and_b32 s7, s7, 0xf800
	s_lshl_b32 s64, s7, 4
	s_and_b32 s6, s6, 0xf800
	v_lshl_add_u64 v[98:99], v[68:69], 0, s[64:65]
	s_lshl_b32 s64, s6, 4
	s_and_b32 s5, s5, 0xf800
	v_lshl_add_u64 v[90:91], v[68:69], 0, s[64:65]
	s_lshl_b32 s64, s5, 4
	s_and_b32 s5, s4, 0xf800
	v_lshl_add_u64 v[82:83], v[68:69], 0, s[64:65]
	s_lshl_b32 s64, s5, 4
	v_lshl_add_u64 v[74:75], v[68:69], 0, s[64:65]
	global_load_dwordx4 v[70:73], v[74:75], off
	s_nop 0
	global_load_dwordx4 v[74:77], v[74:75], off offset:1024
	s_nop 0
	global_load_dwordx4 v[78:81], v[82:83], off
	s_nop 0
	global_load_dwordx4 v[82:85], v[82:83], off offset:1024
	s_nop 0
	global_load_dwordx4 v[86:89], v[90:91], off
	s_nop 0
	global_load_dwordx4 v[90:93], v[90:91], off offset:1024
	s_nop 0
	global_load_dwordx4 v[94:97], v[98:99], off
	s_nop 0
	global_load_dwordx4 v[98:101], v[98:99], off offset:1024
	s_and_b32 s5, s3, 0x3e0
	v_add_u32_e32 v0, s5, v128
	ds_read_b128 v[102:105], v0
	ds_read_b128 v[106:109], v0 offset:33280
	s_add_i32 s6, s3, 32
	s_and_b32 s6, s6, 0x3e0
	v_add_u32_e32 v0, s6, v128
	s_add_i32 s7, s3, 64
	s_and_b32 s7, s7, 0x3e0
	s_add_i32 s8, s3, 0x60
	s_and_b32 s8, s8, 0x3e0
	s_add_i32 s5, s2, 5
	s_add_i32 s6, s2, 6
	s_min_u32 s5, s5, 27
	s_min_u32 s6, s6, 27
	s_add_i32 s5, s5, s33
	s_add_i32 s6, s6, s33
	s_lshl_b32 s5, s5, 11
	s_lshl_b32 s6, s6, 11
	s_addk_i32 s4, 0x2000
	s_addk_i32 s3, 0x80
	s_waitcnt vmcnt(7) lgkmcnt(1)
	v_mfma_f32_32x32x16_f16 v[50:65], v[102:105], v[70:73], v[50:65]
	s_waitcnt lgkmcnt(0)
	v_mfma_f32_32x32x16_f16 v[18:33], v[106:109], v[70:73], v[18:33]
	s_waitcnt vmcnt(6)
	v_mfma_f32_32x32x16_f16 v[34:49], v[102:105], v[74:77], v[34:49]
	v_mfma_f32_32x32x16_f16 v[2:17], v[106:109], v[74:77], v[2:17]
	ds_read_b128 v[70:73], v0
	ds_read_b128 v[74:77], v0 offset:33280
	v_add_u32_e32 v0, s7, v128
	s_add_i32 s7, s2, 7
	s_min_u32 s7, s7, 27
	s_add_i32 s7, s7, s33
	s_lshl_b32 s7, s7, 11
	s_add_i32 s2, s2, 4
	s_waitcnt vmcnt(5) lgkmcnt(1)
	v_mfma_f32_32x32x16_f16 v[50:65], v[70:73], v[78:81], v[50:65]
	s_cmp_lt_u32 s2, 28
	s_waitcnt lgkmcnt(0)
	v_mfma_f32_32x32x16_f16 v[18:33], v[74:77], v[78:81], v[18:33]
	s_waitcnt vmcnt(4)
	v_mfma_f32_32x32x16_f16 v[34:49], v[70:73], v[82:85], v[34:49]
	v_mfma_f32_32x32x16_f16 v[2:17], v[74:77], v[82:85], v[2:17]
	ds_read_b128 v[70:73], v0
	ds_read_b128 v[74:77], v0 offset:33280
	v_add_u32_e32 v0, s8, v128
	s_waitcnt vmcnt(3) lgkmcnt(1)
	v_mfma_f32_32x32x16_f16 v[50:65], v[70:73], v[86:89], v[50:65]
	s_waitcnt lgkmcnt(0)
	v_mfma_f32_32x32x16_f16 v[18:33], v[74:77], v[86:89], v[18:33]
	s_waitcnt vmcnt(2)
	v_mfma_f32_32x32x16_f16 v[34:49], v[70:73], v[90:93], v[34:49]
	v_mfma_f32_32x32x16_f16 v[2:17], v[74:77], v[90:93], v[2:17]
	ds_read_b128 v[70:73], v0
	ds_read_b128 v[74:77], v0 offset:33280
	s_waitcnt vmcnt(1) lgkmcnt(1)
	v_mfma_f32_32x32x16_f16 v[50:65], v[70:73], v[94:97], v[50:65]
	s_waitcnt lgkmcnt(0)
	v_mfma_f32_32x32x16_f16 v[18:33], v[74:77], v[94:97], v[18:33]
	s_waitcnt vmcnt(0)
	v_mfma_f32_32x32x16_f16 v[34:49], v[70:73], v[98:101], v[34:49]
	v_mfma_f32_32x32x16_f16 v[2:17], v[74:77], v[98:101], v[2:17]
	s_cbranch_scc1 .LBB0_512
	s_waitcnt vmcnt(0)
	v_and_b32_e32 v68, 31, v176
	v_lshrrev_b32_e32 v69, 3, v176
	v_and_b32_e32 v69, 4, v69
	v_mul_u32_u24_e32 v69, 0x2c00, v69
	v_lshl_add_u32 v70, v68, 1, v69
	v_lshl_add_u32 v70, s1, 7, v70
	v_add_u32_e32 v71, 0x1800, v70
	global_load_ushort v87, v71, s[34:35] offset:-2048
	global_load_ushort v120, v71, s[34:35] offset:2048
	global_load_ushort v88, v71, s[34:35] offset:-1984
	global_load_ushort v121, v71, s[34:35] offset:2112
	v_add_u32_e32 v72, 0x4400, v70
	global_load_ushort v89, v72, s[34:35] offset:-2048
	global_load_ushort v122, v72, s[34:35] offset:2048
	global_load_ushort v90, v72, s[34:35] offset:-1984
	global_load_ushort v123, v72, s[34:35] offset:2112
	v_add_u32_e32 v73, 0x7000, v70
	global_load_ushort v91, v73, s[34:35] offset:-2048
	global_load_ushort v124, v73, s[34:35] offset:2048
	global_load_ushort v92, v73, s[34:35] offset:-1984
	global_load_ushort v125, v73, s[34:35] offset:2112
	v_add_u32_e32 v74, 0x9c00, v70
	global_load_ushort v93, v74, s[34:35] offset:-2048
	global_load_ushort v126, v74, s[34:35] offset:2048
	global_load_ushort v94, v74, s[34:35] offset:-1984
	global_load_ushort v127, v74, s[34:35] offset:2112
	v_add_u32_e32 v75, 0x17800, v70
	global_load_ushort v95, v75, s[34:35] offset:-2048
	global_load_ushort v129, v75, s[34:35] offset:2048
	global_load_ushort v96, v75, s[34:35] offset:-1984
	global_load_ushort v130, v75, s[34:35] offset:2112
	v_add_u32_e32 v76, 0x1a400, v70
	global_load_ushort v97, v76, s[34:35] offset:-2048
	global_load_ushort v131, v76, s[34:35] offset:2048
	global_load_ushort v98, v76, s[34:35] offset:-1984
	global_load_ushort v132, v76, s[34:35] offset:2112
	v_add_u32_e32 v77, 0x1d000, v70
	global_load_ushort v99, v77, s[34:35] offset:-2048
	global_load_ushort v133, v77, s[34:35] offset:2048
	global_load_ushort v100, v77, s[34:35] offset:-1984
	global_load_ushort v134, v77, s[34:35] offset:2112
	v_add_u32_e32 v78, 0x1fc00, v70
	global_load_ushort v101, v78, s[34:35] offset:-2048
	global_load_ushort v135, v78, s[34:35] offset:2048
	global_load_ushort v102, v78, s[34:35] offset:-1984
	global_load_ushort v136, v78, s[34:35] offset:2112
	v_add_u32_e32 v79, 0x2d800, v70
	global_load_ushort v103, v79, s[34:35] offset:-2048
	global_load_ushort v137, v79, s[34:35] offset:2048
	global_load_ushort v104, v79, s[34:35] offset:-1984
	global_load_ushort v138, v79, s[34:35] offset:2112
	v_add_u32_e32 v80, 0x30400, v70
	global_load_ushort v105, v80, s[34:35] offset:-2048
	global_load_ushort v139, v80, s[34:35] offset:2048
; DI int otid() { int t = threadIdx.x; asm volatile("" : "+v"(t)); return t; }
; DI bf16_t cv1(float x) { return (bf16_t)(pk2(x, 0.f) & 0xffffu); }
; DI float bf2f(bf16_t v) { return (float)__builtin_bit_cast(_Float16, v); }
; DI int crow(int i, int h) { return (i & 3) + 8 * (i >> 2) + 4 * h; }
;     DI void operator()(int unit, const f32x16 (&acc)[MT][NT]) const {
;         const int lane = otid() & 63, r = lane & 31, h = lane >> 5;
; #pragma unroll
;         for (int mi = 0; mi < MT; ++mi)
; #pragma unroll
;             for (int nj = 0; nj < NT; ++nj)
; #pragma unroll
;                 for (int i = 0; i < 16; ++i) {
;                     bf16_t* rowp = priv + (mi * 32 + crow(i, h) + (mi == 2 ? d2 : 0)) * PRIVW; const int c = unit * UW + nj * 32 + r;
;                     float v = bf2f(rowp[gcol + c]) * acc[mi][nj][i];
;                     if (SECOND) v += bf2f(rowp[PC_M + c]);
;                     rowp[PC_M + c] = cv1(v);
;                     if (i == 15) __builtin_amdgcn_sched_barrier(0);
;                 }
;     }
	global_load_ushort v106, v80, s[34:35] offset:-1984
	global_load_ushort v140, v80, s[34:35] offset:2112
	v_add_u32_e32 v81, 0x33000, v70
	global_load_ushort v107, v81, s[34:35] offset:-2048
	global_load_ushort v141, v81, s[34:35] offset:2048
	global_load_ushort v108, v81, s[34:35] offset:-1984
	global_load_ushort v142, v81, s[34:35] offset:2112
	v_add_u32_e32 v82, 0x35c00, v70
	global_load_ushort v109, v82, s[34:35] offset:-2048
	global_load_ushort v143, v82, s[34:35] offset:2048
	global_load_ushort v110, v82, s[34:35] offset:-1984
	global_load_ushort v144, v82, s[34:35] offset:2112
	v_add_u32_e32 v83, 0x43800, v70
	global_load_ushort v111, v83, s[34:35] offset:-2048
	global_load_ushort v145, v83, s[34:35] offset:2048
	global_load_ushort v112, v83, s[34:35] offset:-1984
	global_load_ushort v146, v83, s[34:35] offset:2112
	v_add_u32_e32 v84, 0x46400, v70
	global_load_ushort v113, v84, s[34:35] offset:-2048
	global_load_ushort v147, v84, s[34:35] offset:2048
	global_load_ushort v114, v84, s[34:35] offset:-1984
	global_load_ushort v148, v84, s[34:35] offset:2112
	v_add_u32_e32 v85, 0x49000, v70
	global_load_ushort v116, v85, s[34:35] offset:-2048
	global_load_ushort v149, v85, s[34:35] offset:2048
	global_load_ushort v117, v85, s[34:35] offset:-1984
	global_load_ushort v150, v85, s[34:35] offset:2112
	v_add_u32_e32 v86, 0x4bc00, v70
	global_load_ushort v118, v86, s[34:35] offset:-2048
	global_load_ushort v151, v86, s[34:35] offset:2048
	global_load_ushort v119, v86, s[34:35] offset:-1984
	global_load_ushort v152, v86, s[34:35] offset:2112
	s_waitcnt vmcnt(0)
	v_fma_mixlo_f16 v87, v50, v87, v120 op_sel_hi:[0,1,1]
	global_store_short v71, v87, s[34:35] offset:2048
	v_fma_mixlo_f16 v88, v34, v88, v121 op_sel_hi:[0,1,1]
	global_store_short v71, v88, s[34:35] offset:2112
	v_fma_mixlo_f16 v89, v51, v89, v122 op_sel_hi:[0,1,1]
	global_store_short v72, v89, s[34:35] offset:2048
	v_fma_mixlo_f16 v90, v35, v90, v123 op_sel_hi:[0,1,1]
	global_store_short v72, v90, s[34:35] offset:2112
	v_fma_mixlo_f16 v91, v52, v91, v124 op_sel_hi:[0,1,1]
	global_store_short v73, v91, s[34:35] offset:2048
	v_fma_mixlo_f16 v92, v36, v92, v125 op_sel_hi:[0,1,1]
	global_store_short v73, v92, s[34:35] offset:2112
	v_fma_mixlo_f16 v93, v53, v93, v126 op_sel_hi:[0,1,1]
	global_store_short v74, v93, s[34:35] offset:2048
	v_fma_mixlo_f16 v94, v37, v94, v127 op_sel_hi:[0,1,1]
	global_store_short v74, v94, s[34:35] offset:2112
	v_fma_mixlo_f16 v95, v54, v95, v129 op_sel_hi:[0,1,1]
	global_store_short v75, v95, s[34:35] offset:2048
	v_fma_mixlo_f16 v96, v38, v96, v130 op_sel_hi:[0,1,1]
	global_store_short v75, v96, s[34:35] offset:2112
	v_fma_mixlo_f16 v97, v55, v97, v131 op_sel_hi:[0,1,1]
	global_store_short v76, v97, s[34:35] offset:2048
	v_fma_mixlo_f16 v98, v39, v98, v132 op_sel_hi:[0,1,1]
	global_store_short v76, v98, s[34:35] offset:2112
	v_fma_mixlo_f16 v99, v56, v99, v133 op_sel_hi:[0,1,1]
	global_store_short v77, v99, s[34:35] offset:2048
	v_fma_mixlo_f16 v100, v40, v100, v134 op_sel_hi:[0,1,1]
	global_store_short v77, v100, s[34:35] offset:2112
	v_fma_mixlo_f16 v101, v57, v101, v135 op_sel_hi:[0,1,1]
	global_store_short v78, v101, s[34:35] offset:2048
	v_fma_mixlo_f16 v102, v41, v102, v136 op_sel_hi:[0,1,1]
	global_store_short v78, v102, s[34:35] offset:2112
	v_fma_mixlo_f16 v103, v58, v103, v137 op_sel_hi:[0,1,1]
	global_store_short v79, v103, s[34:35] offset:2048
	v_fma_mixlo_f16 v104, v42, v104, v138 op_sel_hi:[0,1,1]
	global_store_short v79, v104, s[34:35] offset:2112
	v_fma_mixlo_f16 v105, v59, v105, v139 op_sel_hi:[0,1,1]
	global_store_short v80, v105, s[34:35] offset:2048
	v_fma_mixlo_f16 v106, v43, v106, v140 op_sel_hi:[0,1,1]
	global_store_short v80, v106, s[34:35] offset:2112
	v_fma_mixlo_f16 v107, v60, v107, v141 op_sel_hi:[0,1,1]
	global_store_short v81, v107, s[34:35] offset:2048
	v_fma_mixlo_f16 v108, v44, v108, v142 op_sel_hi:[0,1,1]
	global_store_short v81, v108, s[34:35] offset:2112
	v_fma_mixlo_f16 v109, v61, v109, v143 op_sel_hi:[0,1,1]
	global_store_short v82, v109, s[34:35] offset:2048
	v_fma_mixlo_f16 v110, v45, v110, v144 op_sel_hi:[0,1,1]
	global_store_short v82, v110, s[34:35] offset:2112
	v_fma_mixlo_f16 v111, v62, v111, v145 op_sel_hi:[0,1,1]
	global_store_short v83, v111, s[34:35] offset:2048
	v_fma_mixlo_f16 v112, v46, v112, v146 op_sel_hi:[0,1,1]
	global_store_short v83, v112, s[34:35] offset:2112
	v_fma_mixlo_f16 v113, v63, v113, v147 op_sel_hi:[0,1,1]
	global_store_short v84, v113, s[34:35] offset:2048
	v_fma_mixlo_f16 v114, v47, v114, v148 op_sel_hi:[0,1,1]
	global_store_short v84, v114, s[34:35] offset:2112
	v_fma_mixlo_f16 v116, v64, v116, v149 op_sel_hi:[0,1,1]
	global_store_short v85, v116, s[34:35] offset:2048
	v_fma_mixlo_f16 v117, v48, v117, v150 op_sel_hi:[0,1,1]
	global_store_short v85, v117, s[34:35] offset:2112
	v_fma_mixlo_f16 v118, v65, v118, v151 op_sel_hi:[0,1,1]
	global_store_short v86, v118, s[34:35] offset:2048
	v_fma_mixlo_f16 v119, v49, v119, v152 op_sel_hi:[0,1,1]
	global_store_short v86, v119, s[34:35] offset:2112
	v_add_u32_e32 v71, 0x59800, v70
	global_load_ushort v87, v71, s[34:35] offset:-2048
	global_load_ushort v120, v71, s[34:35] offset:2048
	global_load_ushort v88, v71, s[34:35] offset:-1984
	global_load_ushort v121, v71, s[34:35] offset:2112
	v_add_u32_e32 v72, 0x5c400, v70
	global_load_ushort v89, v72, s[34:35] offset:-2048
	global_load_ushort v122, v72, s[34:35] offset:2048
	global_load_ushort v90, v72, s[34:35] offset:-1984
	global_load_ushort v123, v72, s[34:35] offset:2112
	v_add_u32_e32 v73, 0x5f000, v70
	global_load_ushort v91, v73, s[34:35] offset:-2048
	global_load_ushort v124, v73, s[34:35] offset:2048
; #define MFMA32(a, b, c) __builtin_amdgcn_mfma_f32_32x32x16_f16((a), (b), (c), 0, 0, 0)
; DI bf16_t cv1(float x) { return (bf16_t)(pk2(x, 0.f) & 0xffffu); }
; template <int K, class Epi>
; DI void gemm64_res(const bf16_t* A, int lda, const bf16_t* Wp, int NU, unsigned char* lds, const Epi& epi) {
;     ...
;     for (int unit = wave; unit < NU; unit += NWAVE) {
;         const u32x4* bp = Bw + (size_t)(unit * NT) * 64 + lane;
;         f32x16 acc[2][NT];
; #pragma unroll
;         for (int mi = 0; mi < 2; ++mi)
; #pragma unroll
;             for (int nj = 0; nj < NT; ++nj)
; #pragma unroll
;                 for (int i = 0; i < 16; ++i) acc[mi][nj][i] = 0.f;
;         u32x4 bq[PD][NT];
; #pragma unroll
;         for (int s = 0; s < PD; ++s)
; #pragma unroll
;             for (int j = 0; j < NT; ++j) bq[s][j] = bp[(size_t)((s + rot) & (KS - 1)) * kstr + j * 64];
; #pragma unroll 1
;         for (int kk = 0; kk < KS; kk += PD) {
; #pragma unroll
;             for (int s = 0; s < PD; ++s) {
;                 const int ks = kk + s, ksr = (ks + rot) & (KS - 1);
;                 const bf16x8 a0 = *(const bf16x8*)(ab + ksr * 32), a1 = *(const bf16x8*)(ab + 32 * LD + ksr * 32);
; #pragma unroll
;                 for (int j = 0; j < NT; ++j) { acc[0][j] = MFMA32(a0, __builtin_bit_cast(bf16x8, bq[s][j]), acc[0][j]); acc[1][j] = MFMA32(a1, __builtin_bit_cast(bf16x8, bq[s][j]), acc[1][j]); }
;                 int nk = ks + PD; nk = nk < KS ? nk : KS - 1; nk = (nk + rot) & (KS - 1);
; #pragma unroll
;                 for (int j = 0; j < NT; ++j) bq[s][j] = bp[(size_t)nk * kstr + j * 64];
;             }
;         }
;         epi(unit, acc);
;     }
;     DI void operator()(int unit, const f32x16 (&acc)[MT][NT]) const {
;         const int lane = otid() & 63, r = lane & 31, h = lane >> 5;
; #pragma unroll
;         for (int mi = 0; mi < MT; ++mi)
; #pragma unroll
;             for (int nj = 0; nj < NT; ++nj)
; #pragma unroll
;                 for (int i = 0; i < 16; ++i) {
;                     bf16_t* rowp = priv + (mi * 32 + crow(i, h) + (mi == 2 ? d2 : 0)) * PRIVW; const int c = unit * UW + nj * 32 + r;
;                     float v = bf2f(rowp[gcol + c]) * acc[mi][nj][i];
;                     if (SECOND) v += bf2f(rowp[PC_M + c]);
;                     rowp[PC_M + c] = cv1(v);
;                     if (i == 15) __builtin_amdgcn_sched_barrier(0);
;                 }
;     }
	global_load_ushort v92, v73, s[34:35] offset:-1984
	global_load_ushort v125, v73, s[34:35] offset:2112
	v_add_u32_e32 v74, 0x61c00, v70
	global_load_ushort v93, v74, s[34:35] offset:-2048
	global_load_ushort v126, v74, s[34:35] offset:2048
	global_load_ushort v94, v74, s[34:35] offset:-1984
	global_load_ushort v127, v74, s[34:35] offset:2112
	v_add_u32_e32 v75, 0x6f800, v70
	global_load_ushort v95, v75, s[34:35] offset:-2048
	global_load_ushort v129, v75, s[34:35] offset:2048
	global_load_ushort v96, v75, s[34:35] offset:-1984
	global_load_ushort v130, v75, s[34:35] offset:2112
	v_add_u32_e32 v76, 0x72400, v70
	global_load_ushort v97, v76, s[34:35] offset:-2048
	global_load_ushort v131, v76, s[34:35] offset:2048
	global_load_ushort v98, v76, s[34:35] offset:-1984
	global_load_ushort v132, v76, s[34:35] offset:2112
	v_add_u32_e32 v77, 0x75000, v70
	global_load_ushort v99, v77, s[34:35] offset:-2048
	global_load_ushort v133, v77, s[34:35] offset:2048
	global_load_ushort v100, v77, s[34:35] offset:-1984
	global_load_ushort v134, v77, s[34:35] offset:2112
	v_add_u32_e32 v78, 0x77c00, v70
	global_load_ushort v101, v78, s[34:35] offset:-2048
	global_load_ushort v135, v78, s[34:35] offset:2048
	global_load_ushort v102, v78, s[34:35] offset:-1984
	global_load_ushort v136, v78, s[34:35] offset:2112
	v_add_u32_e32 v79, 0x85800, v70
	global_load_ushort v103, v79, s[34:35] offset:-2048
	global_load_ushort v137, v79, s[34:35] offset:2048
	global_load_ushort v104, v79, s[34:35] offset:-1984
	global_load_ushort v138, v79, s[34:35] offset:2112
	v_add_u32_e32 v80, 0x88400, v70
	global_load_ushort v105, v80, s[34:35] offset:-2048
	global_load_ushort v139, v80, s[34:35] offset:2048
	global_load_ushort v106, v80, s[34:35] offset:-1984
	global_load_ushort v140, v80, s[34:35] offset:2112
	v_add_u32_e32 v81, 0x8b000, v70
	global_load_ushort v107, v81, s[34:35] offset:-2048
	global_load_ushort v141, v81, s[34:35] offset:2048
	global_load_ushort v108, v81, s[34:35] offset:-1984
	global_load_ushort v142, v81, s[34:35] offset:2112
	v_add_u32_e32 v82, 0x8dc00, v70
	global_load_ushort v109, v82, s[34:35] offset:-2048
	global_load_ushort v143, v82, s[34:35] offset:2048
	global_load_ushort v110, v82, s[34:35] offset:-1984
	global_load_ushort v144, v82, s[34:35] offset:2112
	v_add_u32_e32 v83, 0x9b800, v70
	global_load_ushort v111, v83, s[34:35] offset:-2048
	global_load_ushort v145, v83, s[34:35] offset:2048
	global_load_ushort v112, v83, s[34:35] offset:-1984
	global_load_ushort v146, v83, s[34:35] offset:2112
	v_add_u32_e32 v84, 0x9e400, v70
	global_load_ushort v113, v84, s[34:35] offset:-2048
	global_load_ushort v147, v84, s[34:35] offset:2048
	global_load_ushort v114, v84, s[34:35] offset:-1984
	global_load_ushort v148, v84, s[34:35] offset:2112
	v_add_u32_e32 v85, 0xa1000, v70
	global_load_ushort v116, v85, s[34:35] offset:-2048
	global_load_ushort v149, v85, s[34:35] offset:2048
	global_load_ushort v117, v85, s[34:35] offset:-1984
	global_load_ushort v150, v85, s[34:35] offset:2112
	v_add_u32_e32 v86, 0xa3c00, v70
	global_load_ushort v118, v86, s[34:35] offset:-2048
	global_load_ushort v151, v86, s[34:35] offset:2048
	global_load_ushort v119, v86, s[34:35] offset:-1984
	global_load_ushort v152, v86, s[34:35] offset:2112
	s_waitcnt vmcnt(0)
	v_fma_mixlo_f16 v87, v18, v87, v120 op_sel_hi:[0,1,1]
	global_store_short v71, v87, s[34:35] offset:2048
	v_fma_mixlo_f16 v88, v2, v88, v121 op_sel_hi:[0,1,1]
	global_store_short v71, v88, s[34:35] offset:2112
	v_fma_mixlo_f16 v89, v19, v89, v122 op_sel_hi:[0,1,1]
	global_store_short v72, v89, s[34:35] offset:2048
	v_fma_mixlo_f16 v90, v3, v90, v123 op_sel_hi:[0,1,1]
	global_store_short v72, v90, s[34:35] offset:2112
	v_fma_mixlo_f16 v91, v20, v91, v124 op_sel_hi:[0,1,1]
	global_store_short v73, v91, s[34:35] offset:2048
	v_fma_mixlo_f16 v92, v4, v92, v125 op_sel_hi:[0,1,1]
	global_store_short v73, v92, s[34:35] offset:2112
	v_fma_mixlo_f16 v93, v21, v93, v126 op_sel_hi:[0,1,1]
	global_store_short v74, v93, s[34:35] offset:2048
	v_fma_mixlo_f16 v94, v5, v94, v127 op_sel_hi:[0,1,1]
	global_store_short v74, v94, s[34:35] offset:2112
	v_fma_mixlo_f16 v95, v22, v95, v129 op_sel_hi:[0,1,1]
	global_store_short v75, v95, s[34:35] offset:2048
	v_fma_mixlo_f16 v96, v6, v96, v130 op_sel_hi:[0,1,1]
	global_store_short v75, v96, s[34:35] offset:2112
	v_fma_mixlo_f16 v97, v23, v97, v131 op_sel_hi:[0,1,1]
	global_store_short v76, v97, s[34:35] offset:2048
	v_fma_mixlo_f16 v98, v7, v98, v132 op_sel_hi:[0,1,1]
	global_store_short v76, v98, s[34:35] offset:2112
	v_fma_mixlo_f16 v99, v24, v99, v133 op_sel_hi:[0,1,1]
	global_store_short v77, v99, s[34:35] offset:2048
	v_fma_mixlo_f16 v100, v8, v100, v134 op_sel_hi:[0,1,1]
	global_store_short v77, v100, s[34:35] offset:2112
	v_fma_mixlo_f16 v101, v25, v101, v135 op_sel_hi:[0,1,1]
	global_store_short v78, v101, s[34:35] offset:2048
	v_fma_mixlo_f16 v102, v9, v102, v136 op_sel_hi:[0,1,1]
	global_store_short v78, v102, s[34:35] offset:2112
	v_fma_mixlo_f16 v103, v26, v103, v137 op_sel_hi:[0,1,1]
	global_store_short v79, v103, s[34:35] offset:2048
	v_fma_mixlo_f16 v104, v10, v104, v138 op_sel_hi:[0,1,1]
	global_store_short v79, v104, s[34:35] offset:2112
	v_fma_mixlo_f16 v105, v27, v105, v139 op_sel_hi:[0,1,1]
	global_store_short v80, v105, s[34:35] offset:2048
	v_fma_mixlo_f16 v106, v11, v106, v140 op_sel_hi:[0,1,1]
	global_store_short v80, v106, s[34:35] offset:2112
	v_fma_mixlo_f16 v107, v28, v107, v141 op_sel_hi:[0,1,1]
	global_store_short v81, v107, s[34:35] offset:2048
	v_fma_mixlo_f16 v108, v12, v108, v142 op_sel_hi:[0,1,1]
	global_store_short v81, v108, s[34:35] offset:2112
	v_fma_mixlo_f16 v109, v29, v109, v143 op_sel_hi:[0,1,1]
	global_store_short v82, v109, s[34:35] offset:2048
	v_fma_mixlo_f16 v110, v13, v110, v144 op_sel_hi:[0,1,1]
	global_store_short v82, v110, s[34:35] offset:2112
	v_fma_mixlo_f16 v111, v30, v111, v145 op_sel_hi:[0,1,1]
	global_store_short v83, v111, s[34:35] offset:2048
	v_fma_mixlo_f16 v112, v14, v112, v146 op_sel_hi:[0,1,1]
	global_store_short v83, v112, s[34:35] offset:2112
	v_fma_mixlo_f16 v113, v31, v113, v147 op_sel_hi:[0,1,1]
	global_store_short v84, v113, s[34:35] offset:2048
	v_fma_mixlo_f16 v114, v15, v114, v148 op_sel_hi:[0,1,1]
	global_store_short v84, v114, s[34:35] offset:2112
	v_fma_mixlo_f16 v116, v32, v116, v149 op_sel_hi:[0,1,1]
	global_store_short v85, v116, s[34:35] offset:2048
	v_fma_mixlo_f16 v117, v16, v117, v150 op_sel_hi:[0,1,1]
	global_store_short v85, v117, s[34:35] offset:2112
	v_fma_mixlo_f16 v118, v33, v118, v151 op_sel_hi:[0,1,1]
	global_store_short v86, v118, s[34:35] offset:2048
	v_fma_mixlo_f16 v119, v17, v119, v152 op_sel_hi:[0,1,1]
	global_store_short v86, v119, s[34:35] offset:2112
	s_waitcnt vmcnt(0)
	s_add_i32 s2, s1, 8
	s_cmp_lt_i32 s1, 8
	s_mov_b32 s1, s2
	s_cbranch_scc1 .LBB0_511
	s_movk_i32 s17, 0x810
	s_movk_i32 s64, 0x3fff

; #define MFMA32(a, b, c) __builtin_amdgcn_mfma_f32_32x32x16_f16((a), (b), (c), 0, 0, 0)
; DI int otid() { int t = threadIdx.x; asm volatile("" : "+v"(t)); return t; }
; DI int crow(int i, int h) { return (i & 3) + 8 * (i >> 2) + 4 * h; }
; template <int K, class Epi>
; DI void gemm64_res(const bf16_t* A, int lda, const bf16_t* Wp, int NU, unsigned char* lds, const Epi& epi) {
;     ...
; #pragma unroll 1
;         for (int kk = 0; kk < KS; kk += PD) {
; #pragma unroll
;             for (int s = 0; s < PD; ++s) {
;                 const int ks = kk + s, ksr = (ks + rot) & (KS - 1);
;                 const bf16x8 a0 = *(const bf16x8*)(ab + ksr * 32), a1 = *(const bf16x8*)(ab + 32 * LD + ksr * 32);
; #pragma unroll
;                 for (int j = 0; j < NT; ++j) { acc[0][j] = MFMA32(a0, __builtin_bit_cast(bf16x8, bq[s][j]), acc[0][j]); acc[1][j] = MFMA32(a1, __builtin_bit_cast(bf16x8, bq[s][j]), acc[1][j]); }
;                 int nk = ks + PD; nk = nk < KS ? nk : KS - 1; nk = (nk + rot) & (KS - 1);
; #pragma unroll
;                 for (int j = 0; j < NT; ++j) bq[s][j] = bp[(size_t)nk * kstr + j * 64];
;             }
;         }
;     DI void operator()(int unit, const f32x16 (&acc)[MT][NT]) const {
;         const int lane = otid() & 63, r = lane & 31, h = lane >> 5;
; #pragma unroll
;         for (int mi = 0; mi < MT; ++mi)
; #pragma unroll
;             for (int nj = 0; nj < NT; ++nj)
; #pragma unroll
;                 for (int i = 0; i < 16; ++i) { float* q = x + ((mi * 32 + crow(i, h) + (mi == 2 ? d2 : 0)) * DM + unit * UW + nj * 32 + r); *q = *q + acc[mi][nj][i]; if (i == 15) __builtin_amdgcn_sched_barrier(0); }
;     }
.LBB0_518:
	s_mov_b32 s9, s65
	v_lshl_add_u64 v[78:79], s[8:9], 4, v[68:69]
	global_load_dwordx4 v[74:77], v[78:79], off
	s_nop 0
	global_load_dwordx4 v[78:81], v[78:79], off offset:1024
	s_and_b32 s3, s31, 0x7c0
	v_add_u32_e32 v73, s3, v0
	v_add_u32_e32 v86, s3, v72
	ds_read_b128 v[82:85], v73
	ds_read_b128 v[86:89], v86
	s_mov_b32 s3, s65
	s_add_i32 s7, s31, 32
	s_waitcnt vmcnt(1) lgkmcnt(1)
	v_mfma_f32_32x32x16_f16 v[50:65], v[82:85], v[74:77], v[50:65]
	s_waitcnt lgkmcnt(0)
	v_mfma_f32_32x32x16_f16 v[18:33], v[86:89], v[74:77], v[18:33]
	v_lshl_add_u64 v[74:75], s[2:3], 4, v[68:69]
	s_and_b32 s2, s7, 0x7e0
	v_add_u32_e32 v73, s2, v0
	global_load_dwordx4 v[74:77], v[74:75], off
	s_mov_b32 s7, s65
	s_add_i32 s3, s37, 4
	s_min_u32 s8, s3, 59
	s_waitcnt vmcnt(1)
	v_mfma_f32_32x32x16_f16 v[34:49], v[82:85], v[78:81], v[34:49]
	v_add_u32_e32 v82, s2, v72
	s_add_i32 s2, s31, 64
	s_and_b32 s2, s2, 0x7c0
	s_add_i32 s8, s8, s80
	s_lshl_b32 s8, s8, 11
	s_and_b32 s8, s8, 0x1f800
	v_mfma_f32_32x32x16_f16 v[2:17], v[86:89], v[78:81], v[2:17]
	ds_read_b128 v[78:81], v73
	ds_read_b128 v[82:85], v82
	global_load_dwordx4 v[86:89], v[70:71], off
	v_lshl_add_u64 v[70:71], s[6:7], 4, v[68:69]
	s_add_i32 s6, s37, 6
	s_add_i32 s7, s37, 7
	s_min_u32 s6, s6, 59
	s_min_u32 s7, s7, 59
	s_add_i32 s6, s6, s80
	s_add_i32 s7, s7, s80
	s_lshl_b32 s6, s6, 11
	s_and_b32 s6, s6, 0x1f800
	s_waitcnt vmcnt(1) lgkmcnt(1)
	v_mfma_f32_32x32x16_f16 v[50:65], v[78:81], v[74:77], v[50:65]
	s_waitcnt lgkmcnt(0)
	v_mfma_f32_32x32x16_f16 v[18:33], v[82:85], v[74:77], v[18:33]
	global_load_dwordx4 v[74:77], v[70:71], off
	s_waitcnt vmcnt(1)
	v_mfma_f32_32x32x16_f16 v[34:49], v[78:81], v[86:89], v[34:49]
	global_load_dwordx4 v[78:81], v[70:71], off offset:1024
	v_add_u32_e32 v70, s2, v0
	v_add_u32_e32 v71, s2, v72
	s_and_b32 s2, s52, 0x1f800
	s_lshl_b32 s64, s2, 4
	s_add_i32 s2, s31, 0x60
	s_and_b32 s2, s2, 0x7e0
	v_mfma_f32_32x32x16_f16 v[2:17], v[82:85], v[86:89], v[2:17]
	ds_read_b128 v[82:85], v70
	ds_read_b128 v[86:89], v71
	v_lshl_add_u64 v[70:71], v[68:69], 0, s[64:65]
	s_addk_i32 s31, 0x80
	s_lshl_b32 s52, s7, 11
	s_waitcnt vmcnt(1) lgkmcnt(1)
	v_mfma_f32_32x32x16_f16 v[50:65], v[82:85], v[74:77], v[50:65]
	s_waitcnt lgkmcnt(0)
	v_mfma_f32_32x32x16_f16 v[18:33], v[86:89], v[74:77], v[18:33]
	global_load_dwordx4 v[74:77], v[70:71], off
	s_waitcnt vmcnt(1)
	v_mfma_f32_32x32x16_f16 v[34:49], v[82:85], v[78:81], v[34:49]
	global_load_dwordx4 v[82:85], v[70:71], off offset:1024
	v_add_u32_e32 v70, s2, v0
	v_add_u32_e32 v71, s2, v72
	s_add_i32 s2, s37, 5
	s_min_u32 s2, s2, 59
	s_add_i32 s2, s2, s80
	s_lshl_b32 s2, s2, 11
	v_mfma_f32_32x32x16_f16 v[2:17], v[86:89], v[78:81], v[2:17]
	ds_read_b128 v[78:81], v70
	ds_read_b128 v[86:89], v71
	s_and_b32 s2, s2, 0x1f800
	s_lshl_b32 s64, s2, 4
	v_lshl_add_u64 v[70:71], v[68:69], 0, s[64:65]
	s_mov_b32 s37, s3
	s_cmp_lt_u32 s3, 60
	v_lshl_add_u64 v[70:71], v[70:71], 0, s[38:39]
	s_waitcnt vmcnt(1) lgkmcnt(1)
	v_mfma_f32_32x32x16_f16 v[50:65], v[78:81], v[74:77], v[50:65]
	s_waitcnt lgkmcnt(0)
	v_mfma_f32_32x32x16_f16 v[18:33], v[86:89], v[74:77], v[18:33]
	s_waitcnt vmcnt(0)
	v_mfma_f32_32x32x16_f16 v[34:49], v[78:81], v[82:85], v[34:49]
	v_mfma_f32_32x32x16_f16 v[2:17], v[86:89], v[82:85], v[2:17]
	s_cbranch_scc1 .LBB0_518
	s_waitcnt vmcnt(0)
	v_and_b32_e32 v68, 31, v176
	v_lshlrev_b32_e32 v69, 9, v176
	v_and_b32_e32 v69, 0x4000, v69
	v_lshl_or_b32 v70, v68, 2, v69
	v_lshl_add_u32 v70, s29, 8, v70
	v_add_u32_e32 v71, 0x1000, v70
	global_load_dword v80, v71, s[0:1] offset:-4096
	global_load_dword v81, v71, s[0:1] offset:-3968
	global_load_dword v82, v71, s[0:1] offset:0
	global_load_dword v83, v71, s[0:1] offset:128
	v_add_u32_e32 v73, 0x3000, v70
	global_load_dword v84, v73, s[0:1] offset:-4096
	global_load_dword v85, v73, s[0:1] offset:-3968
	global_load_dword v86, v73, s[0:1] offset:0
	global_load_dword v87, v73, s[0:1] offset:128
	v_add_u32_e32 v74, 0x9000, v70
	global_load_dword v88, v74, s[0:1] offset:-4096
	global_load_dword v89, v74, s[0:1] offset:-3968
	global_load_dword v90, v74, s[0:1] offset:0
	global_load_dword v91, v74, s[0:1] offset:128
	v_add_u32_e32 v75, 0xb000, v70
	global_load_dword v92, v75, s[0:1] offset:-4096
	global_load_dword v93, v75, s[0:1] offset:-3968
	global_load_dword v94, v75, s[0:1] offset:0
	global_load_dword v95, v75, s[0:1] offset:128
	v_add_u32_e32 v76, 0x11000, v70
	global_load_dword v96, v76, s[0:1] offset:-4096
	global_load_dword v97, v76, s[0:1] offset:-3968
	global_load_dword v98, v76, s[0:1] offset:0
	global_load_dword v99, v76, s[0:1] offset:128
	v_add_u32_e32 v77, 0x13000, v70
	global_load_dword v100, v77, s[0:1] offset:-4096
	global_load_dword v101, v77, s[0:1] offset:-3968
	global_load_dword v102, v77, s[0:1] offset:0
	global_load_dword v103, v77, s[0:1] offset:128
	v_add_u32_e32 v78, 0x19000, v70
	global_load_dword v104, v78, s[0:1] offset:-4096
	global_load_dword v105, v78, s[0:1] offset:-3968
	global_load_dword v106, v78, s[0:1] offset:0
	global_load_dword v107, v78, s[0:1] offset:128
	v_add_u32_e32 v79, 0x1b000, v70
	global_load_dword v108, v79, s[0:1] offset:-4096
	global_load_dword v109, v79, s[0:1] offset:-3968
	global_load_dword v110, v79, s[0:1] offset:0
	global_load_dword v111, v79, s[0:1] offset:128
	s_waitcnt vmcnt(0)
; #define MFMA32(a, b, c) __builtin_amdgcn_mfma_f32_32x32x16_f16((a), (b), (c), 0, 0, 0)
; DI int otid() { int t = threadIdx.x; asm volatile("" : "+v"(t)); return t; }
; DI int crow(int i, int h) { return (i & 3) + 8 * (i >> 2) + 4 * h; }
; template <int K, class Epi>
; DI void gemm64_res(const bf16_t* A, int lda, const bf16_t* Wp, int NU, unsigned char* lds, const Epi& epi) {
;     ...
;     for (int unit = wave; unit < NU; unit += NWAVE) {
;         const u32x4* bp = Bw + (size_t)(unit * NT) * 64 + lane;
;         f32x16 acc[2][NT];
; #pragma unroll
;         for (int mi = 0; mi < 2; ++mi)
; #pragma unroll
;             for (int nj = 0; nj < NT; ++nj)
; #pragma unroll
;                 for (int i = 0; i < 16; ++i) acc[mi][nj][i] = 0.f;
;         u32x4 bq[PD][NT];
; #pragma unroll
;         for (int s = 0; s < PD; ++s)
; #pragma unroll
;             for (int j = 0; j < NT; ++j) bq[s][j] = bp[(size_t)((s + rot) & (KS - 1)) * kstr + j * 64];
; #pragma unroll 1
;         for (int kk = 0; kk < KS; kk += PD) {
; #pragma unroll
;             for (int s = 0; s < PD; ++s) {
;                 const int ks = kk + s, ksr = (ks + rot) & (KS - 1);
;                 const bf16x8 a0 = *(const bf16x8*)(ab + ksr * 32), a1 = *(const bf16x8*)(ab + 32 * LD + ksr * 32);
; #pragma unroll
;                 for (int j = 0; j < NT; ++j) { acc[0][j] = MFMA32(a0, __builtin_bit_cast(bf16x8, bq[s][j]), acc[0][j]); acc[1][j] = MFMA32(a1, __builtin_bit_cast(bf16x8, bq[s][j]), acc[1][j]); }
;                 int nk = ks + PD; nk = nk < KS ? nk : KS - 1; nk = (nk + rot) & (KS - 1);
; #pragma unroll
;                 for (int j = 0; j < NT; ++j) bq[s][j] = bp[(size_t)nk * kstr + j * 64];
;             }
;         }
;         epi(unit, acc);
;     }
;     DI void operator()(int unit, const f32x16 (&acc)[MT][NT]) const {
;         const int lane = otid() & 63, r = lane & 31, h = lane >> 5;
; #pragma unroll
;         for (int mi = 0; mi < MT; ++mi)
; #pragma unroll
;             for (int nj = 0; nj < NT; ++nj)
; #pragma unroll
;                 for (int i = 0; i < 16; ++i) { float* q = x + ((mi * 32 + crow(i, h) + (mi == 2 ? d2 : 0)) * DM + unit * UW + nj * 32 + r); *q = *q + acc[mi][nj][i]; if (i == 15) __builtin_amdgcn_sched_barrier(0); }
;     }
	v_add_f32_e32 v80, v50, v80
	global_store_dword v71, v80, s[0:1] offset:-4096
	v_add_f32_e32 v81, v34, v81
	global_store_dword v71, v81, s[0:1] offset:-3968
	v_add_f32_e32 v82, v51, v82
	global_store_dword v71, v82, s[0:1] offset:0
	v_add_f32_e32 v83, v35, v83
	global_store_dword v71, v83, s[0:1] offset:128
	v_add_f32_e32 v84, v52, v84
	global_store_dword v73, v84, s[0:1] offset:-4096
	v_add_f32_e32 v85, v36, v85
	global_store_dword v73, v85, s[0:1] offset:-3968
	v_add_f32_e32 v86, v53, v86
	global_store_dword v73, v86, s[0:1] offset:0
	v_add_f32_e32 v87, v37, v87
	global_store_dword v73, v87, s[0:1] offset:128
	v_add_f32_e32 v88, v54, v88
	global_store_dword v74, v88, s[0:1] offset:-4096
	v_add_f32_e32 v89, v38, v89
	global_store_dword v74, v89, s[0:1] offset:-3968
	v_add_f32_e32 v90, v55, v90
	global_store_dword v74, v90, s[0:1] offset:0
	v_add_f32_e32 v91, v39, v91
	global_store_dword v74, v91, s[0:1] offset:128
	v_add_f32_e32 v92, v56, v92
	global_store_dword v75, v92, s[0:1] offset:-4096
	v_add_f32_e32 v93, v40, v93
	global_store_dword v75, v93, s[0:1] offset:-3968
	v_add_f32_e32 v94, v57, v94
	global_store_dword v75, v94, s[0:1] offset:0
	v_add_f32_e32 v95, v41, v95
	global_store_dword v75, v95, s[0:1] offset:128
	v_add_f32_e32 v96, v58, v96
	global_store_dword v76, v96, s[0:1] offset:-4096
	v_add_f32_e32 v97, v42, v97
	global_store_dword v76, v97, s[0:1] offset:-3968
	v_add_f32_e32 v98, v59, v98
	global_store_dword v76, v98, s[0:1] offset:0
	v_add_f32_e32 v99, v43, v99
	global_store_dword v76, v99, s[0:1] offset:128
	v_add_f32_e32 v100, v60, v100
	global_store_dword v77, v100, s[0:1] offset:-4096
	v_add_f32_e32 v101, v44, v101
	global_store_dword v77, v101, s[0:1] offset:-3968
	v_add_f32_e32 v102, v61, v102
	global_store_dword v77, v102, s[0:1] offset:0
	v_add_f32_e32 v103, v45, v103
	global_store_dword v77, v103, s[0:1] offset:128
	v_add_f32_e32 v104, v62, v104
	global_store_dword v78, v104, s[0:1] offset:-4096
	v_add_f32_e32 v105, v46, v105
	global_store_dword v78, v105, s[0:1] offset:-3968
	v_add_f32_e32 v106, v63, v106
	global_store_dword v78, v106, s[0:1] offset:0
	v_add_f32_e32 v107, v47, v107
	global_store_dword v78, v107, s[0:1] offset:128
	v_add_f32_e32 v108, v64, v108
	global_store_dword v79, v108, s[0:1] offset:-4096
	v_add_f32_e32 v109, v48, v109
	global_store_dword v79, v109, s[0:1] offset:-3968
	v_add_f32_e32 v110, v65, v110
	global_store_dword v79, v110, s[0:1] offset:0
	v_add_f32_e32 v111, v49, v111
	global_store_dword v79, v111, s[0:1] offset:128
	v_add_u32_e32 v71, 0x21000, v70
	global_load_dword v80, v71, s[0:1] offset:-4096
	global_load_dword v81, v71, s[0:1] offset:-3968
	global_load_dword v82, v71, s[0:1] offset:0
	global_load_dword v83, v71, s[0:1] offset:128
	v_add_u32_e32 v73, 0x23000, v70
	global_load_dword v84, v73, s[0:1] offset:-4096
	global_load_dword v85, v73, s[0:1] offset:-3968
	global_load_dword v86, v73, s[0:1] offset:0
	global_load_dword v87, v73, s[0:1] offset:128
	v_add_u32_e32 v74, 0x29000, v70
	global_load_dword v88, v74, s[0:1] offset:-4096
	global_load_dword v89, v74, s[0:1] offset:-3968
	global_load_dword v90, v74, s[0:1] offset:0
	global_load_dword v91, v74, s[0:1] offset:128
	v_add_u32_e32 v75, 0x2b000, v70
	global_load_dword v92, v75, s[0:1] offset:-4096
	global_load_dword v93, v75, s[0:1] offset:-3968
	global_load_dword v94, v75, s[0:1] offset:0
	global_load_dword v95, v75, s[0:1] offset:128
	v_add_u32_e32 v76, 0x31000, v70
	global_load_dword v96, v76, s[0:1] offset:-4096
	global_load_dword v97, v76, s[0:1] offset:-3968
	global_load_dword v98, v76, s[0:1] offset:0
	global_load_dword v99, v76, s[0:1] offset:128
	v_add_u32_e32 v77, 0x33000, v70
	global_load_dword v100, v77, s[0:1] offset:-4096
	global_load_dword v101, v77, s[0:1] offset:-3968
	global_load_dword v102, v77, s[0:1] offset:0
	global_load_dword v103, v77, s[0:1] offset:128
	v_add_u32_e32 v78, 0x39000, v70
	global_load_dword v104, v78, s[0:1] offset:-4096
	global_load_dword v105, v78, s[0:1] offset:-3968
	global_load_dword v106, v78, s[0:1] offset:0
	global_load_dword v107, v78, s[0:1] offset:128
	v_add_u32_e32 v79, 0x3b000, v70
	global_load_dword v108, v79, s[0:1] offset:-4096
	global_load_dword v109, v79, s[0:1] offset:-3968
	global_load_dword v110, v79, s[0:1] offset:0
	global_load_dword v111, v79, s[0:1] offset:128
	s_waitcnt vmcnt(0)
	v_add_f32_e32 v80, v18, v80
	global_store_dword v71, v80, s[0:1] offset:-4096
	v_add_f32_e32 v81, v2, v81
	global_store_dword v71, v81, s[0:1] offset:-3968
	v_add_f32_e32 v82, v19, v82
	global_store_dword v71, v82, s[0:1] offset:0
	v_add_f32_e32 v83, v3, v83
	global_store_dword v71, v83, s[0:1] offset:128
	v_add_f32_e32 v84, v20, v84
	global_store_dword v73, v84, s[0:1] offset:-4096
	v_add_f32_e32 v85, v4, v85
	global_store_dword v73, v85, s[0:1] offset:-3968
	v_add_f32_e32 v86, v21, v86
	global_store_dword v73, v86, s[0:1] offset:0
	v_add_f32_e32 v87, v5, v87
	global_store_dword v73, v87, s[0:1] offset:128
	v_add_f32_e32 v88, v22, v88
	global_store_dword v74, v88, s[0:1] offset:-4096
	v_add_f32_e32 v89, v6, v89
	global_store_dword v74, v89, s[0:1] offset:-3968
	v_add_f32_e32 v90, v23, v90
	global_store_dword v74, v90, s[0:1] offset:0
	v_add_f32_e32 v91, v7, v91
	global_store_dword v74, v91, s[0:1] offset:128
	v_add_f32_e32 v92, v24, v92
	global_store_dword v75, v92, s[0:1] offset:-4096
	v_add_f32_e32 v93, v8, v93
	global_store_dword v75, v93, s[0:1] offset:-3968
	v_add_f32_e32 v94, v25, v94
	global_store_dword v75, v94, s[0:1] offset:0
	v_add_f32_e32 v95, v9, v95
	global_store_dword v75, v95, s[0:1] offset:128
	v_add_f32_e32 v96, v26, v96
	global_store_dword v76, v96, s[0:1] offset:-4096
	v_add_f32_e32 v97, v10, v97
	global_store_dword v76, v97, s[0:1] offset:-3968
	v_add_f32_e32 v98, v27, v98
	global_store_dword v76, v98, s[0:1] offset:0
	v_add_f32_e32 v99, v11, v99
	global_store_dword v76, v99, s[0:1] offset:128
	v_add_f32_e32 v100, v28, v100
	global_store_dword v77, v100, s[0:1] offset:-4096
	v_add_f32_e32 v101, v12, v101
	global_store_dword v77, v101, s[0:1] offset:-3968
	v_add_f32_e32 v102, v29, v102
	global_store_dword v77, v102, s[0:1] offset:0
	v_add_f32_e32 v103, v13, v103
	global_store_dword v77, v103, s[0:1] offset:128
	v_add_f32_e32 v104, v30, v104
	global_store_dword v78, v104, s[0:1] offset:-4096
	v_add_f32_e32 v105, v14, v105
	global_store_dword v78, v105, s[0:1] offset:-3968
	v_add_f32_e32 v106, v31, v106
	global_store_dword v78, v106, s[0:1] offset:0
	v_add_f32_e32 v107, v15, v107
	global_store_dword v78, v107, s[0:1] offset:128
	v_add_f32_e32 v108, v32, v108
	global_store_dword v79, v108, s[0:1] offset:-4096
	v_add_f32_e32 v109, v16, v109
	global_store_dword v79, v109, s[0:1] offset:-3968
	v_add_f32_e32 v110, v33, v110
	global_store_dword v79, v110, s[0:1] offset:0
	v_add_f32_e32 v111, v17, v111
	global_store_dword v79, v111, s[0:1] offset:128
	s_waitcnt vmcnt(0)
	s_add_i32 s2, s29, 8
	s_cmp_lt_i32 s29, 8
	s_mov_b32 s29, s2
	s_cbranch_scc1 .LBB0_517
	s_movk_i32 s17, 0x810
	s_movk_i32 s64, 0x3fff

; #define MFMA32(a, b, c) __builtin_amdgcn_mfma_f32_32x32x16_f16((a), (b), (c), 0, 0, 0)
; DI int otid() { int t = threadIdx.x; asm volatile("" : "+v"(t)); return t; }
; DI int crow(int i, int h) { return (i & 3) + 8 * (i >> 2) + 4 * h; }
; template <int K, class Epi>
; DI void gemm64_res(const bf16_t* A, int lda, const bf16_t* Wp, int NU, unsigned char* lds, const Epi& epi) {
;     ...
; #pragma unroll 1
;         for (int kk = 0; kk < KS; kk += PD) {
; #pragma unroll
;             for (int s = 0; s < PD; ++s) {
;                 const int ks = kk + s, ksr = (ks + rot) & (KS - 1);
;                 const bf16x8 a0 = *(const bf16x8*)(ab + ksr * 32), a1 = *(const bf16x8*)(ab + 32 * LD + ksr * 32);
; #pragma unroll
;                 for (int j = 0; j < NT; ++j) { acc[0][j] = MFMA32(a0, __builtin_bit_cast(bf16x8, bq[s][j]), acc[0][j]); acc[1][j] = MFMA32(a1, __builtin_bit_cast(bf16x8, bq[s][j]), acc[1][j]); }
;                 int nk = ks + PD; nk = nk < KS ? nk : KS - 1; nk = (nk + rot) & (KS - 1);
; #pragma unroll
;                 for (int j = 0; j < NT; ++j) bq[s][j] = bp[(size_t)nk * kstr + j * 64];
;             }
;         }
;     DI void operator()(int unit, const f32x16 (&acc)[MT][NT]) const {
;         const int lane = otid() & 63, r = lane & 31, h = lane >> 5;
; #pragma unroll
;         for (int mi = 0; mi < MT; ++mi)
; #pragma unroll
;             for (int nj = 0; nj < NT; ++nj)
; #pragma unroll
;                 for (int i = 0; i < 16; ++i) { float* q = x + ((mi * 32 + crow(i, h) + (mi == 2 ? d2 : 0)) * DM + unit * UW + nj * 32 + r); *q = *q + acc[mi][nj][i]; if (i == 15) __builtin_amdgcn_sched_barrier(0); }
;     }
.LBB0_534:
	s_and_b32 s28, s28, 0xf800
	s_lshl_b32 s64, s28, 4
	s_and_b32 s9, s9, 0xf800
	v_lshl_add_u64 v[98:99], v[68:69], 0, s[64:65]
	s_lshl_b32 s64, s9, 4
	s_and_b32 s8, s8, 0xf800
	v_lshl_add_u64 v[90:91], v[68:69], 0, s[64:65]
	s_lshl_b32 s64, s8, 4
	s_and_b32 s8, s7, 0xf800
	v_lshl_add_u64 v[82:83], v[68:69], 0, s[64:65]
	s_lshl_b32 s64, s8, 4
	v_lshl_add_u64 v[74:75], v[68:69], 0, s[64:65]
	global_load_dwordx4 v[70:73], v[74:75], off
	s_nop 0
	global_load_dwordx4 v[74:77], v[74:75], off offset:1024
	s_nop 0
	global_load_dwordx4 v[78:81], v[82:83], off
	s_nop 0
	global_load_dwordx4 v[82:85], v[82:83], off offset:1024
	s_nop 0
	global_load_dwordx4 v[86:89], v[90:91], off
	s_nop 0
	global_load_dwordx4 v[90:93], v[90:91], off offset:1024
	s_nop 0
	global_load_dwordx4 v[94:97], v[98:99], off
	s_nop 0
	global_load_dwordx4 v[98:101], v[98:99], off offset:1024
	s_and_b32 s8, s6, 0x3e0
	v_add_u32_e32 v106, s8, v0
	ds_read_b128 v[102:105], v106
	ds_read_b128 v[106:109], v106 offset:33280
	s_add_i32 s9, s6, 32
	s_and_b32 s9, s9, 0x3e0
	s_add_i32 s28, s6, 64
	s_and_b32 s28, s28, 0x3e0
	s_add_i32 s29, s6, 0x60
	s_and_b32 s29, s29, 0x3e0
	s_add_i32 s8, s3, 5
	s_min_u32 s8, s8, 27
	s_add_i32 s8, s8, s33
	s_lshl_b32 s8, s8, 11
	s_addk_i32 s7, 0x2000
	s_addk_i32 s6, 0x80
	s_waitcnt vmcnt(7) lgkmcnt(1)
	v_mfma_f32_32x32x16_f16 v[50:65], v[102:105], v[70:73], v[50:65]
	s_waitcnt lgkmcnt(0)
	v_mfma_f32_32x32x16_f16 v[18:33], v[106:109], v[70:73], v[18:33]
	s_waitcnt vmcnt(6)
	v_mfma_f32_32x32x16_f16 v[34:49], v[102:105], v[74:77], v[34:49]
	v_mfma_f32_32x32x16_f16 v[2:17], v[106:109], v[74:77], v[2:17]
	v_add_u32_e32 v74, s9, v0
	ds_read_b128 v[70:73], v74
	ds_read_b128 v[74:77], v74 offset:33280
	s_add_i32 s9, s3, 6
	s_min_u32 s9, s9, 27
	s_add_i32 s9, s9, s33
	s_lshl_b32 s9, s9, 11
	s_waitcnt vmcnt(5) lgkmcnt(1)
	v_mfma_f32_32x32x16_f16 v[50:65], v[70:73], v[78:81], v[50:65]
	s_waitcnt lgkmcnt(0)
	v_mfma_f32_32x32x16_f16 v[18:33], v[74:77], v[78:81], v[18:33]
	s_waitcnt vmcnt(4)
	v_mfma_f32_32x32x16_f16 v[34:49], v[70:73], v[82:85], v[34:49]
	v_mfma_f32_32x32x16_f16 v[2:17], v[74:77], v[82:85], v[2:17]
	v_add_u32_e32 v74, s28, v0
	ds_read_b128 v[70:73], v74
	ds_read_b128 v[74:77], v74 offset:33280
	s_add_i32 s28, s3, 7
	s_min_u32 s28, s28, 27
	s_add_i32 s28, s28, s33
	s_lshl_b32 s28, s28, 11
	s_add_i32 s3, s3, 4
	s_waitcnt vmcnt(3) lgkmcnt(1)
	v_mfma_f32_32x32x16_f16 v[50:65], v[70:73], v[86:89], v[50:65]
	s_cmp_lt_u32 s3, 28
	s_waitcnt lgkmcnt(0)
	v_mfma_f32_32x32x16_f16 v[18:33], v[74:77], v[86:89], v[18:33]
	s_waitcnt vmcnt(2)
	v_mfma_f32_32x32x16_f16 v[34:49], v[70:73], v[90:93], v[34:49]
	v_mfma_f32_32x32x16_f16 v[2:17], v[74:77], v[90:93], v[2:17]
	v_add_u32_e32 v74, s29, v0
	ds_read_b128 v[70:73], v74
	ds_read_b128 v[74:77], v74 offset:33280
	s_waitcnt vmcnt(1) lgkmcnt(1)
	v_mfma_f32_32x32x16_f16 v[50:65], v[70:73], v[94:97], v[50:65]
	s_waitcnt lgkmcnt(0)
	v_mfma_f32_32x32x16_f16 v[18:33], v[74:77], v[94:97], v[18:33]
	s_waitcnt vmcnt(0)
	v_mfma_f32_32x32x16_f16 v[34:49], v[70:73], v[98:101], v[34:49]
	v_mfma_f32_32x32x16_f16 v[2:17], v[74:77], v[98:101], v[2:17]
	s_cbranch_scc1 .LBB0_534
	s_waitcnt vmcnt(0)
	v_and_b32_e32 v68, 31, v176
	v_lshlrev_b32_e32 v69, 9, v176
	v_and_b32_e32 v69, 0x4000, v69
	v_lshl_or_b32 v70, v68, 2, v69
	v_lshl_add_u32 v70, s2, 8, v70
	v_add_u32_e32 v71, 0x1000, v70
	global_load_dword v79, v71, s[0:1] offset:-4096
	global_load_dword v80, v71, s[0:1] offset:-3968
	global_load_dword v81, v71, s[0:1] offset:0
	global_load_dword v82, v71, s[0:1] offset:128
	v_add_u32_e32 v72, 0x3000, v70
	global_load_dword v83, v72, s[0:1] offset:-4096
	global_load_dword v84, v72, s[0:1] offset:-3968
	global_load_dword v85, v72, s[0:1] offset:0
	global_load_dword v86, v72, s[0:1] offset:128
	v_add_u32_e32 v73, 0x9000, v70
	global_load_dword v87, v73, s[0:1] offset:-4096
	global_load_dword v88, v73, s[0:1] offset:-3968
	global_load_dword v89, v73, s[0:1] offset:0
	global_load_dword v90, v73, s[0:1] offset:128
	v_add_u32_e32 v74, 0xb000, v70
	global_load_dword v91, v74, s[0:1] offset:-4096
	global_load_dword v92, v74, s[0:1] offset:-3968
	global_load_dword v93, v74, s[0:1] offset:0
	global_load_dword v94, v74, s[0:1] offset:128
	v_add_u32_e32 v75, 0x11000, v70
	global_load_dword v95, v75, s[0:1] offset:-4096
	global_load_dword v96, v75, s[0:1] offset:-3968
	global_load_dword v97, v75, s[0:1] offset:0
	global_load_dword v98, v75, s[0:1] offset:128
	v_add_u32_e32 v76, 0x13000, v70
	global_load_dword v99, v76, s[0:1] offset:-4096
	global_load_dword v100, v76, s[0:1] offset:-3968
	global_load_dword v101, v76, s[0:1] offset:0
	global_load_dword v102, v76, s[0:1] offset:128
	v_add_u32_e32 v77, 0x19000, v70
	global_load_dword v103, v77, s[0:1] offset:-4096
	global_load_dword v104, v77, s[0:1] offset:-3968
	global_load_dword v105, v77, s[0:1] offset:0
	global_load_dword v106, v77, s[0:1] offset:128
	v_add_u32_e32 v78, 0x1b000, v70
	global_load_dword v107, v78, s[0:1] offset:-4096
	global_load_dword v108, v78, s[0:1] offset:-3968
	global_load_dword v109, v78, s[0:1] offset:0
	global_load_dword v110, v78, s[0:1] offset:128
	s_waitcnt vmcnt(0)
; #define MFMA32(a, b, c) __builtin_amdgcn_mfma_f32_32x32x16_f16((a), (b), (c), 0, 0, 0)
; DI int otid() { int t = threadIdx.x; asm volatile("" : "+v"(t)); return t; }
; DI int crow(int i, int h) { return (i & 3) + 8 * (i >> 2) + 4 * h; }
; template <int K, class Epi>
; DI void gemm64_res(const bf16_t* A, int lda, const bf16_t* Wp, int NU, unsigned char* lds, const Epi& epi) {
;     ...
;     for (int unit = wave; unit < NU; unit += NWAVE) {
;         const u32x4* bp = Bw + (size_t)(unit * NT) * 64 + lane;
;         f32x16 acc[2][NT];
; #pragma unroll
;         for (int mi = 0; mi < 2; ++mi)
; #pragma unroll
;             for (int nj = 0; nj < NT; ++nj)
; #pragma unroll
;                 for (int i = 0; i < 16; ++i) acc[mi][nj][i] = 0.f;
;         u32x4 bq[PD][NT];
; #pragma unroll
;         for (int s = 0; s < PD; ++s)
; #pragma unroll
;             for (int j = 0; j < NT; ++j) bq[s][j] = bp[(size_t)((s + rot) & (KS - 1)) * kstr + j * 64];
; #pragma unroll 1
;         for (int kk = 0; kk < KS; kk += PD) {
; #pragma unroll
;             for (int s = 0; s < PD; ++s) {
;                 const int ks = kk + s, ksr = (ks + rot) & (KS - 1);
;                 const bf16x8 a0 = *(const bf16x8*)(ab + ksr * 32), a1 = *(const bf16x8*)(ab + 32 * LD + ksr * 32);
; #pragma unroll
;                 for (int j = 0; j < NT; ++j) { acc[0][j] = MFMA32(a0, __builtin_bit_cast(bf16x8, bq[s][j]), acc[0][j]); acc[1][j] = MFMA32(a1, __builtin_bit_cast(bf16x8, bq[s][j]), acc[1][j]); }
;                 int nk = ks + PD; nk = nk < KS ? nk : KS - 1; nk = (nk + rot) & (KS - 1);
; #pragma unroll
;                 for (int j = 0; j < NT; ++j) bq[s][j] = bp[(size_t)nk * kstr + j * 64];
;             }
;         }
;         epi(unit, acc);
;     }
;     DI void operator()(int unit, const f32x16 (&acc)[MT][NT]) const {
;         const int lane = otid() & 63, r = lane & 31, h = lane >> 5;
; #pragma unroll
;         for (int mi = 0; mi < MT; ++mi)
; #pragma unroll
;             for (int nj = 0; nj < NT; ++nj)
; #pragma unroll
;                 for (int i = 0; i < 16; ++i) { float* q = x + ((mi * 32 + crow(i, h) + (mi == 2 ? d2 : 0)) * DM + unit * UW + nj * 32 + r); *q = *q + acc[mi][nj][i]; if (i == 15) __builtin_amdgcn_sched_barrier(0); }
;     }
	v_add_f32_e32 v79, v50, v79
	global_store_dword v71, v79, s[0:1] offset:-4096
	v_add_f32_e32 v80, v34, v80
	global_store_dword v71, v80, s[0:1] offset:-3968
	v_add_f32_e32 v81, v51, v81
	global_store_dword v71, v81, s[0:1] offset:0
	v_add_f32_e32 v82, v35, v82
	global_store_dword v71, v82, s[0:1] offset:128
	v_add_f32_e32 v83, v52, v83
	global_store_dword v72, v83, s[0:1] offset:-4096
	v_add_f32_e32 v84, v36, v84
	global_store_dword v72, v84, s[0:1] offset:-3968
	v_add_f32_e32 v85, v53, v85
	global_store_dword v72, v85, s[0:1] offset:0
	v_add_f32_e32 v86, v37, v86
	global_store_dword v72, v86, s[0:1] offset:128
	v_add_f32_e32 v87, v54, v87
	global_store_dword v73, v87, s[0:1] offset:-4096
	v_add_f32_e32 v88, v38, v88
	global_store_dword v73, v88, s[0:1] offset:-3968
	v_add_f32_e32 v89, v55, v89
	global_store_dword v73, v89, s[0:1] offset:0
	v_add_f32_e32 v90, v39, v90
	global_store_dword v73, v90, s[0:1] offset:128
	v_add_f32_e32 v91, v56, v91
	global_store_dword v74, v91, s[0:1] offset:-4096
	v_add_f32_e32 v92, v40, v92
	global_store_dword v74, v92, s[0:1] offset:-3968
	v_add_f32_e32 v93, v57, v93
	global_store_dword v74, v93, s[0:1] offset:0
	v_add_f32_e32 v94, v41, v94
	global_store_dword v74, v94, s[0:1] offset:128
	v_add_f32_e32 v95, v58, v95
	global_store_dword v75, v95, s[0:1] offset:-4096
	v_add_f32_e32 v96, v42, v96
	global_store_dword v75, v96, s[0:1] offset:-3968
	v_add_f32_e32 v97, v59, v97
	global_store_dword v75, v97, s[0:1] offset:0
	v_add_f32_e32 v98, v43, v98
	global_store_dword v75, v98, s[0:1] offset:128
	v_add_f32_e32 v99, v60, v99
	global_store_dword v76, v99, s[0:1] offset:-4096
	v_add_f32_e32 v100, v44, v100
	global_store_dword v76, v100, s[0:1] offset:-3968
	v_add_f32_e32 v101, v61, v101
	global_store_dword v76, v101, s[0:1] offset:0
	v_add_f32_e32 v102, v45, v102
	global_store_dword v76, v102, s[0:1] offset:128
	v_add_f32_e32 v103, v62, v103
	global_store_dword v77, v103, s[0:1] offset:-4096
	v_add_f32_e32 v104, v46, v104
	global_store_dword v77, v104, s[0:1] offset:-3968
	v_add_f32_e32 v105, v63, v105
	global_store_dword v77, v105, s[0:1] offset:0
	v_add_f32_e32 v106, v47, v106
	global_store_dword v77, v106, s[0:1] offset:128
	v_add_f32_e32 v107, v64, v107
	global_store_dword v78, v107, s[0:1] offset:-4096
	v_add_f32_e32 v108, v48, v108
	global_store_dword v78, v108, s[0:1] offset:-3968
	v_add_f32_e32 v109, v65, v109
	global_store_dword v78, v109, s[0:1] offset:0
	v_add_f32_e32 v110, v49, v110
	global_store_dword v78, v110, s[0:1] offset:128
	v_add_u32_e32 v71, 0x21000, v70
	global_load_dword v79, v71, s[0:1] offset:-4096
	global_load_dword v80, v71, s[0:1] offset:-3968
	global_load_dword v81, v71, s[0:1] offset:0
	global_load_dword v82, v71, s[0:1] offset:128
	v_add_u32_e32 v72, 0x23000, v70
	global_load_dword v83, v72, s[0:1] offset:-4096
	global_load_dword v84, v72, s[0:1] offset:-3968
	global_load_dword v85, v72, s[0:1] offset:0
	global_load_dword v86, v72, s[0:1] offset:128
	v_add_u32_e32 v73, 0x29000, v70
	global_load_dword v87, v73, s[0:1] offset:-4096
	global_load_dword v88, v73, s[0:1] offset:-3968
	global_load_dword v89, v73, s[0:1] offset:0
	global_load_dword v90, v73, s[0:1] offset:128
	v_add_u32_e32 v74, 0x2b000, v70
	global_load_dword v91, v74, s[0:1] offset:-4096
	global_load_dword v92, v74, s[0:1] offset:-3968
	global_load_dword v93, v74, s[0:1] offset:0
	global_load_dword v94, v74, s[0:1] offset:128
	v_add_u32_e32 v75, 0x31000, v70
	global_load_dword v95, v75, s[0:1] offset:-4096
	global_load_dword v96, v75, s[0:1] offset:-3968
	global_load_dword v97, v75, s[0:1] offset:0
	global_load_dword v98, v75, s[0:1] offset:128
	v_add_u32_e32 v76, 0x33000, v70
	global_load_dword v99, v76, s[0:1] offset:-4096
	global_load_dword v100, v76, s[0:1] offset:-3968
	global_load_dword v101, v76, s[0:1] offset:0
	global_load_dword v102, v76, s[0:1] offset:128
	v_add_u32_e32 v77, 0x39000, v70
	global_load_dword v103, v77, s[0:1] offset:-4096
	global_load_dword v104, v77, s[0:1] offset:-3968
	global_load_dword v105, v77, s[0:1] offset:0
	global_load_dword v106, v77, s[0:1] offset:128
	v_add_u32_e32 v78, 0x3b000, v70
	global_load_dword v107, v78, s[0:1] offset:-4096
	global_load_dword v108, v78, s[0:1] offset:-3968
	global_load_dword v109, v78, s[0:1] offset:0
	global_load_dword v110, v78, s[0:1] offset:128
	s_waitcnt vmcnt(0)
	v_add_f32_e32 v79, v18, v79
	global_store_dword v71, v79, s[0:1] offset:-4096
	v_add_f32_e32 v80, v2, v80
	global_store_dword v71, v80, s[0:1] offset:-3968
	v_add_f32_e32 v81, v19, v81
	global_store_dword v71, v81, s[0:1] offset:0
	v_add_f32_e32 v82, v3, v82
	global_store_dword v71, v82, s[0:1] offset:128
	v_add_f32_e32 v83, v20, v83
	global_store_dword v72, v83, s[0:1] offset:-4096
	v_add_f32_e32 v84, v4, v84
	global_store_dword v72, v84, s[0:1] offset:-3968
	v_add_f32_e32 v85, v21, v85
	global_store_dword v72, v85, s[0:1] offset:0
	v_add_f32_e32 v86, v5, v86
	global_store_dword v72, v86, s[0:1] offset:128
	v_add_f32_e32 v87, v22, v87
	global_store_dword v73, v87, s[0:1] offset:-4096
	v_add_f32_e32 v88, v6, v88
	global_store_dword v73, v88, s[0:1] offset:-3968
	v_add_f32_e32 v89, v23, v89
	global_store_dword v73, v89, s[0:1] offset:0
	v_add_f32_e32 v90, v7, v90
	global_store_dword v73, v90, s[0:1] offset:128
	v_add_f32_e32 v91, v24, v91
	global_store_dword v74, v91, s[0:1] offset:-4096
	v_add_f32_e32 v92, v8, v92
	global_store_dword v74, v92, s[0:1] offset:-3968
	v_add_f32_e32 v93, v25, v93
	global_store_dword v74, v93, s[0:1] offset:0
	v_add_f32_e32 v94, v9, v94
	global_store_dword v74, v94, s[0:1] offset:128
	v_add_f32_e32 v95, v26, v95
	global_store_dword v75, v95, s[0:1] offset:-4096
	v_add_f32_e32 v96, v10, v96
	global_store_dword v75, v96, s[0:1] offset:-3968
	v_add_f32_e32 v97, v27, v97
	global_store_dword v75, v97, s[0:1] offset:0
	v_add_f32_e32 v98, v11, v98
	global_store_dword v75, v98, s[0:1] offset:128
	v_add_f32_e32 v99, v28, v99
	global_store_dword v76, v99, s[0:1] offset:-4096
	v_add_f32_e32 v100, v12, v100
	global_store_dword v76, v100, s[0:1] offset:-3968
	v_add_f32_e32 v101, v29, v101
	global_store_dword v76, v101, s[0:1] offset:0
	v_add_f32_e32 v102, v13, v102
	global_store_dword v76, v102, s[0:1] offset:128
	v_add_f32_e32 v103, v30, v103
	global_store_dword v77, v103, s[0:1] offset:-4096
	v_add_f32_e32 v104, v14, v104
	global_store_dword v77, v104, s[0:1] offset:-3968
	v_add_f32_e32 v105, v31, v105
	global_store_dword v77, v105, s[0:1] offset:0
	v_add_f32_e32 v106, v15, v106
	global_store_dword v77, v106, s[0:1] offset:128
	v_add_f32_e32 v107, v32, v107
	global_store_dword v78, v107, s[0:1] offset:-4096
	v_add_f32_e32 v108, v16, v108
	global_store_dword v78, v108, s[0:1] offset:-3968
	v_add_f32_e32 v109, v33, v109
	global_store_dword v78, v109, s[0:1] offset:0
	v_add_f32_e32 v110, v17, v110
	global_store_dword v78, v110, s[0:1] offset:128
	s_waitcnt vmcnt(0)
	s_add_i32 s3, s2, 8
	s_cmp_lt_i32 s2, 8
	s_mov_b32 s2, s3
	s_cbranch_scc1 .LBB0_533
	s_movk_i32 s17, 0x810
	s_movk_i32 s64, 0x3fff

; #define MFMA32(a, b, c) __builtin_amdgcn_mfma_f32_32x32x16_f16((a), (b), (c), 0, 0, 0)
; template <int K, class Epi>
; DI void gemm64_res(const bf16_t* A, int lda, const bf16_t* Wp, int NU, unsigned char* lds, const Epi& epi) {
;     ...
;     for (int unit = wave; unit < NU; unit += NWAVE) {
;         const u32x4* bp = Bw + (size_t)(unit * NT) * 64 + lane;
;         f32x16 acc[2][NT];
; #pragma unroll
;         for (int mi = 0; mi < 2; ++mi)
; #pragma unroll
;             for (int nj = 0; nj < NT; ++nj)
; #pragma unroll
;                 for (int i = 0; i < 16; ++i) acc[mi][nj][i] = 0.f;
;         u32x4 bq[PD][NT];
; #pragma unroll
;         for (int s = 0; s < PD; ++s)
; #pragma unroll
;             for (int j = 0; j < NT; ++j) bq[s][j] = bp[(size_t)((s + rot) & (KS - 1)) * kstr + j * 64];
; #pragma unroll 1
;         for (int kk = 0; kk < KS; kk += PD) {
; #pragma unroll
;             for (int s = 0; s < PD; ++s) {
;                 const int ks = kk + s, ksr = (ks + rot) & (KS - 1);
;                 const bf16x8 a0 = *(const bf16x8*)(ab + ksr * 32), a1 = *(const bf16x8*)(ab + 32 * LD + ksr * 32);
; #pragma unroll
;                 for (int j = 0; j < NT; ++j) { acc[0][j] = MFMA32(a0, __builtin_bit_cast(bf16x8, bq[s][j]), acc[0][j]); acc[1][j] = MFMA32(a1, __builtin_bit_cast(bf16x8, bq[s][j]), acc[1][j]); }
;                 int nk = ks + PD; nk = nk < KS ? nk : KS - 1; nk = (nk + rot) & (KS - 1);
; #pragma unroll
;                 for (int j = 0; j < NT; ++j) bq[s][j] = bp[(size_t)nk * kstr + j * 64];
;             }
;         }
.LBB0_540:
	s_lshl_b32 s0, s31, 1
	s_ashr_i32 s1, s0, 31
	s_lshl_b64 s[0:1], s[0:1], 10
	v_lshl_add_u64 v[68:69], v[66:67], 0, s[0:1]
	v_readlane_b32 s0, v255, 11
	v_readlane_b32 s1, v255, 12
	s_mov_b32 s1, s65
	s_mov_b32 s2, s0
	v_lshl_add_u64 v[2:3], v[68:69], 0, s[0:1]
	s_mov_b64 s[0:1], 0x2c400
	v_writelane_b32 v255, s2, 11
	v_lshl_add_u64 v[70:71], v[2:3], 0, s[0:1]
	v_mov_b32_e32 v2, 0
	v_writelane_b32 v255, s3, 12
	s_mov_b32 s3, -4
	v_readlane_b32 s2, v254, 46
	v_readlane_b32 s5, v253, 40
	v_readlane_b32 s4, v253, 39
	v_readlane_b32 s0, v253, 38
	v_readlane_b32 s1, v254, 48
	v_mov_b32_e32 v3, v2
	v_mov_b32_e32 v4, v2
	v_mov_b32_e32 v5, v2
	v_mov_b32_e32 v6, v2
	v_mov_b32_e32 v7, v2
	v_mov_b32_e32 v8, v2
	v_mov_b32_e32 v9, v2
	v_mov_b32_e32 v10, v2
	v_mov_b32_e32 v11, v2
	v_mov_b32_e32 v12, v2
	v_mov_b32_e32 v13, v2
	v_mov_b32_e32 v14, v2
	v_mov_b32_e32 v15, v2
	v_mov_b32_e32 v16, v2
	v_mov_b32_e32 v17, v2
	v_mov_b32_e32 v18, v2
	v_mov_b32_e32 v19, v2
	v_mov_b32_e32 v20, v2
	v_mov_b32_e32 v21, v2
	v_mov_b32_e32 v22, v2
	v_mov_b32_e32 v23, v2
	v_mov_b32_e32 v24, v2
	v_mov_b32_e32 v25, v2
	v_mov_b32_e32 v26, v2
	v_mov_b32_e32 v27, v2
	v_mov_b32_e32 v28, v2
	v_mov_b32_e32 v29, v2
	v_mov_b32_e32 v30, v2
	v_mov_b32_e32 v31, v2
	v_mov_b32_e32 v32, v2
	v_mov_b32_e32 v33, v2
	v_mov_b32_e32 v34, v2
	v_mov_b32_e32 v35, v2
	v_mov_b32_e32 v36, v2
	v_mov_b32_e32 v37, v2
	v_mov_b32_e32 v38, v2
	v_mov_b32_e32 v39, v2
	v_mov_b32_e32 v40, v2
	v_mov_b32_e32 v41, v2
	v_mov_b32_e32 v42, v2
	v_mov_b32_e32 v43, v2
	v_mov_b32_e32 v44, v2
	v_mov_b32_e32 v45, v2
	v_mov_b32_e32 v46, v2
	v_mov_b32_e32 v47, v2
	v_mov_b32_e32 v48, v2
	v_mov_b32_e32 v49, v2
	v_mov_b32_e32 v50, v2
	v_mov_b32_e32 v51, v2
	v_mov_b32_e32 v52, v2
	v_mov_b32_e32 v53, v2
	v_mov_b32_e32 v54, v2
	v_mov_b32_e32 v55, v2
	v_mov_b32_e32 v56, v2
	v_mov_b32_e32 v57, v2
	v_mov_b32_e32 v58, v2
	v_mov_b32_e32 v59, v2
	v_mov_b32_e32 v60, v2
	v_mov_b32_e32 v61, v2
	v_mov_b32_e32 v62, v2
	v_mov_b32_e32 v63, v2
	v_mov_b32_e32 v64, v2
	v_mov_b32_e32 v65, v2
	s_add_i32 s0, s80, -4
	s_mov_b32 s101, 0
	s_mov_b32 s2, s0
	s_and_b32 s3, s2, 63
	s_add_i32 s2, s2, 1
	s_mul_i32 s100, s3, 0x2c000
	v_lshl_add_u64 v[92:93], v[68:69], 0, s[100:101]
	global_load_dwordx4 v[116:119], v[92:93], off
	global_load_dwordx4 v[120:123], v[92:93], off offset:1024
	s_and_b32 s3, s2, 63
	s_add_i32 s2, s2, 1
	s_mul_i32 s100, s3, 0x2c000
	v_lshl_add_u64 v[92:93], v[68:69], 0, s[100:101]
	global_load_dwordx4 v[124:127], v[92:93], off
	global_load_dwordx4 v[128:131], v[92:93], off offset:1024
	s_and_b32 s3, s2, 63
	s_add_i32 s2, s2, 1
	s_mul_i32 s100, s3, 0x2c000
	v_lshl_add_u64 v[92:93], v[68:69], 0, s[100:101]
	global_load_dwordx4 v[132:135], v[92:93], off
	global_load_dwordx4 v[136:139], v[92:93], off offset:1024
	s_and_b32 s3, s2, 63
	s_add_i32 s2, s2, 1
	s_mul_i32 s100, s3, 0x2c000
	v_lshl_add_u64 v[92:93], v[68:69], 0, s[100:101]
	global_load_dwordx4 v[140:143], v[92:93], off
	global_load_dwordx4 v[144:147], v[92:93], off offset:1024
	s_and_b32 s3, s2, 63
	s_add_i32 s2, s2, 1
	s_mul_i32 s100, s3, 0x2c000
	v_lshl_add_u64 v[92:93], v[68:69], 0, s[100:101]
	global_load_dwordx4 v[148:151], v[92:93], off
	global_load_dwordx4 v[152:155], v[92:93], off offset:1024
	s_and_b32 s3, s2, 63
	s_add_i32 s2, s2, 1
	s_mul_i32 s100, s3, 0x2c000
	v_lshl_add_u64 v[92:93], v[68:69], 0, s[100:101]
	global_load_dwordx4 v[156:159], v[92:93], off
	global_load_dwordx4 v[160:163], v[92:93], off offset:1024
	s_and_b32 s3, s2, 63
	s_add_i32 s2, s2, 1
	s_mul_i32 s100, s3, 0x2c000
	v_lshl_add_u64 v[92:93], v[68:69], 0, s[100:101]
	global_load_dwordx4 v[164:167], v[92:93], off
	global_load_dwordx4 v[168:171], v[92:93], off offset:1024
	s_and_b32 s3, s2, 63
	s_add_i32 s2, s2, 1
	s_mul_i32 s100, s3, 0x2c000
	v_lshl_add_u64 v[92:93], v[68:69], 0, s[100:101]
	global_load_dwordx4 v[104:107], v[92:93], off
	global_load_dwordx4 v[108:111], v[92:93], off offset:1024
	s_mov_b32 s1, s0
	s_and_b32 s3, s1, 63
	s_lshl_b32 s3, s3, 5
	s_add_i32 s1, s1, 1
	v_add_u32_e32 v94, s3, v0
	v_add_u32_e32 v95, s3, v72
	ds_read_b128 v[76:79], v94
	ds_read_b128 v[80:83], v95
	s_mov_b32 s4, 7
.Lkup2_loop:
	s_and_b32 s3, s1, 63
	s_lshl_b32 s3, s3, 5
	s_add_i32 s1, s1, 1
	v_add_u32_e32 v94, s3, v0
	v_add_u32_e32 v95, s3, v72
	ds_read_b128 v[84:87], v94
	ds_read_b128 v[88:91], v95
	s_waitcnt vmcnt(15) lgkmcnt(2)
	v_mfma_f32_32x32x16_f16 v[50:65], v[76:79], v[116:119], v[50:65]
	v_mfma_f32_32x32x16_f16 v[18:33], v[80:83], v[116:119], v[18:33]
	s_waitcnt vmcnt(14)
	v_mfma_f32_32x32x16_f16 v[34:49], v[76:79], v[120:123], v[34:49]
	v_mfma_f32_32x32x16_f16 v[2:17], v[80:83], v[120:123], v[2:17]
	s_and_b32 s3, s2, 63
	s_add_i32 s2, s2, 1
	s_mul_i32 s100, s3, 0x2c000
	v_lshl_add_u64 v[92:93], v[68:69], 0, s[100:101]
	global_load_dwordx4 v[116:119], v[92:93], off
	global_load_dwordx4 v[120:123], v[92:93], off offset:1024
	s_and_b32 s3, s1, 63
	s_lshl_b32 s3, s3, 5
	s_add_i32 s1, s1, 1
	v_add_u32_e32 v94, s3, v0
	v_add_u32_e32 v95, s3, v72
	ds_read_b128 v[76:79], v94
	ds_read_b128 v[80:83], v95
	s_waitcnt vmcnt(15) lgkmcnt(2)
	v_mfma_f32_32x32x16_f16 v[50:65], v[84:87], v[124:127], v[50:65]
	v_mfma_f32_32x32x16_f16 v[18:33], v[88:91], v[124:127], v[18:33]
	s_waitcnt vmcnt(14)
	v_mfma_f32_32x32x16_f16 v[34:49], v[84:87], v[128:131], v[34:49]
	v_mfma_f32_32x32x16_f16 v[2:17], v[88:91], v[128:131], v[2:17]
	s_and_b32 s3, s2, 63
	s_add_i32 s2, s2, 1
	s_mul_i32 s100, s3, 0x2c000
	v_lshl_add_u64 v[92:93], v[68:69], 0, s[100:101]
	global_load_dwordx4 v[124:127], v[92:93], off
	global_load_dwordx4 v[128:131], v[92:93], off offset:1024
	s_and_b32 s3, s1, 63
	s_lshl_b32 s3, s3, 5
	s_add_i32 s1, s1, 1
	v_add_u32_e32 v94, s3, v0
	v_add_u32_e32 v95, s3, v72
	ds_read_b128 v[84:87], v94
	ds_read_b128 v[88:91], v95
	s_waitcnt vmcnt(15) lgkmcnt(2)
; #define MFMA32(a, b, c) __builtin_amdgcn_mfma_f32_32x32x16_f16((a), (b), (c), 0, 0, 0)
; template <int K, class Epi>
; DI void gemm64_res(const bf16_t* A, int lda, const bf16_t* Wp, int NU, unsigned char* lds, const Epi& epi) {
;     ...
; #pragma unroll 1
;         for (int kk = 0; kk < KS; kk += PD) {
; #pragma unroll
;             for (int s = 0; s < PD; ++s) {
;                 const int ks = kk + s, ksr = (ks + rot) & (KS - 1);
;                 const bf16x8 a0 = *(const bf16x8*)(ab + ksr * 32), a1 = *(const bf16x8*)(ab + 32 * LD + ksr * 32);
; #pragma unroll
;                 for (int j = 0; j < NT; ++j) { acc[0][j] = MFMA32(a0, __builtin_bit_cast(bf16x8, bq[s][j]), acc[0][j]); acc[1][j] = MFMA32(a1, __builtin_bit_cast(bf16x8, bq[s][j]), acc[1][j]); }
;                 int nk = ks + PD; nk = nk < KS ? nk : KS - 1; nk = (nk + rot) & (KS - 1);
; #pragma unroll
;                 for (int j = 0; j < NT; ++j) bq[s][j] = bp[(size_t)nk * kstr + j * 64];
;             }
	v_mfma_f32_32x32x16_f16 v[50:65], v[76:79], v[132:135], v[50:65]
	v_mfma_f32_32x32x16_f16 v[18:33], v[80:83], v[132:135], v[18:33]
	s_waitcnt vmcnt(14)
	v_mfma_f32_32x32x16_f16 v[34:49], v[76:79], v[136:139], v[34:49]
	v_mfma_f32_32x32x16_f16 v[2:17], v[80:83], v[136:139], v[2:17]
	s_and_b32 s3, s2, 63
	s_add_i32 s2, s2, 1
	s_mul_i32 s100, s3, 0x2c000
	v_lshl_add_u64 v[92:93], v[68:69], 0, s[100:101]
	global_load_dwordx4 v[132:135], v[92:93], off
	global_load_dwordx4 v[136:139], v[92:93], off offset:1024
	s_and_b32 s3, s1, 63
	s_lshl_b32 s3, s3, 5
	s_add_i32 s1, s1, 1
	v_add_u32_e32 v94, s3, v0
	v_add_u32_e32 v95, s3, v72
	ds_read_b128 v[76:79], v94
	ds_read_b128 v[80:83], v95
	s_waitcnt vmcnt(15) lgkmcnt(2)
	v_mfma_f32_32x32x16_f16 v[50:65], v[84:87], v[140:143], v[50:65]
	v_mfma_f32_32x32x16_f16 v[18:33], v[88:91], v[140:143], v[18:33]
	s_waitcnt vmcnt(14)
	v_mfma_f32_32x32x16_f16 v[34:49], v[84:87], v[144:147], v[34:49]
	v_mfma_f32_32x32x16_f16 v[2:17], v[88:91], v[144:147], v[2:17]
	s_and_b32 s3, s2, 63
	s_add_i32 s2, s2, 1
	s_mul_i32 s100, s3, 0x2c000
	v_lshl_add_u64 v[92:93], v[68:69], 0, s[100:101]
	global_load_dwordx4 v[140:143], v[92:93], off
	global_load_dwordx4 v[144:147], v[92:93], off offset:1024
	s_and_b32 s3, s1, 63
	s_lshl_b32 s3, s3, 5
	s_add_i32 s1, s1, 1
	v_add_u32_e32 v94, s3, v0
	v_add_u32_e32 v95, s3, v72
	ds_read_b128 v[84:87], v94
	ds_read_b128 v[88:91], v95
	s_waitcnt vmcnt(15) lgkmcnt(2)
	v_mfma_f32_32x32x16_f16 v[50:65], v[76:79], v[148:151], v[50:65]
	v_mfma_f32_32x32x16_f16 v[18:33], v[80:83], v[148:151], v[18:33]
	s_waitcnt vmcnt(14)
	v_mfma_f32_32x32x16_f16 v[34:49], v[76:79], v[152:155], v[34:49]
	v_mfma_f32_32x32x16_f16 v[2:17], v[80:83], v[152:155], v[2:17]
	s_and_b32 s3, s2, 63
	s_add_i32 s2, s2, 1
	s_mul_i32 s100, s3, 0x2c000
	v_lshl_add_u64 v[92:93], v[68:69], 0, s[100:101]
	global_load_dwordx4 v[148:151], v[92:93], off
	global_load_dwordx4 v[152:155], v[92:93], off offset:1024
	s_and_b32 s3, s1, 63
	s_lshl_b32 s3, s3, 5
	s_add_i32 s1, s1, 1
	v_add_u32_e32 v94, s3, v0
	v_add_u32_e32 v95, s3, v72
	ds_read_b128 v[76:79], v94
	ds_read_b128 v[80:83], v95
	s_waitcnt vmcnt(15) lgkmcnt(2)
	v_mfma_f32_32x32x16_f16 v[50:65], v[84:87], v[156:159], v[50:65]
	v_mfma_f32_32x32x16_f16 v[18:33], v[88:91], v[156:159], v[18:33]
	s_waitcnt vmcnt(14)
	v_mfma_f32_32x32x16_f16 v[34:49], v[84:87], v[160:163], v[34:49]
	v_mfma_f32_32x32x16_f16 v[2:17], v[88:91], v[160:163], v[2:17]
	s_and_b32 s3, s2, 63
	s_add_i32 s2, s2, 1
	s_mul_i32 s100, s3, 0x2c000
	v_lshl_add_u64 v[92:93], v[68:69], 0, s[100:101]
	global_load_dwordx4 v[156:159], v[92:93], off
	global_load_dwordx4 v[160:163], v[92:93], off offset:1024
	s_and_b32 s3, s1, 63
	s_lshl_b32 s3, s3, 5
	s_add_i32 s1, s1, 1
	v_add_u32_e32 v94, s3, v0
	v_add_u32_e32 v95, s3, v72
	ds_read_b128 v[84:87], v94
	ds_read_b128 v[88:91], v95
	s_waitcnt vmcnt(15) lgkmcnt(2)
	v_mfma_f32_32x32x16_f16 v[50:65], v[76:79], v[164:167], v[50:65]
	v_mfma_f32_32x32x16_f16 v[18:33], v[80:83], v[164:167], v[18:33]
	s_waitcnt vmcnt(14)
	v_mfma_f32_32x32x16_f16 v[34:49], v[76:79], v[168:171], v[34:49]
	v_mfma_f32_32x32x16_f16 v[2:17], v[80:83], v[168:171], v[2:17]
	s_and_b32 s3, s2, 63
	s_add_i32 s2, s2, 1
	s_mul_i32 s100, s3, 0x2c000
	v_lshl_add_u64 v[92:93], v[68:69], 0, s[100:101]
	global_load_dwordx4 v[164:167], v[92:93], off
	global_load_dwordx4 v[168:171], v[92:93], off offset:1024
	s_and_b32 s3, s1, 63
	s_lshl_b32 s3, s3, 5
	s_add_i32 s1, s1, 1
	v_add_u32_e32 v94, s3, v0
	v_add_u32_e32 v95, s3, v72
	ds_read_b128 v[76:79], v94
	ds_read_b128 v[80:83], v95
	s_waitcnt vmcnt(15) lgkmcnt(2)
	v_mfma_f32_32x32x16_f16 v[50:65], v[84:87], v[104:107], v[50:65]
	v_mfma_f32_32x32x16_f16 v[18:33], v[88:91], v[104:107], v[18:33]
	s_waitcnt vmcnt(14)
	v_mfma_f32_32x32x16_f16 v[34:49], v[84:87], v[108:111], v[34:49]
	v_mfma_f32_32x32x16_f16 v[2:17], v[88:91], v[108:111], v[2:17]
	s_and_b32 s3, s2, 63
	s_add_i32 s2, s2, 1
	s_mul_i32 s100, s3, 0x2c000
	v_lshl_add_u64 v[92:93], v[68:69], 0, s[100:101]
	global_load_dwordx4 v[104:107], v[92:93], off
	global_load_dwordx4 v[108:111], v[92:93], off offset:1024
	s_add_i32 s4, s4, -1
	s_cmp_lg_u32 s4, 0
	s_cbranch_scc1 .Lkup2_loop
	s_and_b32 s3, s1, 63
	s_lshl_b32 s3, s3, 5
	s_add_i32 s1, s1, 1
	v_add_u32_e32 v94, s3, v0
	v_add_u32_e32 v95, s3, v72
	ds_read_b128 v[84:87], v94
	ds_read_b128 v[88:91], v95
	s_waitcnt vmcnt(15) lgkmcnt(2)
	v_mfma_f32_32x32x16_f16 v[50:65], v[76:79], v[116:119], v[50:65]
	v_mfma_f32_32x32x16_f16 v[18:33], v[80:83], v[116:119], v[18:33]
	s_waitcnt vmcnt(14)
	v_mfma_f32_32x32x16_f16 v[34:49], v[76:79], v[120:123], v[34:49]
	v_mfma_f32_32x32x16_f16 v[2:17], v[80:83], v[120:123], v[2:17]
	s_and_b32 s3, s1, 63
	s_lshl_b32 s3, s3, 5
	s_add_i32 s1, s1, 1
	v_add_u32_e32 v94, s3, v0
	v_add_u32_e32 v95, s3, v72
	ds_read_b128 v[76:79], v94
	ds_read_b128 v[80:83], v95
	s_waitcnt vmcnt(13) lgkmcnt(2)
	v_mfma_f32_32x32x16_f16 v[50:65], v[84:87], v[124:127], v[50:65]
	v_mfma_f32_32x32x16_f16 v[18:33], v[88:91], v[124:127], v[18:33]
	s_waitcnt vmcnt(12)
	v_mfma_f32_32x32x16_f16 v[34:49], v[84:87], v[128:131], v[34:49]
	v_mfma_f32_32x32x16_f16 v[2:17], v[88:91], v[128:131], v[2:17]
	s_and_b32 s3, s1, 63
	s_lshl_b32 s3, s3, 5
	s_add_i32 s1, s1, 1
	v_add_u32_e32 v94, s3, v0
	v_add_u32_e32 v95, s3, v72
	ds_read_b128 v[84:87], v94
	ds_read_b128 v[88:91], v95
	s_waitcnt vmcnt(11) lgkmcnt(2)
	v_mfma_f32_32x32x16_f16 v[50:65], v[76:79], v[132:135], v[50:65]
	v_mfma_f32_32x32x16_f16 v[18:33], v[80:83], v[132:135], v[18:33]
	s_waitcnt vmcnt(10)
; #define MFMA32(a, b, c) __builtin_amdgcn_mfma_f32_32x32x16_f16((a), (b), (c), 0, 0, 0)
; DI int otid() { int t = threadIdx.x; asm volatile("" : "+v"(t)); return t; }
; DI bf16_t cv1(float x) { return (bf16_t)(pk2(x, 0.f) & 0xffffu); }
; DI int crow(int i, int h) { return (i & 3) + 8 * (i >> 2) + 4 * h; }
; template <int K, class Epi>
; DI void gemm64_res(const bf16_t* A, int lda, const bf16_t* Wp, int NU, unsigned char* lds, const Epi& epi) {
;     ...
; #pragma unroll 1
;         for (int kk = 0; kk < KS; kk += PD) {
; #pragma unroll
;             for (int s = 0; s < PD; ++s) {
;                 const int ks = kk + s, ksr = (ks + rot) & (KS - 1);
;                 const bf16x8 a0 = *(const bf16x8*)(ab + ksr * 32), a1 = *(const bf16x8*)(ab + 32 * LD + ksr * 32);
; #pragma unroll
;                 for (int j = 0; j < NT; ++j) { acc[0][j] = MFMA32(a0, __builtin_bit_cast(bf16x8, bq[s][j]), acc[0][j]); acc[1][j] = MFMA32(a1, __builtin_bit_cast(bf16x8, bq[s][j]), acc[1][j]); }
;                 int nk = ks + PD; nk = nk < KS ? nk : KS - 1; nk = (nk + rot) & (KS - 1);
; #pragma unroll
;                 for (int j = 0; j < NT; ++j) bq[s][j] = bp[(size_t)nk * kstr + j * 64];
;             }
; template <int MT> DI void st_bf16(bf16_t* base, int ld, int d2, int col0, const f32x16 (&acc)[MT][NT]) {
;     const int lane = otid() & 63, r = lane & 31, h = lane >> 5;
; #pragma unroll
;     for (int mi = 0; mi < MT; ++mi)
; #pragma unroll
;         for (int nj = 0; nj < NT; ++nj)
; #pragma unroll
;             for (int i = 0; i < 16; ++i) base[(mi * 32 + crow(i, h) + (mi == 2 ? d2 : 0)) * ld + col0 + nj * 32 + r] = cv1(acc[mi][nj][i]);
; }
	v_mfma_f32_32x32x16_f16 v[34:49], v[76:79], v[136:139], v[34:49]
	v_mfma_f32_32x32x16_f16 v[2:17], v[80:83], v[136:139], v[2:17]
	s_and_b32 s3, s1, 63
	s_lshl_b32 s3, s3, 5
	s_add_i32 s1, s1, 1
	v_add_u32_e32 v94, s3, v0
	v_add_u32_e32 v95, s3, v72
	ds_read_b128 v[76:79], v94
	ds_read_b128 v[80:83], v95
	s_waitcnt vmcnt(9) lgkmcnt(2)
	v_mfma_f32_32x32x16_f16 v[50:65], v[84:87], v[140:143], v[50:65]
	v_mfma_f32_32x32x16_f16 v[18:33], v[88:91], v[140:143], v[18:33]
	s_waitcnt vmcnt(8)
	v_mfma_f32_32x32x16_f16 v[34:49], v[84:87], v[144:147], v[34:49]
	v_mfma_f32_32x32x16_f16 v[2:17], v[88:91], v[144:147], v[2:17]
	s_and_b32 s3, s1, 63
	s_lshl_b32 s3, s3, 5
	s_add_i32 s1, s1, 1
	v_add_u32_e32 v94, s3, v0
	v_add_u32_e32 v95, s3, v72
	ds_read_b128 v[84:87], v94
	ds_read_b128 v[88:91], v95
	s_waitcnt vmcnt(7) lgkmcnt(2)
	v_mfma_f32_32x32x16_f16 v[50:65], v[76:79], v[148:151], v[50:65]
	v_mfma_f32_32x32x16_f16 v[18:33], v[80:83], v[148:151], v[18:33]
	s_waitcnt vmcnt(6)
	v_mfma_f32_32x32x16_f16 v[34:49], v[76:79], v[152:155], v[34:49]
	v_mfma_f32_32x32x16_f16 v[2:17], v[80:83], v[152:155], v[2:17]
	s_and_b32 s3, s1, 63
	s_lshl_b32 s3, s3, 5
	s_add_i32 s1, s1, 1
	v_add_u32_e32 v94, s3, v0
	v_add_u32_e32 v95, s3, v72
	ds_read_b128 v[76:79], v94
	ds_read_b128 v[80:83], v95
	s_waitcnt vmcnt(5) lgkmcnt(2)
	v_mfma_f32_32x32x16_f16 v[50:65], v[84:87], v[156:159], v[50:65]
	v_mfma_f32_32x32x16_f16 v[18:33], v[88:91], v[156:159], v[18:33]
	s_waitcnt vmcnt(4)
	v_mfma_f32_32x32x16_f16 v[34:49], v[84:87], v[160:163], v[34:49]
	v_mfma_f32_32x32x16_f16 v[2:17], v[88:91], v[160:163], v[2:17]
	s_and_b32 s3, s1, 63
	s_lshl_b32 s3, s3, 5
	s_add_i32 s1, s1, 1
	v_add_u32_e32 v94, s3, v0
	v_add_u32_e32 v95, s3, v72
	ds_read_b128 v[84:87], v94
	ds_read_b128 v[88:91], v95
	s_waitcnt vmcnt(3) lgkmcnt(2)
	v_mfma_f32_32x32x16_f16 v[50:65], v[76:79], v[164:167], v[50:65]
	v_mfma_f32_32x32x16_f16 v[18:33], v[80:83], v[164:167], v[18:33]
	s_waitcnt vmcnt(2)
	v_mfma_f32_32x32x16_f16 v[34:49], v[76:79], v[168:171], v[34:49]
	v_mfma_f32_32x32x16_f16 v[2:17], v[80:83], v[168:171], v[2:17]
	s_waitcnt vmcnt(1) lgkmcnt(0)
	v_mfma_f32_32x32x16_f16 v[50:65], v[84:87], v[104:107], v[50:65]
	v_mfma_f32_32x32x16_f16 v[18:33], v[88:91], v[104:107], v[18:33]
	s_waitcnt vmcnt(0)
	v_mfma_f32_32x32x16_f16 v[34:49], v[84:87], v[108:111], v[34:49]
	v_mfma_f32_32x32x16_f16 v[2:17], v[88:91], v[108:111], v[2:17]
	s_nop 7
	s_nop 3
	v_mov_b32_e32 v68, v176
	s_lshl_b32 s0, s31, 6
	s_nop 4
	v_cvt_f16_f32_e32 v50, v50
	v_lshrrev_b32_e32 v69, 3, v68
	v_and_b32_e32 v70, 4, v69
	v_and_or_b32 v71, v68, 31, s0
	v_mad_u32_u24 v68, v70, s44, v71
	v_ashrrev_i32_e32 v69, 31, v68
	v_lshl_add_u64 v[68:69], v[68:69], 1, s[34:35]
	v_cvt_f16_f32_e32 v74, v51
	v_mad_u32_u24 v75, v70, s44, s44
	global_store_short v[68:69], v50, off
	v_add_u32_e32 v50, v75, v71
	v_ashrrev_i32_e32 v51, 31, v50
	v_lshl_add_u64 v[50:51], v[50:51], 1, s[34:35]
	global_store_short v[50:51], v74, off
	v_cvt_f16_f32_e32 v52, v52
	v_mad_u32_u24 v74, v70, s44, v191
	v_add_u32_e32 v50, v74, v71
	v_ashrrev_i32_e32 v51, 31, v50
	v_lshl_add_u64 v[50:51], v[50:51], 1, s[34:35]
	global_store_short v[50:51], v52, off
	v_cvt_f16_f32_e32 v52, v53
	v_mad_u32_u24 v53, v70, s44, v192
	v_add_u32_e32 v50, v53, v71
	v_ashrrev_i32_e32 v51, 31, v50
	v_lshl_add_u64 v[50:51], v[50:51], 1, s[34:35]
	global_store_short v[50:51], v52, off
	v_cvt_f16_f32_e32 v52, v54
	v_mad_u32_u24 v54, v70, s44, v193
	v_add_u32_e32 v50, v54, v71
	v_ashrrev_i32_e32 v51, 31, v50
	v_lshl_add_u64 v[50:51], v[50:51], 1, s[34:35]
	global_store_short v[50:51], v52, off
	v_cvt_f16_f32_e32 v52, v55
	v_mad_u32_u24 v55, v70, s44, v194
	v_add_u32_e32 v50, v55, v71
	v_ashrrev_i32_e32 v51, 31, v50
	v_lshl_add_u64 v[50:51], v[50:51], 1, s[34:35]
	global_store_short v[50:51], v52, off
	v_cvt_f16_f32_e32 v52, v56
	v_mad_u32_u24 v56, v70, s44, v195
	v_add_u32_e32 v50, v56, v71
	v_ashrrev_i32_e32 v51, 31, v50
	v_lshl_add_u64 v[50:51], v[50:51], 1, s[34:35]
	global_store_short v[50:51], v52, off
	v_cvt_f16_f32_e32 v52, v57
	v_mad_u32_u24 v57, v70, s44, v196
	v_add_u32_e32 v50, v57, v71
	v_ashrrev_i32_e32 v51, 31, v50
	v_lshl_add_u64 v[50:51], v[50:51], 1, s[34:35]
	global_store_short v[50:51], v52, off
	v_cvt_f16_f32_e32 v52, v58
	v_mad_u32_u24 v58, v70, s44, v197
	v_add_u32_e32 v50, v58, v71
	v_ashrrev_i32_e32 v51, 31, v50
	v_lshl_add_u64 v[50:51], v[50:51], 1, s[34:35]
	global_store_short v[50:51], v52, off
	v_cvt_f16_f32_e32 v52, v59
	v_mad_u32_u24 v59, v70, s44, v198
	v_add_u32_e32 v50, v59, v71
	v_ashrrev_i32_e32 v51, 31, v50
	v_lshl_add_u64 v[50:51], v[50:51], 1, s[34:35]
	global_store_short v[50:51], v52, off
	v_cvt_f16_f32_e32 v52, v60
	v_mad_u32_u24 v60, v70, s44, v199
	v_add_u32_e32 v50, v60, v71
	v_ashrrev_i32_e32 v51, 31, v50
	v_lshl_add_u64 v[50:51], v[50:51], 1, s[34:35]
	global_store_short v[50:51], v52, off
	v_cvt_f16_f32_e32 v52, v61
	v_mad_u32_u24 v61, v70, s44, v200
	v_add_u32_e32 v50, v61, v71
	v_ashrrev_i32_e32 v51, 31, v50
	v_lshl_add_u64 v[50:51], v[50:51], 1, s[34:35]
	global_store_short v[50:51], v52, off
	v_cvt_f16_f32_e32 v52, v62
	v_mad_u32_u24 v62, v70, s44, v201
	v_add_u32_e32 v50, v62, v71
	v_ashrrev_i32_e32 v51, 31, v50
	v_lshl_add_u64 v[50:51], v[50:51], 1, s[34:35]
	global_store_short v[50:51], v52, off
	v_cvt_f16_f32_e32 v52, v63
	v_mad_u32_u24 v63, v70, s44, v202
	v_add_u32_e32 v50, v63, v71
	v_ashrrev_i32_e32 v51, 31, v50
	v_lshl_add_u64 v[50:51], v[50:51], 1, s[34:35]
	global_store_short v[50:51], v52, off
	v_cvt_f16_f32_e32 v52, v64
	v_mad_u32_u24 v64, v70, s44, v203
	v_add_u32_e32 v50, v64, v71
	v_ashrrev_i32_e32 v51, 31, v50
	v_lshl_add_u64 v[50:51], v[50:51], 1, s[34:35]
; DI int otid() { int t = threadIdx.x; asm volatile("" : "+v"(t)); return t; }
; DI bf16_t cv1(float x) { return (bf16_t)(pk2(x, 0.f) & 0xffffu); }
; DI int crow(int i, int h) { return (i & 3) + 8 * (i >> 2) + 4 * h; }
; template <int MT> DI void st_bf16(bf16_t* base, int ld, int d2, int col0, const f32x16 (&acc)[MT][NT]) {
;     const int lane = otid() & 63, r = lane & 31, h = lane >> 5;
; #pragma unroll
;     for (int mi = 0; mi < MT; ++mi)
; #pragma unroll
;         for (int nj = 0; nj < NT; ++nj)
; #pragma unroll
;             for (int i = 0; i < 16; ++i) base[(mi * 32 + crow(i, h) + (mi == 2 ? d2 : 0)) * ld + col0 + nj * 32 + r] = cv1(acc[mi][nj][i]);
; }
	global_store_short v[50:51], v52, off
	v_cvt_f16_f32_e32 v52, v65
	v_mad_u32_u24 v65, v70, s44, v204
	v_add_u32_e32 v50, v65, v71
	v_cvt_f16_f32_e32 v34, v34
	v_ashrrev_i32_e32 v51, 31, v50
	v_lshl_add_u64 v[50:51], v[50:51], 1, s[34:35]
	global_store_short v[50:51], v52, off
	v_or_b32_e32 v50, 32, v71
	v_cvt_f16_f32_e32 v51, v35
	global_store_short v[68:69], v34, off offset:64
	v_add_u32_e32 v34, v75, v50
	v_ashrrev_i32_e32 v35, 31, v34
	v_lshl_add_u64 v[34:35], v[34:35], 1, s[34:35]
	v_cvt_f16_f32_e32 v36, v36
	global_store_short v[34:35], v51, off
	v_add_u32_e32 v34, v74, v50
	v_ashrrev_i32_e32 v35, 31, v34
	v_lshl_add_u64 v[34:35], v[34:35], 1, s[34:35]
	global_store_short v[34:35], v36, off
	v_cvt_f16_f32_e32 v36, v37
	v_add_u32_e32 v34, v53, v50
	v_ashrrev_i32_e32 v35, 31, v34
	v_lshl_add_u64 v[34:35], v[34:35], 1, s[34:35]
	global_store_short v[34:35], v36, off
	v_cvt_f16_f32_e32 v36, v38
	v_add_u32_e32 v34, v54, v50
	v_ashrrev_i32_e32 v35, 31, v34
	v_lshl_add_u64 v[34:35], v[34:35], 1, s[34:35]
	global_store_short v[34:35], v36, off
	v_cvt_f16_f32_e32 v36, v39
	v_add_u32_e32 v34, v55, v50
	v_ashrrev_i32_e32 v35, 31, v34
	v_lshl_add_u64 v[34:35], v[34:35], 1, s[34:35]
	global_store_short v[34:35], v36, off
	v_cvt_f16_f32_e32 v36, v40
	v_add_u32_e32 v34, v56, v50
	v_ashrrev_i32_e32 v35, 31, v34
	v_lshl_add_u64 v[34:35], v[34:35], 1, s[34:35]
	global_store_short v[34:35], v36, off
	v_cvt_f16_f32_e32 v36, v41
	v_add_u32_e32 v34, v57, v50
	v_ashrrev_i32_e32 v35, 31, v34
	v_lshl_add_u64 v[34:35], v[34:35], 1, s[34:35]
	global_store_short v[34:35], v36, off
	v_cvt_f16_f32_e32 v36, v42
	v_add_u32_e32 v34, v58, v50
	v_ashrrev_i32_e32 v35, 31, v34
	v_lshl_add_u64 v[34:35], v[34:35], 1, s[34:35]
	global_store_short v[34:35], v36, off
	v_cvt_f16_f32_e32 v36, v43
	v_add_u32_e32 v34, v59, v50
	v_ashrrev_i32_e32 v35, 31, v34
	v_lshl_add_u64 v[34:35], v[34:35], 1, s[34:35]
	global_store_short v[34:35], v36, off
	v_cvt_f16_f32_e32 v36, v44
	v_add_u32_e32 v34, v60, v50
	v_ashrrev_i32_e32 v35, 31, v34
	v_lshl_add_u64 v[34:35], v[34:35], 1, s[34:35]
	global_store_short v[34:35], v36, off
	v_cvt_f16_f32_e32 v36, v45
	v_add_u32_e32 v34, v61, v50
	v_ashrrev_i32_e32 v35, 31, v34
	v_lshl_add_u64 v[34:35], v[34:35], 1, s[34:35]
	global_store_short v[34:35], v36, off
	v_cvt_f16_f32_e32 v36, v46
	v_add_u32_e32 v34, v62, v50
	v_ashrrev_i32_e32 v35, 31, v34
	v_lshl_add_u64 v[34:35], v[34:35], 1, s[34:35]
	global_store_short v[34:35], v36, off
	v_cvt_f16_f32_e32 v36, v47
	v_add_u32_e32 v34, v63, v50
	v_ashrrev_i32_e32 v35, 31, v34
	v_lshl_add_u64 v[34:35], v[34:35], 1, s[34:35]
	global_store_short v[34:35], v36, off
	v_cvt_f16_f32_e32 v36, v48
	v_add_u32_e32 v34, v64, v50
	v_ashrrev_i32_e32 v35, 31, v34
	v_lshl_add_u64 v[34:35], v[34:35], 1, s[34:35]
	global_store_short v[34:35], v36, off
	v_cvt_f16_f32_e32 v36, v49
	v_add_u32_e32 v34, v65, v50
	v_ashrrev_i32_e32 v35, 31, v34
	v_lshl_add_u64 v[34:35], v[34:35], 1, s[34:35]
	global_store_short v[34:35], v36, off
	v_cvt_f16_f32_e32 v18, v18
	v_mad_u32_u24 v36, v70, s44, v205
	v_add_u32_e32 v34, v36, v71
	v_ashrrev_i32_e32 v35, 31, v34
	v_lshl_add_u64 v[34:35], v[34:35], 1, s[34:35]
	global_store_short v[34:35], v18, off
	v_cvt_f16_f32_e32 v34, v19
	v_mad_u32_u24 v35, v70, s44, v206
	v_add_u32_e32 v18, v35, v71
	v_ashrrev_i32_e32 v19, 31, v18
	v_lshl_add_u64 v[18:19], v[18:19], 1, s[34:35]
	global_store_short v[18:19], v34, off
	v_cvt_f16_f32_e32 v20, v20
	v_mad_u32_u24 v34, v70, s44, v207
	v_add_u32_e32 v18, v34, v71
	v_ashrrev_i32_e32 v19, 31, v18
	v_mul_u32_u24_e32 v73, 0x1600, v70
	v_lshl_add_u64 v[18:19], v[18:19], 1, s[34:35]
	global_store_short v[18:19], v20, off
	v_cvt_f16_f32_e32 v20, v21
	v_or_b32_e32 v21, 0x30200, v73
	v_add_u32_e32 v18, v21, v71
	v_ashrrev_i32_e32 v19, 31, v18
	v_lshl_add_u64 v[18:19], v[18:19], 1, s[34:35]
	global_store_short v[18:19], v20, off
	v_cvt_f16_f32_e32 v20, v22
	v_mad_u32_u24 v22, v70, s44, v208
	v_add_u32_e32 v18, v22, v71
	v_ashrrev_i32_e32 v19, 31, v18
	v_lshl_add_u64 v[18:19], v[18:19], 1, s[34:35]
	global_store_short v[18:19], v20, off
	v_cvt_f16_f32_e32 v20, v23
	v_or_b32_e32 v23, 0x38600, v73
	v_add_u32_e32 v18, v23, v71
	v_ashrrev_i32_e32 v19, 31, v18
	v_lshl_add_u64 v[18:19], v[18:19], 1, s[34:35]
	global_store_short v[18:19], v20, off
	v_cvt_f16_f32_e32 v20, v24
	v_mad_u32_u24 v24, v70, s44, v209
	v_add_u32_e32 v18, v24, v71
	v_ashrrev_i32_e32 v19, 31, v18
	v_lshl_add_u64 v[18:19], v[18:19], 1, s[34:35]
	global_store_short v[18:19], v20, off
	v_cvt_f16_f32_e32 v20, v25
	v_mad_u32_u24 v25, v70, s44, v210
	v_add_u32_e32 v18, v25, v71
	v_ashrrev_i32_e32 v19, 31, v18
	v_lshl_add_u64 v[18:19], v[18:19], 1, s[34:35]
	global_store_short v[18:19], v20, off
	v_cvt_f16_f32_e32 v20, v26
	v_mad_u32_u24 v26, v70, s44, v211
	v_add_u32_e32 v18, v26, v71
	v_ashrrev_i32_e32 v19, 31, v18
; DI int otid() { int t = threadIdx.x; asm volatile("" : "+v"(t)); return t; }
; DI bf16_t cv1(float x) { return (bf16_t)(pk2(x, 0.f) & 0xffffu); }
; DI int crow(int i, int h) { return (i & 3) + 8 * (i >> 2) + 4 * h; }
; template <int MT> DI void st_bf16(bf16_t* base, int ld, int d2, int col0, const f32x16 (&acc)[MT][NT]) {
;     const int lane = otid() & 63, r = lane & 31, h = lane >> 5;
; #pragma unroll
;     for (int mi = 0; mi < MT; ++mi)
; #pragma unroll
;         for (int nj = 0; nj < NT; ++nj)
; #pragma unroll
;             for (int i = 0; i < 16; ++i) base[(mi * 32 + crow(i, h) + (mi == 2 ? d2 : 0)) * ld + col0 + nj * 32 + r] = cv1(acc[mi][nj][i]);
; }
;     DI void operator()(int unit, const f32x16 (&acc)[MT][NT]) const {
;     ...
;         const int lane = otid() & 63, r = lane & 31, h = lane >> 5;
; #pragma unroll
;         for (int mi = 1; mi < MT; ++mi)
; #pragma unroll
;             for (int nj = 0; nj < NT; ++nj)
; #pragma unroll
;                 for (int i = 0; i < 16; ++i) {
;                     const int lr = mi * 32 + crow(i, h), c = unit * UW + nj * 32 + r;
;                     if (mi == 1) { if (lr >= 62) { halo[(lr - 62) * DFF2 + c] = acc[mi][nj][i]; if (pconv) pconv[(lr - 62) * DFF2 + c] = acc[mi][nj][i]; } }
;                     else if ((lr & 15) >= 14) sconv[(((lr - 64) >> 4) * 2 + ((lr & 15) - 14)) * DFF2 + c] = acc[mi][nj][i];
;                 }
	v_lshl_add_u64 v[18:19], v[18:19], 1, s[34:35]
	global_store_short v[18:19], v20, off
	v_cvt_f16_f32_e32 v20, v27
	v_mad_u32_u24 v27, v70, s44, v212
	v_add_u32_e32 v18, v27, v71
	v_ashrrev_i32_e32 v19, 31, v18
	v_lshl_add_u64 v[18:19], v[18:19], 1, s[34:35]
	global_store_short v[18:19], v20, off
	v_cvt_f16_f32_e32 v20, v28
	v_mad_u32_u24 v28, v70, s44, v213
	v_add_u32_e32 v18, v28, v71
	v_ashrrev_i32_e32 v19, 31, v18
	v_lshl_add_u64 v[18:19], v[18:19], 1, s[34:35]
	global_store_short v[18:19], v20, off
	v_cvt_f16_f32_e32 v20, v29
	v_mad_u32_u24 v29, v70, s44, v214
	v_add_u32_e32 v18, v29, v71
	v_ashrrev_i32_e32 v19, 31, v18
	v_lshl_add_u64 v[18:19], v[18:19], 1, s[34:35]
	global_store_short v[18:19], v20, off
	v_cvt_f16_f32_e32 v20, v30
	v_mad_u32_u24 v30, v70, s44, v215
	v_add_u32_e32 v18, v30, v71
	v_ashrrev_i32_e32 v19, 31, v18
	v_lshl_add_u64 v[18:19], v[18:19], 1, s[34:35]
	global_store_short v[18:19], v20, off
	v_cvt_f16_f32_e32 v20, v31
	v_mad_u32_u24 v31, v70, s44, v216
	v_add_u32_e32 v18, v31, v71
	v_ashrrev_i32_e32 v19, 31, v18
	v_lshl_add_u64 v[18:19], v[18:19], 1, s[34:35]
	global_store_short v[18:19], v20, off
	v_cvt_f16_f32_e32 v20, v32
	v_mad_u32_u24 v37, v70, s44, v217
	v_add_u32_e32 v18, v37, v71
	v_ashrrev_i32_e32 v19, 31, v18
	v_lshl_add_u64 v[18:19], v[18:19], 1, s[34:35]
	global_store_short v[18:19], v20, off
	v_cvt_f16_f32_e32 v20, v33
	v_mad_u32_u24 v38, v70, s44, v218
	v_add_u32_e32 v18, v38, v71
	v_ashrrev_i32_e32 v19, 31, v18
	v_lshl_add_u64 v[18:19], v[18:19], 1, s[34:35]
	v_cvt_f16_f32_e32 v2, v2
	global_store_short v[18:19], v20, off
	v_add_u32_e32 v18, v36, v50
	v_ashrrev_i32_e32 v19, 31, v18
	v_lshl_add_u64 v[18:19], v[18:19], 1, s[34:35]
	global_store_short v[18:19], v2, off
	v_cvt_f16_f32_e32 v18, v3
	v_add_u32_e32 v2, v35, v50
	v_ashrrev_i32_e32 v3, 31, v2
	v_lshl_add_u64 v[2:3], v[2:3], 1, s[34:35]
	v_cvt_f16_f32_e32 v4, v4
	global_store_short v[2:3], v18, off
	v_add_u32_e32 v2, v34, v50
	v_ashrrev_i32_e32 v3, 31, v2
	v_lshl_add_u64 v[2:3], v[2:3], 1, s[34:35]
	global_store_short v[2:3], v4, off
	v_cvt_f16_f32_e32 v4, v5
	v_add_u32_e32 v2, v21, v50
	v_ashrrev_i32_e32 v3, 31, v2
	v_lshl_add_u64 v[2:3], v[2:3], 1, s[34:35]
	global_store_short v[2:3], v4, off
	v_cvt_f16_f32_e32 v4, v6
	v_add_u32_e32 v2, v22, v50
	v_ashrrev_i32_e32 v3, 31, v2
	v_lshl_add_u64 v[2:3], v[2:3], 1, s[34:35]
	global_store_short v[2:3], v4, off
	v_cvt_f16_f32_e32 v4, v7
	v_add_u32_e32 v2, v23, v50
	v_ashrrev_i32_e32 v3, 31, v2
	v_lshl_add_u64 v[2:3], v[2:3], 1, s[34:35]
	global_store_short v[2:3], v4, off
	v_cvt_f16_f32_e32 v4, v8
	v_add_u32_e32 v2, v24, v50
	v_ashrrev_i32_e32 v3, 31, v2
	v_lshl_add_u64 v[2:3], v[2:3], 1, s[34:35]
	global_store_short v[2:3], v4, off
	v_cvt_f16_f32_e32 v4, v9
	v_add_u32_e32 v2, v25, v50
	v_ashrrev_i32_e32 v3, 31, v2
	v_lshl_add_u64 v[2:3], v[2:3], 1, s[34:35]
	global_store_short v[2:3], v4, off
	v_cvt_f16_f32_e32 v4, v10
	v_add_u32_e32 v2, v26, v50
	v_ashrrev_i32_e32 v3, 31, v2
	v_lshl_add_u64 v[2:3], v[2:3], 1, s[34:35]
	global_store_short v[2:3], v4, off
	v_cvt_f16_f32_e32 v4, v11
	v_add_u32_e32 v2, v27, v50
	v_ashrrev_i32_e32 v3, 31, v2
	v_lshl_add_u64 v[2:3], v[2:3], 1, s[34:35]
	global_store_short v[2:3], v4, off
	v_cvt_f16_f32_e32 v4, v12
	v_add_u32_e32 v2, v28, v50
	v_ashrrev_i32_e32 v3, 31, v2
	v_lshl_add_u64 v[2:3], v[2:3], 1, s[34:35]
	global_store_short v[2:3], v4, off
	v_cvt_f16_f32_e32 v4, v13
	v_add_u32_e32 v2, v29, v50
	v_ashrrev_i32_e32 v3, 31, v2
	v_lshl_add_u64 v[2:3], v[2:3], 1, s[34:35]
	global_store_short v[2:3], v4, off
	v_cvt_f16_f32_e32 v4, v14
	v_add_u32_e32 v2, v30, v50
	v_ashrrev_i32_e32 v3, 31, v2
	v_lshl_add_u64 v[2:3], v[2:3], 1, s[34:35]
	global_store_short v[2:3], v4, off
	v_cvt_f16_f32_e32 v4, v15
	v_add_u32_e32 v2, v31, v50
	v_ashrrev_i32_e32 v3, 31, v2
	v_lshl_add_u64 v[2:3], v[2:3], 1, s[34:35]
	global_store_short v[2:3], v4, off
	v_cvt_f16_f32_e32 v4, v16
	v_add_u32_e32 v2, v37, v50
	v_ashrrev_i32_e32 v3, 31, v2
	v_lshl_add_u64 v[2:3], v[2:3], 1, s[34:35]
	global_store_short v[2:3], v4, off
	v_cvt_f16_f32_e32 v4, v17
	v_add_u32_e32 v2, v38, v50
	v_ashrrev_i32_e32 v3, 31, v2
	v_lshl_add_u64 v[2:3], v[2:3], 1, s[34:35]
	global_store_short v[2:3], v4, off
	v_mov_b32_e32 v2, v176
	s_add_i32 s0, s0, 0xfffd6c00
	v_lshrrev_b32_e32 v3, 3, v2
	v_and_or_b32 v6, v2, 31, s0
	v_and_b32_e32 v2, 32, v2
	v_and_b32_e32 v5, 4, v3
	v_cmp_ne_u32_e64 s[4:5], 0, v2
	v_cndmask_b32_e64 v2, 0, 1, s[28:29]
	v_or_b32_e32 v4, 26, v5
	v_cmp_ne_u32_e64 s[0:1], 1, v2
	s_and_saveexec_b64 s[2:3], s[4:5]
	s_cbranch_execz .LBB0_545
	v_mad_u32_u24 v2, v4, s44, v6
	v_ashrrev_i32_e32 v3, 31, v2
	v_lshl_add_u64 v[8:9], v[2:3], 2, s[8:9]
	s_and_b64 vcc, exec, s[0:1]
	global_store_dword v[8:9], v32, off
	s_cbranch_vccnz .LBB0_545
	v_lshl_add_u64 v[2:3], v[2:3], 2, s[58:59]
	global_store_dword v[2:3], v32, off

; DI int otid() { int t = threadIdx.x; asm volatile("" : "+v"(t)); return t; }
; DI int crow(int i, int h) { return (i & 3) + 8 * (i >> 2) + 4 * h; }
;     DI void operator()(int unit, const f32x16 (&acc)[MT][NT]) const {
;         const int lane = otid() & 63, r = lane & 31, h = lane >> 5;
; #pragma unroll
;         for (int mi = 0; mi < MT; ++mi)
; #pragma unroll
;             for (int nj = 0; nj < NT; ++nj)
; #pragma unroll
;                 for (int i = 0; i < 16; ++i) { float* q = x + ((mi * 32 + crow(i, h) + (mi == 2 ? d2 : 0)) * DM + unit * UW + nj * 32 + r); *q = *q + acc[mi][nj][i]; if (i == 15) __builtin_amdgcn_sched_barrier(0); }
;     }
.LBB0_814:
	s_and_saveexec_b64 s[56:57], s[6:7]
	s_cbranch_execz .LBB0_803
	s_waitcnt vmcnt(0)
	v_and_b32_e32 v2, 31, v176
	v_lshlrev_b32_e32 v112, 9, v176
	v_and_b32_e32 v112, 0x4000, v112
	v_lshl_or_b32 v113, v2, 2, v112
	v_lshl_add_u32 v113, v232, 8, v113
	v_add_u32_e32 v114, 0x1000, v113
	global_load_dword v123, v114, s[8:9] offset:-4096
	global_load_dword v124, v114, s[8:9] offset:-3968
	global_load_dword v125, v114, s[8:9] offset:0
	global_load_dword v126, v114, s[8:9] offset:128
	v_add_u32_e32 v116, 0x3000, v113
	global_load_dword v127, v116, s[8:9] offset:-4096
	global_load_dword v128, v116, s[8:9] offset:-3968
	global_load_dword v129, v116, s[8:9] offset:0
	global_load_dword v130, v116, s[8:9] offset:128
	v_add_u32_e32 v117, 0x9000, v113
	global_load_dword v131, v117, s[8:9] offset:-4096
	global_load_dword v132, v117, s[8:9] offset:-3968
	global_load_dword v133, v117, s[8:9] offset:0
	global_load_dword v134, v117, s[8:9] offset:128
	v_add_u32_e32 v118, 0xb000, v113
	global_load_dword v135, v118, s[8:9] offset:-4096
	global_load_dword v136, v118, s[8:9] offset:-3968
	global_load_dword v137, v118, s[8:9] offset:0
	global_load_dword v138, v118, s[8:9] offset:128
	v_add_u32_e32 v119, 0x11000, v113
	global_load_dword v139, v119, s[8:9] offset:-4096
	global_load_dword v140, v119, s[8:9] offset:-3968
	global_load_dword v141, v119, s[8:9] offset:0
	global_load_dword v142, v119, s[8:9] offset:128
	v_add_u32_e32 v120, 0x13000, v113
	global_load_dword v143, v120, s[8:9] offset:-4096
	global_load_dword v144, v120, s[8:9] offset:-3968
	global_load_dword v145, v120, s[8:9] offset:0
	global_load_dword v146, v120, s[8:9] offset:128
	v_add_u32_e32 v121, 0x19000, v113
	global_load_dword v147, v121, s[8:9] offset:-4096
	global_load_dword v148, v121, s[8:9] offset:-3968
	global_load_dword v149, v121, s[8:9] offset:0
	global_load_dword v150, v121, s[8:9] offset:128
	v_add_u32_e32 v122, 0x1b000, v113
	global_load_dword v151, v122, s[8:9] offset:-4096
	global_load_dword v152, v122, s[8:9] offset:-3968
	global_load_dword v153, v122, s[8:9] offset:0
	global_load_dword v154, v122, s[8:9] offset:128
	s_waitcnt vmcnt(0)
	v_add_f32_e32 v123, v96, v123
	global_store_dword v114, v123, s[8:9] offset:-4096
	v_add_f32_e32 v124, v80, v124
	global_store_dword v114, v124, s[8:9] offset:-3968
	v_add_f32_e32 v125, v97, v125
	global_store_dword v114, v125, s[8:9] offset:0
	v_add_f32_e32 v126, v81, v126
	global_store_dword v114, v126, s[8:9] offset:128
	v_add_f32_e32 v127, v98, v127
	global_store_dword v116, v127, s[8:9] offset:-4096
	v_add_f32_e32 v128, v82, v128
	global_store_dword v116, v128, s[8:9] offset:-3968
	v_add_f32_e32 v129, v99, v129
	global_store_dword v116, v129, s[8:9] offset:0
	v_add_f32_e32 v130, v83, v130
	global_store_dword v116, v130, s[8:9] offset:128
	v_add_f32_e32 v131, v100, v131
	global_store_dword v117, v131, s[8:9] offset:-4096
	v_add_f32_e32 v132, v84, v132
	global_store_dword v117, v132, s[8:9] offset:-3968
	v_add_f32_e32 v133, v101, v133
	global_store_dword v117, v133, s[8:9] offset:0
	v_add_f32_e32 v134, v85, v134
	global_store_dword v117, v134, s[8:9] offset:128
	v_add_f32_e32 v135, v102, v135
	global_store_dword v118, v135, s[8:9] offset:-4096
	v_add_f32_e32 v136, v86, v136
	global_store_dword v118, v136, s[8:9] offset:-3968
	v_add_f32_e32 v137, v103, v137
	global_store_dword v118, v137, s[8:9] offset:0
	v_add_f32_e32 v138, v87, v138
	global_store_dword v118, v138, s[8:9] offset:128
	v_add_f32_e32 v139, v104, v139
	global_store_dword v119, v139, s[8:9] offset:-4096
	v_add_f32_e32 v140, v88, v140
	global_store_dword v119, v140, s[8:9] offset:-3968
	v_add_f32_e32 v141, v105, v141
	global_store_dword v119, v141, s[8:9] offset:0
	v_add_f32_e32 v142, v89, v142
	global_store_dword v119, v142, s[8:9] offset:128
	v_add_f32_e32 v143, v106, v143
	global_store_dword v120, v143, s[8:9] offset:-4096
	v_add_f32_e32 v144, v90, v144
	global_store_dword v120, v144, s[8:9] offset:-3968
	v_add_f32_e32 v145, v107, v145
	global_store_dword v120, v145, s[8:9] offset:0
	v_add_f32_e32 v146, v91, v146
	global_store_dword v120, v146, s[8:9] offset:128
	v_add_f32_e32 v147, v108, v147
	global_store_dword v121, v147, s[8:9] offset:-4096
	v_add_f32_e32 v148, v92, v148
	global_store_dword v121, v148, s[8:9] offset:-3968
	v_add_f32_e32 v149, v109, v149
	global_store_dword v121, v149, s[8:9] offset:0
	v_add_f32_e32 v150, v93, v150
	global_store_dword v121, v150, s[8:9] offset:128
	v_add_f32_e32 v151, v110, v151
	global_store_dword v122, v151, s[8:9] offset:-4096
	v_add_f32_e32 v152, v94, v152
	global_store_dword v122, v152, s[8:9] offset:-3968
	v_add_f32_e32 v153, v111, v153
	global_store_dword v122, v153, s[8:9] offset:0
	v_add_f32_e32 v154, v95, v154
	global_store_dword v122, v154, s[8:9] offset:128
	v_add_u32_e32 v114, 0x21000, v113
	global_load_dword v123, v114, s[8:9] offset:-4096
	global_load_dword v124, v114, s[8:9] offset:-3968
	global_load_dword v125, v114, s[8:9] offset:0
	global_load_dword v126, v114, s[8:9] offset:128
	v_add_u32_e32 v116, 0x23000, v113
	global_load_dword v127, v116, s[8:9] offset:-4096
	global_load_dword v128, v116, s[8:9] offset:-3968
	global_load_dword v129, v116, s[8:9] offset:0
	global_load_dword v130, v116, s[8:9] offset:128
	v_add_u32_e32 v117, 0x29000, v113
	global_load_dword v131, v117, s[8:9] offset:-4096
	global_load_dword v132, v117, s[8:9] offset:-3968
	global_load_dword v133, v117, s[8:9] offset:0
	global_load_dword v134, v117, s[8:9] offset:128
	v_add_u32_e32 v118, 0x2b000, v113
	global_load_dword v135, v118, s[8:9] offset:-4096
	global_load_dword v136, v118, s[8:9] offset:-3968
	global_load_dword v137, v118, s[8:9] offset:0
	global_load_dword v138, v118, s[8:9] offset:128
	v_add_u32_e32 v119, 0x31000, v113
	global_load_dword v139, v119, s[8:9] offset:-4096
	global_load_dword v140, v119, s[8:9] offset:-3968
	global_load_dword v141, v119, s[8:9] offset:0
	global_load_dword v142, v119, s[8:9] offset:128
	v_add_u32_e32 v120, 0x33000, v113
	global_load_dword v143, v120, s[8:9] offset:-4096
	global_load_dword v144, v120, s[8:9] offset:-3968
	global_load_dword v145, v120, s[8:9] offset:0
	global_load_dword v146, v120, s[8:9] offset:128
	v_add_u32_e32 v121, 0x39000, v113
	global_load_dword v147, v121, s[8:9] offset:-4096
	global_load_dword v148, v121, s[8:9] offset:-3968
	global_load_dword v149, v121, s[8:9] offset:0
	global_load_dword v150, v121, s[8:9] offset:128
	v_add_u32_e32 v122, 0x3b000, v113
	global_load_dword v151, v122, s[8:9] offset:-4096
	global_load_dword v152, v122, s[8:9] offset:-3968
	global_load_dword v153, v122, s[8:9] offset:0
	global_load_dword v154, v122, s[8:9] offset:128
	s_waitcnt vmcnt(0)
; DI int otid() { int t = threadIdx.x; asm volatile("" : "+v"(t)); return t; }
; DI int crow(int i, int h) { return (i & 3) + 8 * (i >> 2) + 4 * h; }
;     DI void operator()(int unit, const f32x16 (&acc)[MT][NT]) const {
;         const int lane = otid() & 63, r = lane & 31, h = lane >> 5;
; #pragma unroll
;         for (int mi = 0; mi < MT; ++mi)
; #pragma unroll
;             for (int nj = 0; nj < NT; ++nj)
; #pragma unroll
;                 for (int i = 0; i < 16; ++i) { float* q = x + ((mi * 32 + crow(i, h) + (mi == 2 ? d2 : 0)) * DM + unit * UW + nj * 32 + r); *q = *q + acc[mi][nj][i]; if (i == 15) __builtin_amdgcn_sched_barrier(0); }
;     }
	v_add_f32_e32 v123, v64, v123
	global_store_dword v114, v123, s[8:9] offset:-4096
	v_add_f32_e32 v124, v48, v124
	global_store_dword v114, v124, s[8:9] offset:-3968
	v_add_f32_e32 v125, v65, v125
	global_store_dword v114, v125, s[8:9] offset:0
	v_add_f32_e32 v126, v49, v126
	global_store_dword v114, v126, s[8:9] offset:128
	v_add_f32_e32 v127, v66, v127
	global_store_dword v116, v127, s[8:9] offset:-4096
	v_add_f32_e32 v128, v50, v128
	global_store_dword v116, v128, s[8:9] offset:-3968
	v_add_f32_e32 v129, v67, v129
	global_store_dword v116, v129, s[8:9] offset:0
	v_add_f32_e32 v130, v51, v130
	global_store_dword v116, v130, s[8:9] offset:128
	v_add_f32_e32 v131, v68, v131
	global_store_dword v117, v131, s[8:9] offset:-4096
	v_add_f32_e32 v132, v52, v132
	global_store_dword v117, v132, s[8:9] offset:-3968
	v_add_f32_e32 v133, v69, v133
	global_store_dword v117, v133, s[8:9] offset:0
	v_add_f32_e32 v134, v53, v134
	global_store_dword v117, v134, s[8:9] offset:128
	v_add_f32_e32 v135, v70, v135
	global_store_dword v118, v135, s[8:9] offset:-4096
	v_add_f32_e32 v136, v54, v136
	global_store_dword v118, v136, s[8:9] offset:-3968
	v_add_f32_e32 v137, v71, v137
	global_store_dword v118, v137, s[8:9] offset:0
	v_add_f32_e32 v138, v55, v138
	global_store_dword v118, v138, s[8:9] offset:128
	v_add_f32_e32 v139, v72, v139
	global_store_dword v119, v139, s[8:9] offset:-4096
	v_add_f32_e32 v140, v56, v140
	global_store_dword v119, v140, s[8:9] offset:-3968
	v_add_f32_e32 v141, v73, v141
	global_store_dword v119, v141, s[8:9] offset:0
	v_add_f32_e32 v142, v57, v142
	global_store_dword v119, v142, s[8:9] offset:128
	v_add_f32_e32 v143, v74, v143
	global_store_dword v120, v143, s[8:9] offset:-4096
	v_add_f32_e32 v144, v58, v144
	global_store_dword v120, v144, s[8:9] offset:-3968
	v_add_f32_e32 v145, v75, v145
	global_store_dword v120, v145, s[8:9] offset:0
	v_add_f32_e32 v146, v59, v146
	global_store_dword v120, v146, s[8:9] offset:128
	v_add_f32_e32 v147, v76, v147
	global_store_dword v121, v147, s[8:9] offset:-4096
	v_add_f32_e32 v148, v60, v148
	global_store_dword v121, v148, s[8:9] offset:-3968
	v_add_f32_e32 v149, v77, v149
	global_store_dword v121, v149, s[8:9] offset:0
	v_add_f32_e32 v150, v61, v150
	global_store_dword v121, v150, s[8:9] offset:128
	v_add_f32_e32 v151, v78, v151
	global_store_dword v122, v151, s[8:9] offset:-4096
	v_add_f32_e32 v152, v62, v152
	global_store_dword v122, v152, s[8:9] offset:-3968
	v_add_f32_e32 v153, v79, v153
	global_store_dword v122, v153, s[8:9] offset:0
	v_add_f32_e32 v154, v63, v154
	global_store_dword v122, v154, s[8:9] offset:128
	s_sub_i32 s100, 0x4000, s94
	v_lshl_add_u32 v112, s100, 12, v113
	v_add_u32_e32 v114, 0x1000, v112
	global_load_dword v123, v114, s[8:9] offset:-4096
	global_load_dword v124, v114, s[8:9] offset:-3968
	global_load_dword v125, v114, s[8:9] offset:0
	global_load_dword v126, v114, s[8:9] offset:128
	v_add_u32_e32 v116, 0x3000, v112
	global_load_dword v127, v116, s[8:9] offset:-4096
	global_load_dword v128, v116, s[8:9] offset:-3968
	global_load_dword v129, v116, s[8:9] offset:0
	global_load_dword v130, v116, s[8:9] offset:128
	v_add_u32_e32 v117, 0x9000, v112
	global_load_dword v131, v117, s[8:9] offset:-4096
	global_load_dword v132, v117, s[8:9] offset:-3968
	global_load_dword v133, v117, s[8:9] offset:0
	global_load_dword v134, v117, s[8:9] offset:128
	v_add_u32_e32 v118, 0xb000, v112
	global_load_dword v135, v118, s[8:9] offset:-4096
	global_load_dword v136, v118, s[8:9] offset:-3968
	global_load_dword v137, v118, s[8:9] offset:0
	global_load_dword v138, v118, s[8:9] offset:128
	v_add_u32_e32 v119, 0x11000, v112
	global_load_dword v139, v119, s[8:9] offset:-4096
	global_load_dword v140, v119, s[8:9] offset:-3968
	global_load_dword v141, v119, s[8:9] offset:0
	global_load_dword v142, v119, s[8:9] offset:128
	v_add_u32_e32 v120, 0x13000, v112
	global_load_dword v143, v120, s[8:9] offset:-4096
	global_load_dword v144, v120, s[8:9] offset:-3968
	global_load_dword v145, v120, s[8:9] offset:0
	global_load_dword v146, v120, s[8:9] offset:128
	v_add_u32_e32 v121, 0x19000, v112
	global_load_dword v147, v121, s[8:9] offset:-4096
	global_load_dword v148, v121, s[8:9] offset:-3968
	global_load_dword v149, v121, s[8:9] offset:0
	global_load_dword v150, v121, s[8:9] offset:128
	v_add_u32_e32 v122, 0x1b000, v112
	global_load_dword v151, v122, s[8:9] offset:-4096
	global_load_dword v152, v122, s[8:9] offset:-3968
	global_load_dword v153, v122, s[8:9] offset:0
	global_load_dword v154, v122, s[8:9] offset:128
	s_waitcnt vmcnt(0)
;     ...
;     for (int pass = 0; pass * NWAVE < NU; ++pass) {
;         const int unit = pass * NWAVE + wave;
;         const bool active = unit < NU;
;         const int ucl = active ? unit : NU - 1;
;         const u32x4* bp = Bw + (size_t)(ucl * NT) * 64 + lane;
;         const size_t kstr = (size_t)NU * NT * 64;
;         f32x16 acc[MT][NT];
; #pragma unroll
;         for (int mi = 0; mi < MT; ++mi)
; #pragma unroll
;             for (int nj = 0; nj < NT; ++nj)
; #pragma unroll
;                 for (int i = 0; i < 16; ++i) acc[mi][nj][i] = 0.f;
;         u32x4 bq[PD][NT];
; #pragma unroll
;         for (int s = 0; s < PD; ++s)
; #pragma unroll
;             for (int j = 0; j < NT; ++j) bq[s][j] = bp[(size_t)s * kstr + j * 64];
;         u32x4 areg[MT];
;         if (pass == 0) __syncthreads();
; #pragma unroll
;         for (int i = 0; i < MT; ++i) { const int idx = i * NTHR + tid, row = idx >> 4, seg = idx & 15; areg[i] = *(const u32x4*)(A + ((row + (i == 2 ? d2 : 0)) * lda + seg * 8)); }
; #pragma unroll
;         for (int i = 0; i < MT; ++i) { const int idx = i * NTHR + tid, row = idx >> 4, seg = idx & 15; *(u32x4*)(lds + row * A_LD + seg * 16) = areg[i]; }
;         lds_barrier();
; #pragma unroll 1
;         for (int c = 0; c < NCH; ++c) {
;             if (c + 1 < NCH) {
; #pragma unroll
;                 for (int i = 0; i < MT; ++i) { const int idx = i * NTHR + tid, row = idx >> 4, seg = idx & 15; areg[i] = *(const u32x4*)(A + ((row + (i == 2 ? d2 : 0)) * lda + (c + 1) * A_CHUNK + seg * 8)); }
;             }
;             const unsigned char* ab = lds + (c & 1) * A_BUF + r * A_LD + 16 * h;
;             if (active) {
;                 bf16x8 a[MT], n[MT];
; #pragma unroll
;                 for (int mi = 0; mi < MT; ++mi) a[mi] = *(const bf16x8*)(ab + mi * 32 * A_LD);
; #pragma unroll
;                 for (int ks = 0; ks < A_CHUNK / 16; ++ks) {
;     DI void operator()(int unit, const f32x16 (&acc)[MT][NT]) const {
;         const int lane = otid() & 63, r = lane & 31, h = lane >> 5;
; #pragma unroll
;         for (int mi = 0; mi < MT; ++mi)
; #pragma unroll
;             for (int nj = 0; nj < NT; ++nj)
; #pragma unroll
;                 for (int i = 0; i < 16; ++i) { float* q = x + ((mi * 32 + crow(i, h) + (mi == 2 ? d2 : 0)) * DM + unit * UW + nj * 32 + r); *q = *q + acc[mi][nj][i]; if (i == 15) __builtin_amdgcn_sched_barrier(0); }
;     }
	v_add_f32_e32 v123, v32, v123
	global_store_dword v114, v123, s[8:9] offset:-4096
	v_add_f32_e32 v124, v16, v124
	global_store_dword v114, v124, s[8:9] offset:-3968
	v_add_f32_e32 v125, v33, v125
	global_store_dword v114, v125, s[8:9] offset:0
	v_add_f32_e32 v126, v17, v126
	global_store_dword v114, v126, s[8:9] offset:128
	v_add_f32_e32 v127, v34, v127
	global_store_dword v116, v127, s[8:9] offset:-4096
	v_add_f32_e32 v128, v18, v128
	global_store_dword v116, v128, s[8:9] offset:-3968
	v_add_f32_e32 v129, v35, v129
	global_store_dword v116, v129, s[8:9] offset:0
	v_add_f32_e32 v130, v19, v130
	global_store_dword v116, v130, s[8:9] offset:128
	v_add_f32_e32 v131, v36, v131
	global_store_dword v117, v131, s[8:9] offset:-4096
	v_add_f32_e32 v132, v20, v132
	global_store_dword v117, v132, s[8:9] offset:-3968
	v_add_f32_e32 v133, v37, v133
	global_store_dword v117, v133, s[8:9] offset:0
	v_add_f32_e32 v134, v21, v134
	global_store_dword v117, v134, s[8:9] offset:128
	v_add_f32_e32 v135, v38, v135
	global_store_dword v118, v135, s[8:9] offset:-4096
	v_add_f32_e32 v136, v22, v136
	global_store_dword v118, v136, s[8:9] offset:-3968
	v_add_f32_e32 v137, v39, v137
	global_store_dword v118, v137, s[8:9] offset:0
	v_add_f32_e32 v138, v23, v138
	global_store_dword v118, v138, s[8:9] offset:128
	v_add_f32_e32 v139, v40, v139
	global_store_dword v119, v139, s[8:9] offset:-4096
	v_add_f32_e32 v140, v24, v140
	global_store_dword v119, v140, s[8:9] offset:-3968
	v_add_f32_e32 v141, v41, v141
	global_store_dword v119, v141, s[8:9] offset:0
	v_add_f32_e32 v142, v25, v142
	global_store_dword v119, v142, s[8:9] offset:128
	v_add_f32_e32 v143, v42, v143
	global_store_dword v120, v143, s[8:9] offset:-4096
	v_add_f32_e32 v144, v26, v144
	global_store_dword v120, v144, s[8:9] offset:-3968
	v_add_f32_e32 v145, v43, v145
	global_store_dword v120, v145, s[8:9] offset:0
	v_add_f32_e32 v146, v27, v146
	global_store_dword v120, v146, s[8:9] offset:128
	v_add_f32_e32 v147, v44, v147
	global_store_dword v121, v147, s[8:9] offset:-4096
	v_add_f32_e32 v148, v28, v148
	global_store_dword v121, v148, s[8:9] offset:-3968
	v_add_f32_e32 v149, v45, v149
	global_store_dword v121, v149, s[8:9] offset:0
	v_add_f32_e32 v150, v29, v150
	global_store_dword v121, v150, s[8:9] offset:128
	v_add_f32_e32 v151, v46, v151
	global_store_dword v122, v151, s[8:9] offset:-4096
	v_add_f32_e32 v152, v30, v152
	global_store_dword v122, v152, s[8:9] offset:-3968
	v_add_f32_e32 v153, v47, v153
	global_store_dword v122, v153, s[8:9] offset:0
	v_add_f32_e32 v154, v31, v154
	global_store_dword v122, v154, s[8:9] offset:128
	s_waitcnt vmcnt(0)
	s_branch .LBB0_803

; DI int otid() { int t = threadIdx.x; asm volatile("" : "+v"(t)); return t; }
; DI int crow(int i, int h) { return (i & 3) + 8 * (i >> 2) + 4 * h; }
;     DI void operator()(int unit, const f32x16 (&acc)[MT][NT]) const {
;         const int lane = otid() & 63, r = lane & 31, h = lane >> 5;
; #pragma unroll
;         for (int mi = 0; mi < MT; ++mi)
; #pragma unroll
;             for (int nj = 0; nj < NT; ++nj)
; #pragma unroll
;                 for (int i = 0; i < 16; ++i) { float* q = x + ((mi * 32 + crow(i, h) + (mi == 2 ? d2 : 0)) * DM + unit * UW + nj * 32 + r); *q = *q + acc[mi][nj][i]; if (i == 15) __builtin_amdgcn_sched_barrier(0); }
;     }
.LBB0_879:
	s_and_saveexec_b64 s[56:57], s[6:7]
	s_cbranch_execz .LBB0_868
	s_waitcnt vmcnt(0)
	v_and_b32_e32 v2, 31, v176
	v_lshlrev_b32_e32 v80, 9, v176
	v_and_b32_e32 v80, 0x4000, v80
	v_lshl_or_b32 v81, v2, 2, v80
	v_lshl_add_u32 v81, v143, 8, v81
	v_add_u32_e32 v82, 0x1000, v81
	global_load_dword v90, v82, s[8:9] offset:-4096
	global_load_dword v91, v82, s[8:9] offset:-3968
	global_load_dword v92, v82, s[8:9] offset:0
	global_load_dword v93, v82, s[8:9] offset:128
	v_add_u32_e32 v83, 0x3000, v81
	global_load_dword v94, v83, s[8:9] offset:-4096
	global_load_dword v95, v83, s[8:9] offset:-3968
	global_load_dword v96, v83, s[8:9] offset:0
	global_load_dword v97, v83, s[8:9] offset:128
	v_add_u32_e32 v84, 0x9000, v81
	global_load_dword v98, v84, s[8:9] offset:-4096
	global_load_dword v99, v84, s[8:9] offset:-3968
	global_load_dword v100, v84, s[8:9] offset:0
	global_load_dword v101, v84, s[8:9] offset:128
	v_add_u32_e32 v85, 0xb000, v81
	global_load_dword v102, v85, s[8:9] offset:-4096
	global_load_dword v103, v85, s[8:9] offset:-3968
	global_load_dword v104, v85, s[8:9] offset:0
	global_load_dword v105, v85, s[8:9] offset:128
	v_add_u32_e32 v86, 0x11000, v81
	global_load_dword v106, v86, s[8:9] offset:-4096
	global_load_dword v107, v86, s[8:9] offset:-3968
	global_load_dword v108, v86, s[8:9] offset:0
	global_load_dword v109, v86, s[8:9] offset:128
	v_add_u32_e32 v87, 0x13000, v81
	global_load_dword v110, v87, s[8:9] offset:-4096
	global_load_dword v111, v87, s[8:9] offset:-3968
	global_load_dword v112, v87, s[8:9] offset:0
	global_load_dword v113, v87, s[8:9] offset:128
	v_add_u32_e32 v88, 0x19000, v81
	global_load_dword v114, v88, s[8:9] offset:-4096
	global_load_dword v116, v88, s[8:9] offset:-3968
	global_load_dword v117, v88, s[8:9] offset:0
	global_load_dword v118, v88, s[8:9] offset:128
	v_add_u32_e32 v89, 0x1b000, v81
	global_load_dword v119, v89, s[8:9] offset:-4096
	global_load_dword v128, v89, s[8:9] offset:-3968
	global_load_dword v129, v89, s[8:9] offset:0
	global_load_dword v130, v89, s[8:9] offset:128
	s_waitcnt vmcnt(0)
	v_add_f32_e32 v90, v64, v90
	global_store_dword v82, v90, s[8:9] offset:-4096
	v_add_f32_e32 v91, v48, v91
	global_store_dword v82, v91, s[8:9] offset:-3968
	v_add_f32_e32 v92, v65, v92
	global_store_dword v82, v92, s[8:9] offset:0
	v_add_f32_e32 v93, v49, v93
	global_store_dword v82, v93, s[8:9] offset:128
	v_add_f32_e32 v94, v66, v94
	global_store_dword v83, v94, s[8:9] offset:-4096
	v_add_f32_e32 v95, v50, v95
	global_store_dword v83, v95, s[8:9] offset:-3968
	v_add_f32_e32 v96, v67, v96
	global_store_dword v83, v96, s[8:9] offset:0
	v_add_f32_e32 v97, v51, v97
	global_store_dword v83, v97, s[8:9] offset:128
	v_add_f32_e32 v98, v68, v98
	global_store_dword v84, v98, s[8:9] offset:-4096
	v_add_f32_e32 v99, v52, v99
	global_store_dword v84, v99, s[8:9] offset:-3968
	v_add_f32_e32 v100, v69, v100
	global_store_dword v84, v100, s[8:9] offset:0
	v_add_f32_e32 v101, v53, v101
	global_store_dword v84, v101, s[8:9] offset:128
	v_add_f32_e32 v102, v70, v102
	global_store_dword v85, v102, s[8:9] offset:-4096
	v_add_f32_e32 v103, v54, v103
	global_store_dword v85, v103, s[8:9] offset:-3968
	v_add_f32_e32 v104, v71, v104
	global_store_dword v85, v104, s[8:9] offset:0
	v_add_f32_e32 v105, v55, v105
	global_store_dword v85, v105, s[8:9] offset:128
	v_add_f32_e32 v106, v72, v106
	global_store_dword v86, v106, s[8:9] offset:-4096
	v_add_f32_e32 v107, v56, v107
	global_store_dword v86, v107, s[8:9] offset:-3968
	v_add_f32_e32 v108, v73, v108
	global_store_dword v86, v108, s[8:9] offset:0
	v_add_f32_e32 v109, v57, v109
	global_store_dword v86, v109, s[8:9] offset:128
	v_add_f32_e32 v110, v74, v110
	global_store_dword v87, v110, s[8:9] offset:-4096
	v_add_f32_e32 v111, v58, v111
	global_store_dword v87, v111, s[8:9] offset:-3968
	v_add_f32_e32 v112, v75, v112
	global_store_dword v87, v112, s[8:9] offset:0
	v_add_f32_e32 v113, v59, v113
	global_store_dword v87, v113, s[8:9] offset:128
	v_add_f32_e32 v114, v76, v114
	global_store_dword v88, v114, s[8:9] offset:-4096
	v_add_f32_e32 v116, v60, v116
	global_store_dword v88, v116, s[8:9] offset:-3968
	v_add_f32_e32 v117, v77, v117
	global_store_dword v88, v117, s[8:9] offset:0
	v_add_f32_e32 v118, v61, v118
	global_store_dword v88, v118, s[8:9] offset:128
	v_add_f32_e32 v119, v78, v119
	global_store_dword v89, v119, s[8:9] offset:-4096
	v_add_f32_e32 v128, v62, v128
	global_store_dword v89, v128, s[8:9] offset:-3968
	v_add_f32_e32 v129, v79, v129
	global_store_dword v89, v129, s[8:9] offset:0
	v_add_f32_e32 v130, v63, v130
	global_store_dword v89, v130, s[8:9] offset:128
	v_add_u32_e32 v82, 0x21000, v81
	global_load_dword v90, v82, s[8:9] offset:-4096
	global_load_dword v91, v82, s[8:9] offset:-3968
	global_load_dword v92, v82, s[8:9] offset:0
	global_load_dword v93, v82, s[8:9] offset:128
	v_add_u32_e32 v83, 0x23000, v81
	global_load_dword v94, v83, s[8:9] offset:-4096
	global_load_dword v95, v83, s[8:9] offset:-3968
	global_load_dword v96, v83, s[8:9] offset:0
	global_load_dword v97, v83, s[8:9] offset:128
	v_add_u32_e32 v84, 0x29000, v81
	global_load_dword v98, v84, s[8:9] offset:-4096
	global_load_dword v99, v84, s[8:9] offset:-3968
	global_load_dword v100, v84, s[8:9] offset:0
	global_load_dword v101, v84, s[8:9] offset:128
	v_add_u32_e32 v85, 0x2b000, v81
	global_load_dword v102, v85, s[8:9] offset:-4096
	global_load_dword v103, v85, s[8:9] offset:-3968
	global_load_dword v104, v85, s[8:9] offset:0
	global_load_dword v105, v85, s[8:9] offset:128
	v_add_u32_e32 v86, 0x31000, v81
	global_load_dword v106, v86, s[8:9] offset:-4096
	global_load_dword v107, v86, s[8:9] offset:-3968
	global_load_dword v108, v86, s[8:9] offset:0
	global_load_dword v109, v86, s[8:9] offset:128
	v_add_u32_e32 v87, 0x33000, v81
	global_load_dword v110, v87, s[8:9] offset:-4096
	global_load_dword v111, v87, s[8:9] offset:-3968
	global_load_dword v112, v87, s[8:9] offset:0
	global_load_dword v113, v87, s[8:9] offset:128
	v_add_u32_e32 v88, 0x39000, v81
	global_load_dword v114, v88, s[8:9] offset:-4096
	global_load_dword v116, v88, s[8:9] offset:-3968
	global_load_dword v117, v88, s[8:9] offset:0
	global_load_dword v118, v88, s[8:9] offset:128
	v_add_u32_e32 v89, 0x3b000, v81
	global_load_dword v119, v89, s[8:9] offset:-4096
	global_load_dword v128, v89, s[8:9] offset:-3968
	global_load_dword v129, v89, s[8:9] offset:0
	global_load_dword v130, v89, s[8:9] offset:128
	s_waitcnt vmcnt(0)
; DI int otid() { int t = threadIdx.x; asm volatile("" : "+v"(t)); return t; }
; DI int crow(int i, int h) { return (i & 3) + 8 * (i >> 2) + 4 * h; }
;     DI void operator()(int unit, const f32x16 (&acc)[MT][NT]) const {
;         const int lane = otid() & 63, r = lane & 31, h = lane >> 5;
; #pragma unroll
;         for (int mi = 0; mi < MT; ++mi)
; #pragma unroll
;             for (int nj = 0; nj < NT; ++nj)
; #pragma unroll
;                 for (int i = 0; i < 16; ++i) { float* q = x + ((mi * 32 + crow(i, h) + (mi == 2 ? d2 : 0)) * DM + unit * UW + nj * 32 + r); *q = *q + acc[mi][nj][i]; if (i == 15) __builtin_amdgcn_sched_barrier(0); }
;     }
	v_add_f32_e32 v90, v32, v90
	global_store_dword v82, v90, s[8:9] offset:-4096
	v_add_f32_e32 v91, v16, v91
	global_store_dword v82, v91, s[8:9] offset:-3968
	v_add_f32_e32 v92, v33, v92
	global_store_dword v82, v92, s[8:9] offset:0
	v_add_f32_e32 v93, v17, v93
	global_store_dword v82, v93, s[8:9] offset:128
	v_add_f32_e32 v94, v34, v94
	global_store_dword v83, v94, s[8:9] offset:-4096
	v_add_f32_e32 v95, v18, v95
	global_store_dword v83, v95, s[8:9] offset:-3968
	v_add_f32_e32 v96, v35, v96
	global_store_dword v83, v96, s[8:9] offset:0
	v_add_f32_e32 v97, v19, v97
	global_store_dword v83, v97, s[8:9] offset:128
	v_add_f32_e32 v98, v36, v98
	global_store_dword v84, v98, s[8:9] offset:-4096
	v_add_f32_e32 v99, v20, v99
	global_store_dword v84, v99, s[8:9] offset:-3968
	v_add_f32_e32 v100, v37, v100
	global_store_dword v84, v100, s[8:9] offset:0
	v_add_f32_e32 v101, v21, v101
	global_store_dword v84, v101, s[8:9] offset:128
	v_add_f32_e32 v102, v38, v102
	global_store_dword v85, v102, s[8:9] offset:-4096
	v_add_f32_e32 v103, v22, v103
	global_store_dword v85, v103, s[8:9] offset:-3968
	v_add_f32_e32 v104, v39, v104
	global_store_dword v85, v104, s[8:9] offset:0
	v_add_f32_e32 v105, v23, v105
	global_store_dword v85, v105, s[8:9] offset:128
	v_add_f32_e32 v106, v40, v106
	global_store_dword v86, v106, s[8:9] offset:-4096
	v_add_f32_e32 v107, v24, v107
	global_store_dword v86, v107, s[8:9] offset:-3968
	v_add_f32_e32 v108, v41, v108
	global_store_dword v86, v108, s[8:9] offset:0
	v_add_f32_e32 v109, v25, v109
	global_store_dword v86, v109, s[8:9] offset:128
	v_add_f32_e32 v110, v42, v110
	global_store_dword v87, v110, s[8:9] offset:-4096
	v_add_f32_e32 v111, v26, v111
	global_store_dword v87, v111, s[8:9] offset:-3968
	v_add_f32_e32 v112, v43, v112
	global_store_dword v87, v112, s[8:9] offset:0
	v_add_f32_e32 v113, v27, v113
	global_store_dword v87, v113, s[8:9] offset:128
	v_add_f32_e32 v114, v44, v114
	global_store_dword v88, v114, s[8:9] offset:-4096
	v_add_f32_e32 v116, v28, v116
	global_store_dword v88, v116, s[8:9] offset:-3968
	v_add_f32_e32 v117, v45, v117
	global_store_dword v88, v117, s[8:9] offset:0
	v_add_f32_e32 v118, v29, v118
	global_store_dword v88, v118, s[8:9] offset:128
	v_add_f32_e32 v119, v46, v119
	global_store_dword v89, v119, s[8:9] offset:-4096
	v_add_f32_e32 v128, v30, v128
	global_store_dword v89, v128, s[8:9] offset:-3968
	v_add_f32_e32 v129, v47, v129
	global_store_dword v89, v129, s[8:9] offset:0
	v_add_f32_e32 v130, v31, v130
	global_store_dword v89, v130, s[8:9] offset:128
	s_waitcnt vmcnt(0)
	s_branch .LBB0_868

; #define LAS __attribute__((address_space(3)))
; __global__ void __launch_bounds__(NTHR) mega(Params p) {
;     cg::grid_group grid = cg::this_grid();
;     __shared__ __attribute__((aligned(16))) unsigned char lds[LDS_BYTES];
;     __shared__ uint4 xb_words;
;     if (threadIdx.x == 0) xb_words = make_uint4(0u, 0u, 0u, 0u);
;     __syncthreads();
;     (void)xcd_barrier_post((unsigned*)(p.ws + OFF_BAR), (volatile LAS unsigned*)&xb_words);
;     ...
;     const int G = gridDim.x, bid = blockIdx.x, tid = threadIdx.x;
;     const int gtid = bid * NTHR + tid, gthreads = G * NTHR;
;     const int tb = G == NTILE ? (bid & 7) * (NTILE / 8) + (bid >> 3) : bid;
;     unsigned char* ws = p.ws;
;     pack_layer(p, 0, gtid, gthreads);
;     for (int l = 0; l < DEPTH; ++l) {
;         pack_w(p.in[20] + (size_t)l * DM * 512, p.in[18] + l * DM, DM, 512, (bf16_t*)(ws + OFF_UHALO) + (size_t)(l * 2 + 0) * 512 * 1024, 0, gtid, gthreads);
;         pack_w(p.in[21] + (size_t)l * DM * 512, p.in[18] + l * DM, DM, 512, (bf16_t*)(ws + OFF_UHALO) + (size_t)(l * 2 + 1) * 512 * 1024, 0, gtid, gthreads);
;     }
;     conv_sample_caches(p, 0, gthreads);
;     for (int t = tb; t < NTILE; t += G) {
;         const int row0 = t * 64;
;         if (t < 4) norm_rows<0, 3>(p.in[0] + (size_t)row0 * DM, p.in[1] + (size_t)(32 * t) * DM, p.out + (size_t)row0 * DM, tile_d2(t), (bf16_t*)(ws + OFF_XB) + (size_t)row0 * DM, nullptr);
;     }
;     for (int t = tb; t < NTILE; t += G) {
;         const int row0 = t * 64;
;         if (t >= 4) norm_rows<0, 2>(p.in[0] + (size_t)row0 * DM, p.in[1], p.out + (size_t)row0 * DM, 0, (bf16_t*)(ws + OFF_XB) + (size_t)row0 * DM, nullptr);
;     }
;     for (int e = tb; e < 8; e += G) if (e >= 4) norm_rows<1, 2>(nullptr, nullptr, (float*)(p.in[2] + (size_t)(e - 4) * 64 * DM), 0, (bf16_t*)(ws + OFF_MEMB) + (size_t)(e - 4) * 64 * DM, nullptr);
;     { __syncthreads(); grid.sync(); }
;     for (int t = tb; t < NTILE; t += G) if (t < 4) phaseA<3>(p, 0, t, lds);
;     for (int t = tb; t < NTILE; t += G) if (t >= 4) phaseA<2>(p, 0, t, lds);
;     for (int e = tb; e < 36; e += G) if (e >= 4) mem_kv_unit(p, e - 4, lds);
;     ...
;     for (int l = 0; l < DEPTH; ++l) {
;         for (int t = tb; t < NTILE; t += G) if (t < 4) phaseB<3>(p, l, t, lds);
;         for (int t = tb; t < NTILE; t += G) if (t >= 4) phaseB<2>(p, l, t, lds);
;         if (l + 1 < DEPTH) {
	.amdhsa_kernel _Z4mega6Params
		.amdhsa_group_segment_fixed_size 132112
		.amdhsa_private_segment_fixed_size 0
		.amdhsa_kernarg_size 504
		.amdhsa_user_sgpr_count 2
		.amdhsa_user_sgpr_dispatch_ptr 0
		.amdhsa_user_sgpr_queue_ptr 0
		.amdhsa_user_sgpr_kernarg_segment_ptr 1
		.amdhsa_user_sgpr_dispatch_id 0
		.amdhsa_user_sgpr_kernarg_preload_length 0
		.amdhsa_user_sgpr_kernarg_preload_offset 0
		.amdhsa_user_sgpr_private_segment_size 0
		.amdhsa_uses_dynamic_stack 0
		.amdhsa_enable_private_segment 0
		.amdhsa_system_sgpr_workgroup_id_x 1
		.amdhsa_system_sgpr_workgroup_id_y 0
		.amdhsa_system_sgpr_workgroup_id_z 0
		.amdhsa_system_sgpr_workgroup_info 0
		.amdhsa_system_vgpr_workitem_id 2
		.amdhsa_next_free_vgpr 256
		.amdhsa_next_free_sgpr 102
		.amdhsa_accum_offset 256
		.amdhsa_reserve_vcc 1
		.amdhsa_float_round_mode_32 0
		.amdhsa_float_round_mode_16_64 0
		.amdhsa_float_denorm_mode_32 3
		.amdhsa_float_denorm_mode_16_64 3
		.amdhsa_dx10_clamp 1
		.amdhsa_ieee_mode 1
		.amdhsa_fp16_overflow 0
		.amdhsa_tg_split 0
		.amdhsa_exception_fp_ieee_invalid_op 0
		.amdhsa_exception_fp_denorm_src 0
		.amdhsa_exception_fp_ieee_div_zero 0
		.amdhsa_exception_fp_ieee_overflow 0
		.amdhsa_exception_fp_ieee_underflow 0
		.amdhsa_exception_fp_ieee_inexact 0
		.amdhsa_exception_int_div_zero 0
	.end_amdhsa_kernel

; #define LAS __attribute__((address_space(3)))
; __global__ void __launch_bounds__(NTHR) mega(Params p) {
;     cg::grid_group grid = cg::this_grid();
;     __shared__ __attribute__((aligned(16))) unsigned char lds[LDS_BYTES];
;     __shared__ uint4 xb_words;
;     if (threadIdx.x == 0) xb_words = make_uint4(0u, 0u, 0u, 0u);
;     __syncthreads();
;     (void)xcd_barrier_post((unsigned*)(p.ws + OFF_BAR), (volatile LAS unsigned*)&xb_words);
;     ...
;     const int G = gridDim.x, bid = blockIdx.x, tid = threadIdx.x;
;     const int gtid = bid * NTHR + tid, gthreads = G * NTHR;
;     const int tb = G == NTILE ? (bid & 7) * (NTILE / 8) + (bid >> 3) : bid;
;     unsigned char* ws = p.ws;
;     pack_layer(p, 0, gtid, gthreads);
;     for (int l = 0; l < DEPTH; ++l) {
;         pack_w(p.in[20] + (size_t)l * DM * 512, p.in[18] + l * DM, DM, 512, (bf16_t*)(ws + OFF_UHALO) + (size_t)(l * 2 + 0) * 512 * 1024, 0, gtid, gthreads);
;         pack_w(p.in[21] + (size_t)l * DM * 512, p.in[18] + l * DM, DM, 512, (bf16_t*)(ws + OFF_UHALO) + (size_t)(l * 2 + 1) * 512 * 1024, 0, gtid, gthreads);
;     }
;     conv_sample_caches(p, 0, gthreads);
;     for (int t = tb; t < NTILE; t += G) {
;         const int row0 = t * 64;
;         if (t < 4) norm_rows<0, 3>(p.in[0] + (size_t)row0 * DM, p.in[1] + (size_t)(32 * t) * DM, p.out + (size_t)row0 * DM, tile_d2(t), (bf16_t*)(ws + OFF_XB) + (size_t)row0 * DM, nullptr);
;     }
;     for (int t = tb; t < NTILE; t += G) {
;         const int row0 = t * 64;
;         if (t >= 4) norm_rows<0, 2>(p.in[0] + (size_t)row0 * DM, p.in[1], p.out + (size_t)row0 * DM, 0, (bf16_t*)(ws + OFF_XB) + (size_t)row0 * DM, nullptr);
;     }
;     for (int e = tb; e < 8; e += G) if (e >= 4) norm_rows<1, 2>(nullptr, nullptr, (float*)(p.in[2] + (size_t)(e - 4) * 64 * DM), 0, (bf16_t*)(ws + OFF_MEMB) + (size_t)(e - 4) * 64 * DM, nullptr);
;     { __syncthreads(); grid.sync(); }
;     for (int t = tb; t < NTILE; t += G) if (t < 4) phaseA<3>(p, 0, t, lds);
;     for (int t = tb; t < NTILE; t += G) if (t >= 4) phaseA<2>(p, 0, t, lds);
;     for (int e = tb; e < 36; e += G) if (e >= 4) mem_kv_unit(p, e - 4, lds);
;     ...
;     for (int l = 0; l < DEPTH; ++l) {
;         for (int t = tb; t < NTILE; t += G) if (t < 4) phaseB<3>(p, l, t, lds);
;         for (int t = tb; t < NTILE; t += G) if (t >= 4) phaseB<2>(p, l, t, lds);
;         if (l + 1 < DEPTH) {
amdhsa.kernels:
  - .agpr_count:     0
    .args:
      - .offset:         0
        .size:           248
        .value_kind:     by_value
      - .offset:         248
        .size:           4
        .value_kind:     hidden_block_count_x
      - .offset:         252
        .size:           4
        .value_kind:     hidden_block_count_y
      - .offset:         256
        .size:           4
        .value_kind:     hidden_block_count_z
      - .offset:         260
        .size:           2
        .value_kind:     hidden_group_size_x
      - .offset:         262
        .size:           2
        .value_kind:     hidden_group_size_y
      - .offset:         264
        .size:           2
        .value_kind:     hidden_group_size_z
      - .offset:         266
        .size:           2
        .value_kind:     hidden_remainder_x
      - .offset:         268
        .size:           2
        .value_kind:     hidden_remainder_y
      - .offset:         270
        .size:           2
        .value_kind:     hidden_remainder_z
      - .offset:         288
        .size:           8
        .value_kind:     hidden_global_offset_x
      - .offset:         296
        .size:           8
        .value_kind:     hidden_global_offset_y
      - .offset:         304
        .size:           8
        .value_kind:     hidden_global_offset_z
      - .offset:         312
        .size:           2
        .value_kind:     hidden_grid_dims
      - .offset:         336
        .size:           8
        .value_kind:     hidden_multigrid_sync_arg
    .group_segment_fixed_size: 132112
    .kernarg_segment_align: 8
    .kernarg_segment_size: 504
    .language:       OpenCL C
    .language_version:
      - 2
      - 0
    .max_flat_workgroup_size: 512
    .name:           _Z4mega6Params
    .private_segment_fixed_size: 0
    .sgpr_count:     108
    .sgpr_spill_count: 274
    .symbol:         _Z4mega6Params.kd
    .uniform_work_group_size: 1
    .uses_dynamic_stack: false
    .vgpr_count:     256
    .vgpr_spill_count: 0
    .wavefront_size: 64
